# residual epilogues: row sum-of-squares reduced with v_permlane16/32_swap instead of two ds_bpermute round trips; unsigned fixed-point conversion (8 instances)
# speedup vs baseline: 1.0227x; 1.0075x over previous
; __device__ __forceinline__ void fx_add(float* p, size_t idx, float s) { atomicAdd((unsigned long long*)p + idx, (unsigned long long)(long long)(s * 4294967296.0f)); }
; __device__ __forceinline__ unsigned cvtpk(float lo, float hi) { f32x2v_ v = {lo, hi}; bf16x2v_ b = __builtin_convertvector(v, bf16x2v_); return __builtin_bit_cast(unsigned, b); }
;     __device__ __forceinline__ void operator()(const f32x4 (&acc)[2][2][4][2], const Unit& u, int wr, int wc, int fr, int fq) const {
;     ...
;                     const f32x4 v0 = a0 + acc[ai][bj][m][0] * alpha, v1 = a1 + acc[ai][bj][m][1] * alpha;
;                     u32x4 w; w.x = cvtpk(v0[0], v0[1]); w.y = cvtpk(v0[2], v0[3]); w.z = cvtpk(v1[0], v1[1]); w.w = cvtpk(v1[2], v1[3]);
;                     *(u32x4*)(xb + off + bj * HALF) = w;
;                     s += (v0[0] * v0[0] + v0[1] * v0[1]) + (v0[2] * v0[2] + v0[3] * v0[3]) + (v1[0] * v1[0] + v1[1] * v1[1]) + (v1[2] * v1[2] + v1[3] * v1[3]); }
;                 s += __shfl_xor(s, 16); s += __shfl_xor(s, 32);
;                 if (fq == 0) fx_add(ssout, row, s); }
.LBB0_278:
	v_mul_f32_e32 v134, v161, v161
	v_mul_f32_e32 v131, v131, v131
	v_fmac_f32_e32 v134, v160, v160
	v_fmac_f32_e32 v131, v130, v130
	s_waitcnt vmcnt(0)
	v_pk_fma_f32 v[118:119], v[118:119], 0.5, v[122:123] op_sel_hi:[1,0,1]
	v_pk_fma_f32 v[116:117], v[116:117], 0.5, v[120:121] op_sel_hi:[1,0,1]
	v_add_f32_e32 v130, v134, v131
	v_mul_f32_e32 v131, v133, v133
	v_pk_fma_f32 v[122:123], v[112:113], 0.5, v[124:125] op_sel_hi:[1,0,1]
	v_mul_f32_e32 v112, v117, v117
	v_mul_f32_e32 v113, v119, v119
	v_fmac_f32_e32 v131, v132, v132
	v_mul_f32_e32 v129, v129, v129
	v_fmac_f32_e32 v112, v116, v116
	v_fmac_f32_e32 v113, v118, v118
	v_add_f32_e32 v130, v131, v130
	v_fmac_f32_e32 v129, v128, v128
	v_add_f32_e32 v112, v112, v113
	v_mul_f32_e32 v113, v123, v123
	v_add_f32_e32 v129, v129, v130
	v_and_b32_e32 v130, 64, v170
	v_pk_fma_f32 v[120:121], v[114:115], 0.5, v[126:127] op_sel_hi:[1,0,1]
	v_fmac_f32_e32 v113, v122, v122
	v_xor_b32_e32 v128, 16, v170
	v_add_u32_e32 v130, 64, v130
	v_add_f32_e32 v112, v113, v112
	v_mul_f32_e32 v113, v121, v121
	v_cmp_lt_i32_e32 vcc, v128, v130
	v_fmac_f32_e32 v113, v120, v120
	v_add_f32_e32 v112, v113, v112
	v_cndmask_b32_e32 v128, v170, v128, vcc
	v_lshlrev_b32_e32 v128, 2, v128
	v_add_f32_e32 v112, v129, v112
	v_mov_b32_e32 v113, v112
	s_nop 1
	v_permlane16_swap_b32_e32 v113, v112
	v_xor_b32_e32 v131, 32, v170
	v_cmp_lt_i32_e32 vcc, v131, v130
	v_cvt_pk_bf16_f32 v115, v118, v119
	s_waitcnt lgkmcnt(0)
	v_add_f32_e32 v112, v112, v113
	v_cndmask_b32_e32 v114, v170, v131, vcc
	v_lshlrev_b32_e32 v129, 2, v114
	v_mov_b32_e32 v113, v112
	s_nop 1
	v_permlane32_swap_b32_e32 v113, v112
	v_cvt_pk_bf16_f32 v114, v116, v117
	v_cvt_pk_bf16_f32 v116, v122, v123
	v_cvt_pk_bf16_f32 v117, v120, v121
	global_store_dwordx4 v[156:157], v[114:117], off offset:256
	s_and_saveexec_b64 s[50:51], s[6:7]
	s_cbranch_execz .LBB0_280
	s_waitcnt lgkmcnt(0)
	v_add_f32_e32 v112, v112, v113
	v_mul_f32_e32 v112, 0x4f800000, v112
	v_trunc_f32_e32 v112, v112
	v_mul_f32_e64 v113, |v112|, s67
	v_floor_f32_e32 v113, v113
	v_fma_f32 v114, v113, s86, |v112|
	v_cvt_u32_f32_e32 v112, v114
	v_cvt_u32_f32_e32 v113, v113
	v_lshl_add_u64 v[114:115], v[154:155], 3, s[24:25]
	global_atomic_add_x2 v[114:115], v[112:113], off

; __device__ __forceinline__ void fx_add(float* p, size_t idx, float s) { atomicAdd((unsigned long long*)p + idx, (unsigned long long)(long long)(s * 4294967296.0f)); }
; __device__ __forceinline__ unsigned cvtpk(float lo, float hi) { f32x2v_ v = {lo, hi}; bf16x2v_ b = __builtin_convertvector(v, bf16x2v_); return __builtin_bit_cast(unsigned, b); }
;     __device__ __forceinline__ void operator()(const f32x4 (&acc)[2][2][4][2], const Unit& u, int wr, int wc, int fr, int fq) const {
;     ...
;                     const f32x4 v0 = a0 + acc[ai][bj][m][0] * alpha, v1 = a1 + acc[ai][bj][m][1] * alpha;
;                     u32x4 w; w.x = cvtpk(v0[0], v0[1]); w.y = cvtpk(v0[2], v0[3]); w.z = cvtpk(v1[0], v1[1]); w.w = cvtpk(v1[2], v1[3]);
;                     *(u32x4*)(xb + off + bj * HALF) = w;
;                     s += (v0[0] * v0[0] + v0[1] * v0[1]) + (v0[2] * v0[2] + v0[3] * v0[3]) + (v1[0] * v1[0] + v1[1] * v1[1]) + (v1[2] * v1[2] + v1[3] * v1[3]); }
;                 s += __shfl_xor(s, 16); s += __shfl_xor(s, 32);
;                 if (fq == 0) fx_add(ssout, row, s); }
.LBB0_286:
	s_waitcnt vmcnt(0)
	v_pk_fma_f32 v[102:103], v[102:103], 0.5, v[106:107] op_sel_hi:[1,0,1]
	v_pk_fma_f32 v[100:101], v[100:101], 0.5, v[104:105] op_sel_hi:[1,0,1]
	v_pk_fma_f32 v[106:107], v[96:97], 0.5, v[108:109] op_sel_hi:[1,0,1]
	v_mul_f32_e32 v96, v101, v101
	v_mul_f32_e32 v97, v103, v103
	v_mul_f32_e32 v118, v127, v127
	v_mul_f32_e32 v115, v115, v115
	v_fmac_f32_e32 v96, v100, v100
	v_fmac_f32_e32 v97, v102, v102
	v_fmac_f32_e32 v118, v126, v126
	v_fmac_f32_e32 v115, v114, v114
	v_add_f32_e32 v96, v96, v97
	v_mul_f32_e32 v97, v107, v107
	v_add_f32_e32 v114, v118, v115
	v_mul_f32_e32 v115, v117, v117
	v_pk_fma_f32 v[104:105], v[98:99], 0.5, v[110:111] op_sel_hi:[1,0,1]
	v_fmac_f32_e32 v97, v106, v106
	v_fmac_f32_e32 v115, v116, v116
	v_mul_f32_e32 v113, v113, v113
	v_add_f32_e32 v96, v97, v96
	v_mul_f32_e32 v97, v105, v105
	v_add_f32_e32 v114, v115, v114
	v_fmac_f32_e32 v113, v112, v112
	v_fmac_f32_e32 v97, v104, v104
	v_add_f32_e32 v112, v113, v114
	v_add_f32_e32 v96, v97, v96
	v_add_f32_e32 v96, v112, v96
	v_mov_b32_e32 v97, v96
	s_nop 1
	v_permlane16_swap_b32_e32 v97, v96
	v_cvt_pk_bf16_f32 v98, v100, v101
	v_cvt_pk_bf16_f32 v99, v102, v103
	v_cvt_pk_bf16_f32 v100, v106, v107
	v_cvt_pk_bf16_f32 v101, v104, v105
	s_waitcnt lgkmcnt(0)
	v_add_f32_e32 v96, v96, v97
	v_mov_b32_e32 v97, v96
	s_nop 1
	v_permlane32_swap_b32_e32 v97, v96
	global_store_dwordx4 v[122:123], v[98:101], off offset:256
	s_and_saveexec_b64 s[50:51], s[6:7]
	s_cbranch_execz .LBB0_288
	s_waitcnt lgkmcnt(0)
	v_add_f32_e32 v96, v96, v97
	v_mul_f32_e32 v96, 0x4f800000, v96
	v_trunc_f32_e32 v96, v96
	v_mul_f32_e64 v97, |v96|, s67
	v_floor_f32_e32 v97, v97
	v_fma_f32 v98, v97, s86, |v96|
	v_cvt_u32_f32_e32 v96, v98
	v_cvt_u32_f32_e32 v97, v97
	v_lshl_add_u64 v[98:99], v[120:121], 3, s[24:25]
	global_atomic_add_x2 v[98:99], v[96:97], off

; __device__ __forceinline__ void fx_add(float* p, size_t idx, float s) { atomicAdd((unsigned long long*)p + idx, (unsigned long long)(long long)(s * 4294967296.0f)); }
; __device__ __forceinline__ unsigned cvtpk(float lo, float hi) { f32x2v_ v = {lo, hi}; bf16x2v_ b = __builtin_convertvector(v, bf16x2v_); return __builtin_bit_cast(unsigned, b); }
;     __device__ __forceinline__ void operator()(const f32x4 (&acc)[2][2][4][2], const Unit& u, int wr, int wc, int fr, int fq) const {
;     ...
;                     const f32x4 v0 = a0 + acc[ai][bj][m][0] * alpha, v1 = a1 + acc[ai][bj][m][1] * alpha;
;                     u32x4 w; w.x = cvtpk(v0[0], v0[1]); w.y = cvtpk(v0[2], v0[3]); w.z = cvtpk(v1[0], v1[1]); w.w = cvtpk(v1[2], v1[3]);
;                     *(u32x4*)(xb + off + bj * HALF) = w;
;                     s += (v0[0] * v0[0] + v0[1] * v0[1]) + (v0[2] * v0[2] + v0[3] * v0[3]) + (v1[0] * v1[0] + v1[1] * v1[1]) + (v1[2] * v1[2] + v1[3] * v1[3]); }
;                 s += __shfl_xor(s, 16); s += __shfl_xor(s, 32);
;                 if (fq == 0) fx_add(ssout, row, s); }
.LBB0_294:
	s_waitcnt vmcnt(0)
	v_pk_fma_f32 v[86:87], v[86:87], 0.5, v[90:91] op_sel_hi:[1,0,1]
	v_pk_fma_f32 v[84:85], v[84:85], 0.5, v[88:89] op_sel_hi:[1,0,1]
	v_pk_fma_f32 v[90:91], v[80:81], 0.5, v[92:93] op_sel_hi:[1,0,1]
	v_mul_f32_e32 v80, v85, v85
	v_mul_f32_e32 v81, v87, v87
	v_mul_f32_e32 v102, v111, v111
	v_mul_f32_e32 v99, v99, v99
	v_fmac_f32_e32 v80, v84, v84
	v_fmac_f32_e32 v81, v86, v86
	v_fmac_f32_e32 v102, v110, v110
	v_fmac_f32_e32 v99, v98, v98
	v_add_f32_e32 v80, v80, v81
	v_mul_f32_e32 v81, v91, v91
	v_add_f32_e32 v98, v102, v99
	v_mul_f32_e32 v99, v101, v101
	v_pk_fma_f32 v[88:89], v[82:83], 0.5, v[94:95] op_sel_hi:[1,0,1]
	v_fmac_f32_e32 v81, v90, v90
	v_fmac_f32_e32 v99, v100, v100
	v_mul_f32_e32 v97, v97, v97
	v_add_f32_e32 v80, v81, v80
	v_mul_f32_e32 v81, v89, v89
	v_add_f32_e32 v98, v99, v98
	v_fmac_f32_e32 v97, v96, v96
	v_fmac_f32_e32 v81, v88, v88
	v_add_f32_e32 v96, v97, v98
	v_add_f32_e32 v80, v81, v80
	v_add_f32_e32 v80, v96, v80
	v_mov_b32_e32 v81, v80
	s_nop 1
	v_permlane16_swap_b32_e32 v81, v80
	v_cvt_pk_bf16_f32 v82, v84, v85
	v_cvt_pk_bf16_f32 v83, v86, v87
	v_cvt_pk_bf16_f32 v84, v90, v91
	v_cvt_pk_bf16_f32 v85, v88, v89
	s_waitcnt lgkmcnt(0)
	v_add_f32_e32 v80, v80, v81
	v_mov_b32_e32 v81, v80
	s_nop 1
	v_permlane32_swap_b32_e32 v81, v80
	global_store_dwordx4 v[106:107], v[82:85], off offset:256
	s_and_saveexec_b64 s[50:51], s[6:7]
	s_cbranch_execz .LBB0_296
	s_waitcnt lgkmcnt(0)
	v_add_f32_e32 v80, v80, v81
	v_mul_f32_e32 v80, 0x4f800000, v80
	v_trunc_f32_e32 v80, v80
	v_mul_f32_e64 v81, |v80|, s67
	v_floor_f32_e32 v81, v81
	v_fma_f32 v82, v81, s86, |v80|
	v_cvt_u32_f32_e32 v80, v82
	v_cvt_u32_f32_e32 v81, v81
	v_lshl_add_u64 v[82:83], v[104:105], 3, s[24:25]
	global_atomic_add_x2 v[82:83], v[80:81], off

; __device__ __forceinline__ void fx_add(float* p, size_t idx, float s) { atomicAdd((unsigned long long*)p + idx, (unsigned long long)(long long)(s * 4294967296.0f)); }
; __device__ __forceinline__ unsigned cvtpk(float lo, float hi) { f32x2v_ v = {lo, hi}; bf16x2v_ b = __builtin_convertvector(v, bf16x2v_); return __builtin_bit_cast(unsigned, b); }
;     __device__ __forceinline__ void operator()(const f32x4 (&acc)[2][2][4][2], const Unit& u, int wr, int wc, int fr, int fq) const {
;     ...
;                     const f32x4 v0 = a0 + acc[ai][bj][m][0] * alpha, v1 = a1 + acc[ai][bj][m][1] * alpha;
;                     u32x4 w; w.x = cvtpk(v0[0], v0[1]); w.y = cvtpk(v0[2], v0[3]); w.z = cvtpk(v1[0], v1[1]); w.w = cvtpk(v1[2], v1[3]);
;                     *(u32x4*)(xb + off + bj * HALF) = w;
;                     s += (v0[0] * v0[0] + v0[1] * v0[1]) + (v0[2] * v0[2] + v0[3] * v0[3]) + (v1[0] * v1[0] + v1[1] * v1[1]) + (v1[2] * v1[2] + v1[3] * v1[3]); }
;                 s += __shfl_xor(s, 16); s += __shfl_xor(s, 32);
;                 if (fq == 0) fx_add(ssout, row, s); }
.LBB0_302:
	s_waitcnt vmcnt(0)
	v_pk_fma_f32 v[70:71], v[70:71], 0.5, v[74:75] op_sel_hi:[1,0,1]
	v_pk_fma_f32 v[68:69], v[68:69], 0.5, v[72:73] op_sel_hi:[1,0,1]
	v_pk_fma_f32 v[74:75], v[64:65], 0.5, v[76:77] op_sel_hi:[1,0,1]
	v_mul_f32_e32 v64, v69, v69
	v_mul_f32_e32 v65, v71, v71
	v_mul_f32_e32 v86, v95, v95
	v_mul_f32_e32 v83, v83, v83
	v_fmac_f32_e32 v64, v68, v68
	v_fmac_f32_e32 v65, v70, v70
	v_fmac_f32_e32 v86, v94, v94
	v_fmac_f32_e32 v83, v82, v82
	v_add_f32_e32 v64, v64, v65
	v_mul_f32_e32 v65, v75, v75
	v_add_f32_e32 v82, v86, v83
	v_mul_f32_e32 v83, v85, v85
	v_pk_fma_f32 v[72:73], v[66:67], 0.5, v[78:79] op_sel_hi:[1,0,1]
	v_fmac_f32_e32 v65, v74, v74
	v_fmac_f32_e32 v83, v84, v84
	v_mul_f32_e32 v81, v81, v81
	v_add_f32_e32 v64, v65, v64
	v_mul_f32_e32 v65, v73, v73
	v_add_f32_e32 v82, v83, v82
	v_fmac_f32_e32 v81, v80, v80
	v_fmac_f32_e32 v65, v72, v72
	v_add_f32_e32 v80, v81, v82
	v_add_f32_e32 v64, v65, v64
	v_add_f32_e32 v64, v80, v64
	v_mov_b32_e32 v65, v64
	s_nop 1
	v_permlane16_swap_b32_e32 v65, v64
	v_cvt_pk_bf16_f32 v66, v68, v69
	v_cvt_pk_bf16_f32 v67, v70, v71
	v_cvt_pk_bf16_f32 v68, v74, v75
	v_cvt_pk_bf16_f32 v69, v72, v73
	s_waitcnt lgkmcnt(0)
	v_add_f32_e32 v64, v64, v65
	v_mov_b32_e32 v65, v64
	s_nop 1
	v_permlane32_swap_b32_e32 v65, v64
	global_store_dwordx4 v[90:91], v[66:69], off offset:256
	s_and_saveexec_b64 s[50:51], s[6:7]
	s_cbranch_execz .LBB0_304
	s_waitcnt lgkmcnt(0)
	v_add_f32_e32 v64, v64, v65
	v_mul_f32_e32 v64, 0x4f800000, v64
	v_trunc_f32_e32 v64, v64
	v_mul_f32_e64 v65, |v64|, s67
	v_floor_f32_e32 v65, v65
	v_fma_f32 v66, v65, s86, |v64|
	v_cvt_u32_f32_e32 v64, v66
	v_cvt_u32_f32_e32 v65, v65
	v_lshl_add_u64 v[66:67], v[88:89], 3, s[24:25]
	global_atomic_add_x2 v[66:67], v[64:65], off

; __device__ __forceinline__ void fx_add(float* p, size_t idx, float s) { atomicAdd((unsigned long long*)p + idx, (unsigned long long)(long long)(s * 4294967296.0f)); }
; __device__ __forceinline__ unsigned cvtpk(float lo, float hi) { f32x2v_ v = {lo, hi}; bf16x2v_ b = __builtin_convertvector(v, bf16x2v_); return __builtin_bit_cast(unsigned, b); }
;     __device__ __forceinline__ void operator()(const f32x4 (&acc)[2][2][4][2], const Unit& u, int wr, int wc, int fr, int fq) const {
;     ...
;                     const f32x4 v0 = a0 + acc[ai][bj][m][0] * alpha, v1 = a1 + acc[ai][bj][m][1] * alpha;
;                     u32x4 w; w.x = cvtpk(v0[0], v0[1]); w.y = cvtpk(v0[2], v0[3]); w.z = cvtpk(v1[0], v1[1]); w.w = cvtpk(v1[2], v1[3]);
;                     *(u32x4*)(xb + off + bj * HALF) = w;
;                     s += (v0[0] * v0[0] + v0[1] * v0[1]) + (v0[2] * v0[2] + v0[3] * v0[3]) + (v1[0] * v1[0] + v1[1] * v1[1]) + (v1[2] * v1[2] + v1[3] * v1[3]); }
;                 s += __shfl_xor(s, 16); s += __shfl_xor(s, 32);
;                 if (fq == 0) fx_add(ssout, row, s); }
.LBB0_310:
	s_waitcnt vmcnt(0)
	v_pk_fma_f32 v[54:55], v[54:55], 0.5, v[58:59] op_sel_hi:[1,0,1]
	v_pk_fma_f32 v[52:53], v[52:53], 0.5, v[56:57] op_sel_hi:[1,0,1]
	v_pk_fma_f32 v[58:59], v[48:49], 0.5, v[60:61] op_sel_hi:[1,0,1]
	v_mul_f32_e32 v48, v53, v53
	v_mul_f32_e32 v49, v55, v55
	v_mul_f32_e32 v70, v79, v79
	v_mul_f32_e32 v67, v67, v67
	v_fmac_f32_e32 v48, v52, v52
	v_fmac_f32_e32 v49, v54, v54
	v_fmac_f32_e32 v70, v78, v78
	v_fmac_f32_e32 v67, v66, v66
	v_add_f32_e32 v48, v48, v49
	v_mul_f32_e32 v49, v59, v59
	v_add_f32_e32 v66, v70, v67
	v_mul_f32_e32 v67, v69, v69
	v_pk_fma_f32 v[56:57], v[50:51], 0.5, v[62:63] op_sel_hi:[1,0,1]
	v_fmac_f32_e32 v49, v58, v58
	v_fmac_f32_e32 v67, v68, v68
	v_mul_f32_e32 v65, v65, v65
	v_add_f32_e32 v48, v49, v48
	v_mul_f32_e32 v49, v57, v57
	v_add_f32_e32 v66, v67, v66
	v_fmac_f32_e32 v65, v64, v64
	v_fmac_f32_e32 v49, v56, v56
	v_add_f32_e32 v64, v65, v66
	v_add_f32_e32 v48, v49, v48
	v_add_f32_e32 v48, v64, v48
	v_mov_b32_e32 v49, v48
	s_nop 1
	v_permlane16_swap_b32_e32 v49, v48
	v_cvt_pk_bf16_f32 v50, v52, v53
	v_cvt_pk_bf16_f32 v51, v54, v55
	v_cvt_pk_bf16_f32 v52, v58, v59
	v_cvt_pk_bf16_f32 v53, v56, v57
	s_waitcnt lgkmcnt(0)
	v_add_f32_e32 v48, v48, v49
	v_mov_b32_e32 v49, v48
	s_nop 1
	v_permlane32_swap_b32_e32 v49, v48
	global_store_dwordx4 v[74:75], v[50:53], off offset:256
	s_and_saveexec_b64 s[50:51], s[6:7]
	s_cbranch_execz .LBB0_312
	s_waitcnt lgkmcnt(0)
	v_add_f32_e32 v48, v48, v49
	v_mul_f32_e32 v48, 0x4f800000, v48
	v_trunc_f32_e32 v48, v48
	v_mul_f32_e64 v49, |v48|, s67
	v_floor_f32_e32 v49, v49
	v_fma_f32 v50, v49, s86, |v48|
	v_cvt_u32_f32_e32 v48, v50
	v_cvt_u32_f32_e32 v49, v49
	v_lshl_add_u64 v[50:51], v[72:73], 3, s[24:25]
	global_atomic_add_x2 v[50:51], v[48:49], off

; __device__ __forceinline__ void fx_add(float* p, size_t idx, float s) { atomicAdd((unsigned long long*)p + idx, (unsigned long long)(long long)(s * 4294967296.0f)); }
; __device__ __forceinline__ unsigned cvtpk(float lo, float hi) { f32x2v_ v = {lo, hi}; bf16x2v_ b = __builtin_convertvector(v, bf16x2v_); return __builtin_bit_cast(unsigned, b); }
;     __device__ __forceinline__ void operator()(const f32x4 (&acc)[2][2][4][2], const Unit& u, int wr, int wc, int fr, int fq) const {
;     ...
;                     const f32x4 v0 = a0 + acc[ai][bj][m][0] * alpha, v1 = a1 + acc[ai][bj][m][1] * alpha;
;                     u32x4 w; w.x = cvtpk(v0[0], v0[1]); w.y = cvtpk(v0[2], v0[3]); w.z = cvtpk(v1[0], v1[1]); w.w = cvtpk(v1[2], v1[3]);
;                     *(u32x4*)(xb + off + bj * HALF) = w;
;                     s += (v0[0] * v0[0] + v0[1] * v0[1]) + (v0[2] * v0[2] + v0[3] * v0[3]) + (v1[0] * v1[0] + v1[1] * v1[1]) + (v1[2] * v1[2] + v1[3] * v1[3]); }
;                 s += __shfl_xor(s, 16); s += __shfl_xor(s, 32);
;                 if (fq == 0) fx_add(ssout, row, s); }
.LBB0_318:
	s_waitcnt vmcnt(0)
	v_pk_fma_f32 v[38:39], v[38:39], 0.5, v[42:43] op_sel_hi:[1,0,1]
	v_pk_fma_f32 v[36:37], v[36:37], 0.5, v[40:41] op_sel_hi:[1,0,1]
	v_pk_fma_f32 v[42:43], v[32:33], 0.5, v[44:45] op_sel_hi:[1,0,1]
	v_mul_f32_e32 v32, v37, v37
	v_mul_f32_e32 v33, v39, v39
	v_mul_f32_e32 v54, v63, v63
	v_mul_f32_e32 v51, v51, v51
	v_fmac_f32_e32 v32, v36, v36
	v_fmac_f32_e32 v33, v38, v38
	v_fmac_f32_e32 v54, v62, v62
	v_fmac_f32_e32 v51, v50, v50
	v_add_f32_e32 v32, v32, v33
	v_mul_f32_e32 v33, v43, v43
	v_add_f32_e32 v50, v54, v51
	v_mul_f32_e32 v51, v53, v53
	v_pk_fma_f32 v[40:41], v[34:35], 0.5, v[46:47] op_sel_hi:[1,0,1]
	v_fmac_f32_e32 v33, v42, v42
	v_fmac_f32_e32 v51, v52, v52
	v_mul_f32_e32 v49, v49, v49
	v_add_f32_e32 v32, v33, v32
	v_mul_f32_e32 v33, v41, v41
	v_add_f32_e32 v50, v51, v50
	v_fmac_f32_e32 v49, v48, v48
	v_fmac_f32_e32 v33, v40, v40
	v_add_f32_e32 v48, v49, v50
	v_add_f32_e32 v32, v33, v32
	v_add_f32_e32 v32, v48, v32
	v_mov_b32_e32 v33, v32
	s_nop 1
	v_permlane16_swap_b32_e32 v33, v32
	v_cvt_pk_bf16_f32 v34, v36, v37
	v_cvt_pk_bf16_f32 v35, v38, v39
	v_cvt_pk_bf16_f32 v36, v42, v43
	v_cvt_pk_bf16_f32 v37, v40, v41
	s_waitcnt lgkmcnt(0)
	v_add_f32_e32 v32, v32, v33
	v_mov_b32_e32 v33, v32
	s_nop 1
	v_permlane32_swap_b32_e32 v33, v32
	global_store_dwordx4 v[58:59], v[34:37], off offset:256
	s_and_saveexec_b64 s[50:51], s[6:7]
	s_cbranch_execz .LBB0_320
	s_waitcnt lgkmcnt(0)
	v_add_f32_e32 v32, v32, v33
	v_mul_f32_e32 v32, 0x4f800000, v32
	v_trunc_f32_e32 v32, v32
	v_mul_f32_e64 v33, |v32|, s67
	v_floor_f32_e32 v33, v33
	v_fma_f32 v34, v33, s86, |v32|
	v_cvt_u32_f32_e32 v32, v34
	v_cvt_u32_f32_e32 v33, v33
	v_lshl_add_u64 v[34:35], v[56:57], 3, s[24:25]
	global_atomic_add_x2 v[34:35], v[32:33], off

; __device__ __forceinline__ void fx_add(float* p, size_t idx, float s) { atomicAdd((unsigned long long*)p + idx, (unsigned long long)(long long)(s * 4294967296.0f)); }
; __device__ __forceinline__ unsigned cvtpk(float lo, float hi) { f32x2v_ v = {lo, hi}; bf16x2v_ b = __builtin_convertvector(v, bf16x2v_); return __builtin_bit_cast(unsigned, b); }
;     __device__ __forceinline__ void operator()(const f32x4 (&acc)[2][2][4][2], const Unit& u, int wr, int wc, int fr, int fq) const {
;     ...
;                     const f32x4 v0 = a0 + acc[ai][bj][m][0] * alpha, v1 = a1 + acc[ai][bj][m][1] * alpha;
;                     u32x4 w; w.x = cvtpk(v0[0], v0[1]); w.y = cvtpk(v0[2], v0[3]); w.z = cvtpk(v1[0], v1[1]); w.w = cvtpk(v1[2], v1[3]);
;                     *(u32x4*)(xb + off + bj * HALF) = w;
;                     s += (v0[0] * v0[0] + v0[1] * v0[1]) + (v0[2] * v0[2] + v0[3] * v0[3]) + (v1[0] * v1[0] + v1[1] * v1[1]) + (v1[2] * v1[2] + v1[3] * v1[3]); }
;                 s += __shfl_xor(s, 16); s += __shfl_xor(s, 32);
;                 if (fq == 0) fx_add(ssout, row, s); }
.LBB0_326:
	s_waitcnt vmcnt(0)
	v_pk_fma_f32 v[22:23], v[22:23], 0.5, v[26:27] op_sel_hi:[1,0,1]
	v_pk_fma_f32 v[20:21], v[20:21], 0.5, v[24:25] op_sel_hi:[1,0,1]
	v_pk_fma_f32 v[26:27], v[16:17], 0.5, v[28:29] op_sel_hi:[1,0,1]
	v_mul_f32_e32 v16, v21, v21
	v_mul_f32_e32 v17, v23, v23
	v_mul_f32_e32 v38, v47, v47
	v_mul_f32_e32 v35, v35, v35
	v_fmac_f32_e32 v16, v20, v20
	v_fmac_f32_e32 v17, v22, v22
	v_fmac_f32_e32 v38, v46, v46
	v_fmac_f32_e32 v35, v34, v34
	v_add_f32_e32 v16, v16, v17
	v_mul_f32_e32 v17, v27, v27
	v_add_f32_e32 v34, v38, v35
	v_mul_f32_e32 v35, v37, v37
	v_pk_fma_f32 v[24:25], v[18:19], 0.5, v[30:31] op_sel_hi:[1,0,1]
	v_fmac_f32_e32 v17, v26, v26
	v_fmac_f32_e32 v35, v36, v36
	v_mul_f32_e32 v33, v33, v33
	v_add_f32_e32 v16, v17, v16
	v_mul_f32_e32 v17, v25, v25
	v_add_f32_e32 v34, v35, v34
	v_fmac_f32_e32 v33, v32, v32
	v_fmac_f32_e32 v17, v24, v24
	v_add_f32_e32 v32, v33, v34
	v_add_f32_e32 v16, v17, v16
	v_add_f32_e32 v16, v32, v16
	v_mov_b32_e32 v17, v16
	s_nop 1
	v_permlane16_swap_b32_e32 v17, v16
	v_cvt_pk_bf16_f32 v18, v20, v21
	v_cvt_pk_bf16_f32 v19, v22, v23
	v_cvt_pk_bf16_f32 v20, v26, v27
	v_cvt_pk_bf16_f32 v21, v24, v25
	s_waitcnt lgkmcnt(0)
	v_add_f32_e32 v16, v16, v17
	v_mov_b32_e32 v17, v16
	s_nop 1
	v_permlane32_swap_b32_e32 v17, v16
	global_store_dwordx4 v[42:43], v[18:21], off offset:256
	s_and_saveexec_b64 s[50:51], s[6:7]
	s_cbranch_execz .LBB0_328
	s_waitcnt lgkmcnt(0)
	v_add_f32_e32 v16, v16, v17
	v_mul_f32_e32 v16, 0x4f800000, v16
	v_trunc_f32_e32 v16, v16
	v_mul_f32_e64 v17, |v16|, s67
	v_floor_f32_e32 v17, v17
	v_fma_f32 v18, v17, s86, |v16|
	v_cvt_u32_f32_e32 v16, v18
	v_cvt_u32_f32_e32 v17, v17
	v_lshl_add_u64 v[18:19], v[40:41], 3, s[24:25]
	global_atomic_add_x2 v[18:19], v[16:17], off

; __device__ __forceinline__ void fx_add(float* p, size_t idx, float s) { atomicAdd((unsigned long long*)p + idx, (unsigned long long)(long long)(s * 4294967296.0f)); }
; __device__ __forceinline__ unsigned cvtpk(float lo, float hi) { f32x2v_ v = {lo, hi}; bf16x2v_ b = __builtin_convertvector(v, bf16x2v_); return __builtin_bit_cast(unsigned, b); }
;     __device__ __forceinline__ void operator()(const f32x4 (&acc)[2][2][4][2], const Unit& u, int wr, int wc, int fr, int fq) const {
;     ...
;                     const f32x4 v0 = a0 + acc[ai][bj][m][0] * alpha, v1 = a1 + acc[ai][bj][m][1] * alpha;
;                     u32x4 w; w.x = cvtpk(v0[0], v0[1]); w.y = cvtpk(v0[2], v0[3]); w.z = cvtpk(v1[0], v1[1]); w.w = cvtpk(v1[2], v1[3]);
;                     *(u32x4*)(xb + off + bj * HALF) = w;
;                     s += (v0[0] * v0[0] + v0[1] * v0[1]) + (v0[2] * v0[2] + v0[3] * v0[3]) + (v1[0] * v1[0] + v1[1] * v1[1]) + (v1[2] * v1[2] + v1[3] * v1[3]); }
;                 s += __shfl_xor(s, 16); s += __shfl_xor(s, 32);
;                 if (fq == 0) fx_add(ssout, row, s); }
.LBB0_334:
	s_waitcnt vmcnt(0)
	v_pk_fma_f32 v[6:7], v[6:7], 0.5, v[10:11] op_sel_hi:[1,0,1]
	v_pk_fma_f32 v[4:5], v[4:5], 0.5, v[8:9] op_sel_hi:[1,0,1]
	v_pk_fma_f32 v[10:11], v[0:1], 0.5, v[12:13] op_sel_hi:[1,0,1]
	v_mul_f32_e32 v0, v5, v5
	v_mul_f32_e32 v1, v7, v7
	v_mul_f32_e32 v22, v31, v31
	v_mul_f32_e32 v19, v19, v19
	v_fmac_f32_e32 v0, v4, v4
	v_fmac_f32_e32 v1, v6, v6
	v_fmac_f32_e32 v22, v30, v30
	v_fmac_f32_e32 v19, v18, v18
	v_add_f32_e32 v0, v0, v1
	v_mul_f32_e32 v1, v11, v11
	v_add_f32_e32 v18, v22, v19
	v_mul_f32_e32 v19, v21, v21
	v_pk_fma_f32 v[8:9], v[2:3], 0.5, v[14:15] op_sel_hi:[1,0,1]
	v_fmac_f32_e32 v1, v10, v10
	v_fmac_f32_e32 v19, v20, v20
	v_mul_f32_e32 v17, v17, v17
	v_add_f32_e32 v0, v1, v0
	v_mul_f32_e32 v1, v9, v9
	v_add_f32_e32 v18, v19, v18
	v_fmac_f32_e32 v17, v16, v16
	v_fmac_f32_e32 v1, v8, v8
	v_add_f32_e32 v16, v17, v18
	v_add_f32_e32 v0, v1, v0
	v_add_f32_e32 v0, v16, v0
	v_mov_b32_e32 v1, v0
	s_nop 1
	v_permlane16_swap_b32_e32 v1, v0
	v_cvt_pk_bf16_f32 v2, v4, v5
	v_cvt_pk_bf16_f32 v3, v6, v7
	v_cvt_pk_bf16_f32 v4, v10, v11
	v_cvt_pk_bf16_f32 v5, v8, v9
	s_waitcnt lgkmcnt(0)
	v_add_f32_e32 v0, v0, v1
	v_mov_b32_e32 v1, v0
	s_nop 1
	v_permlane32_swap_b32_e32 v1, v0
	global_store_dwordx4 v[26:27], v[2:5], off offset:256
	s_and_saveexec_b64 s[10:11], s[6:7]
	s_cbranch_execz .LBB0_336
	s_waitcnt lgkmcnt(0)
	v_add_f32_e32 v0, v0, v1
	v_mul_f32_e32 v0, 0x4f800000, v0
	v_trunc_f32_e32 v0, v0
	v_mul_f32_e64 v1, |v0|, s67
	v_floor_f32_e32 v1, v1
	v_fma_f32 v2, v1, s86, |v0|
	v_cvt_u32_f32_e32 v0, v2
	v_cvt_u32_f32_e32 v1, v1
	v_lshl_add_u64 v[2:3], v[24:25], 3, s[24:25]
	global_atomic_add_x2 v[2:3], v[0:1], off

; __device__ __forceinline__ void fx_add(float* p, size_t idx, float s) { atomicAdd((unsigned long long*)p + idx, (unsigned long long)(long long)(s * 4294967296.0f)); }
; __device__ __forceinline__ unsigned cvtpk(float lo, float hi) { f32x2v_ v = {lo, hi}; bf16x2v_ b = __builtin_convertvector(v, bf16x2v_); return __builtin_bit_cast(unsigned, b); }
;     __device__ __forceinline__ void operator()(const f32x4 (&acc)[2][2][4][2], const Unit& u, int wr, int wc, int fr, int fq) const {
;     ...
;             for (int m = 0; m < 4; ++m) { const int row = row0 + ai * HALF + m * 16; const size_t off = (size_t)row * 1024 + col0; float s = 0.f;
; #pragma unroll
;                 for (int bj = 0; bj < 2; ++bj) { f32x4 a0, a1;
;                     if (xin32) { const float* p = xin32 + off + bj * HALF; a0 = *(const f32x4*)p; a1 = *(const f32x4*)(p + 4); }
;                     else { const u32x4 w = *(const u32x4*)(xb + off + bj * HALF);
;                         a0 = (f32x4){__uint_as_float(w.x << 16), __uint_as_float(w.x & 0xffff0000u), __uint_as_float(w.y << 16), __uint_as_float(w.y & 0xffff0000u)};
;                         a1 = (f32x4){__uint_as_float(w.z << 16), __uint_as_float(w.z & 0xffff0000u), __uint_as_float(w.w << 16), __uint_as_float(w.w & 0xffff0000u)}; }
;                     const f32x4 v0 = a0 + acc[ai][bj][m][0] * alpha, v1 = a1 + acc[ai][bj][m][1] * alpha;
;                     u32x4 w; w.x = cvtpk(v0[0], v0[1]); w.y = cvtpk(v0[2], v0[3]); w.z = cvtpk(v1[0], v1[1]); w.w = cvtpk(v1[2], v1[3]);
;                     *(u32x4*)(xb + off + bj * HALF) = w;
;                     s += (v0[0] * v0[0] + v0[1] * v0[1]) + (v0[2] * v0[2] + v0[3] * v0[3]) + (v1[0] * v1[0] + v1[1] * v1[1]) + (v1[2] * v1[2] + v1[3] * v1[3]); }
;                 s += __shfl_xor(s, 16); s += __shfl_xor(s, 32);
;                 if (fq == 0) fx_add(ssout, row, s); }
.LBB0_653:
	v_lshl_add_u32 v150, s58, 8, v129
	v_ashrrev_i32_e32 v151, 31, v150
	v_lshl_or_b32 v148, s56, 8, v154
	v_lshlrev_b64 v[160:161], 11, v[150:151]
	v_ashrrev_i32_e32 v149, 31, v148
	v_lshl_add_u64 v[160:161], s[22:23], 0, v[160:161]
	v_lshl_add_u64 v[170:171], v[148:149], 1, v[160:161]
	global_load_dwordx4 v[162:165], v[170:171], off
	global_load_dwordx4 v[166:169], v[170:171], off offset:256
	v_and_b32_e32 v160, 64, v158
	v_xor_b32_e32 v159, 16, v158
	v_add_u32_e32 v160, 64, v160
	v_xor_b32_e32 v161, 32, v158
	v_cmp_lt_i32_e32 vcc, v159, v160
	s_waitcnt vmcnt(0)
	v_lshlrev_b32_e32 v172, 16, v162
	v_cndmask_b32_e32 v159, v158, v159, vcc
	v_cmp_lt_i32_e32 vcc, v161, v160
	v_and_b32_e32 v173, 0xffff0000, v162
	v_lshlrev_b32_e32 v162, 16, v163
	v_and_b32_e32 v163, 0xffff0000, v163
	v_lshlrev_b32_e32 v176, 16, v166
	v_and_b32_e32 v177, 0xffff0000, v166
	v_lshlrev_b32_e32 v166, 16, v167
	v_and_b32_e32 v167, 0xffff0000, v167
	v_cndmask_b32_e32 v161, v158, v161, vcc
	v_lshlrev_b32_e32 v174, 16, v164
	v_and_b32_e32 v175, 0xffff0000, v164
	v_lshlrev_b32_e32 v164, 16, v165
	v_and_b32_e32 v165, 0xffff0000, v165
	v_lshlrev_b32_e32 v178, 16, v168
	v_and_b32_e32 v179, 0xffff0000, v168
	v_lshlrev_b32_e32 v168, 16, v169
	v_and_b32_e32 v169, 0xffff0000, v169
	v_pk_add_f32 v[126:127], v[126:127], v[162:163]
	v_pk_add_f32 v[124:125], v[124:125], v[172:173]
	v_pk_add_f32 v[118:119], v[118:119], v[166:167]
	v_pk_add_f32 v[116:117], v[116:117], v[176:177]
	v_lshlrev_b32_e32 v160, 2, v159
	v_lshlrev_b32_e32 v159, 2, v161
	v_pk_add_f32 v[122:123], v[122:123], v[164:165]
	v_pk_add_f32 v[120:121], v[120:121], v[174:175]
	v_pk_add_f32 v[162:163], v[114:115], v[168:169]
	v_pk_add_f32 v[164:165], v[112:113], v[178:179]
	v_mul_f32_e32 v114, v125, v125
	v_mul_f32_e32 v115, v127, v127
	v_mul_f32_e32 v161, v117, v117
	v_mul_f32_e32 v166, v119, v119
	v_cvt_pk_bf16_f32 v112, v124, v125
	v_mul_f32_e32 v125, v121, v121
	v_mul_f32_e32 v167, v165, v165
	v_fmac_f32_e32 v114, v124, v124
	v_fmac_f32_e32 v115, v126, v126
	v_fmac_f32_e32 v161, v116, v116
	v_fmac_f32_e32 v166, v118, v118
	v_cvt_pk_bf16_f32 v113, v126, v127
	v_mul_f32_e32 v127, v123, v123
	v_mul_f32_e32 v168, v163, v163
	v_fmac_f32_e32 v125, v120, v120
	v_fmac_f32_e32 v167, v164, v164
	v_add_f32_e32 v114, v114, v115
	v_add_f32_e32 v115, v161, v166
	v_fmac_f32_e32 v127, v122, v122
	v_fmac_f32_e32 v168, v162, v162
	v_add_f32_e32 v114, v125, v114
	v_add_f32_e32 v115, v167, v115
	v_add_f32_e32 v114, v127, v114
	v_add_f32_e32 v115, v168, v115
	v_add_f32_e32 v124, v114, v115
	v_mov_b32_e32 v125, v124
	s_nop 1
	v_permlane16_swap_b32_e32 v125, v124
	v_cvt_pk_bf16_f32 v114, v120, v121
	v_cvt_pk_bf16_f32 v115, v122, v123
	global_store_dwordx4 v[170:171], v[112:115], off
	s_waitcnt lgkmcnt(0)
	s_nop 0
	v_add_f32_e32 v112, v124, v125
	v_mov_b32_e32 v113, v112
	s_nop 1
	v_permlane32_swap_b32_e32 v113, v112
	v_cvt_pk_bf16_f32 v114, v116, v117
	v_cvt_pk_bf16_f32 v115, v118, v119
	v_cvt_pk_bf16_f32 v116, v164, v165
	v_cvt_pk_bf16_f32 v117, v162, v163
	global_store_dwordx4 v[170:171], v[114:117], off offset:256
	s_and_saveexec_b64 s[56:57], s[6:7]
	s_cbranch_execz .LBB0_655
	s_waitcnt lgkmcnt(0)
	v_add_f32_e32 v112, v112, v113
	v_mul_f32_e32 v112, 0x4f800000, v112
	v_trunc_f32_e32 v112, v112
	v_mul_f32_e64 v113, |v112|, s87
	v_floor_f32_e32 v113, v113
	v_fma_f32 v114, v113, s88, |v112|
	v_cvt_u32_f32_e32 v112, v114
	v_cvt_u32_f32_e32 v113, v113
	v_lshl_add_u64 v[114:115], v[150:151], 3, s[10:11]
	global_atomic_add_x2 v[114:115], v[112:113], off
.LBB0_655:
	s_or_b64 exec, exec, s[56:57]
	v_or_b32_e32 v112, 16, v150
	s_waitcnt lgkmcnt(0)
	v_ashrrev_i32_e32 v113, 31, v112
	v_lshlrev_b64 v[114:115], 11, v[112:113]
	v_lshl_add_u64 v[114:115], s[22:23], 0, v[114:115]
	v_lshl_add_u64 v[122:123], v[148:149], 1, v[114:115]
	global_load_dwordx4 v[114:117], v[122:123], off
	global_load_dwordx4 v[118:121], v[122:123], off offset:256
	s_waitcnt vmcnt(1)
	v_lshlrev_b32_e32 v124, 16, v114
	v_and_b32_e32 v125, 0xffff0000, v114
	v_lshlrev_b32_e32 v114, 16, v115
	v_and_b32_e32 v115, 0xffff0000, v115
	s_waitcnt vmcnt(0)
	v_lshlrev_b32_e32 v162, 16, v118
	v_and_b32_e32 v163, 0xffff0000, v118
	v_lshlrev_b32_e32 v118, 16, v119
	v_and_b32_e32 v119, 0xffff0000, v119
	v_lshlrev_b32_e32 v126, 16, v116
	v_and_b32_e32 v127, 0xffff0000, v116
	v_lshlrev_b32_e32 v116, 16, v117
	v_and_b32_e32 v117, 0xffff0000, v117
	v_lshlrev_b32_e32 v164, 16, v120
	v_and_b32_e32 v165, 0xffff0000, v120
	v_lshlrev_b32_e32 v120, 16, v121
	v_and_b32_e32 v121, 0xffff0000, v121
	v_pk_add_f32 v[110:111], v[110:111], v[114:115]
	v_pk_add_f32 v[108:109], v[108:109], v[124:125]
	v_pk_add_f32 v[102:103], v[102:103], v[118:119]
	v_pk_add_f32 v[100:101], v[100:101], v[162:163]
	v_pk_add_f32 v[106:107], v[106:107], v[116:117]
	v_pk_add_f32 v[104:105], v[104:105], v[126:127]
	v_pk_add_f32 v[114:115], v[98:99], v[120:121]
	v_pk_add_f32 v[116:117], v[96:97], v[164:165]
	v_mul_f32_e32 v98, v109, v109
	v_mul_f32_e32 v99, v111, v111
	v_mul_f32_e32 v118, v101, v101
	v_mul_f32_e32 v119, v103, v103
	v_cvt_pk_bf16_f32 v96, v108, v109
	v_mul_f32_e32 v109, v105, v105
	v_mul_f32_e32 v120, v117, v117
	v_fmac_f32_e32 v98, v108, v108
	v_fmac_f32_e32 v99, v110, v110
	v_fmac_f32_e32 v118, v100, v100
	v_fmac_f32_e32 v119, v102, v102
	v_cvt_pk_bf16_f32 v97, v110, v111
	v_mul_f32_e32 v111, v107, v107
	v_mul_f32_e32 v121, v115, v115
	v_fmac_f32_e32 v109, v104, v104
	v_fmac_f32_e32 v120, v116, v116
	v_add_f32_e32 v98, v98, v99
	v_add_f32_e32 v99, v118, v119
	v_fmac_f32_e32 v111, v106, v106
	v_fmac_f32_e32 v121, v114, v114
	v_add_f32_e32 v98, v109, v98
	v_add_f32_e32 v99, v120, v99
	v_add_f32_e32 v98, v111, v98
	v_add_f32_e32 v99, v121, v99
	v_add_f32_e32 v108, v98, v99
	v_mov_b32_e32 v109, v108
	s_nop 1
	v_permlane16_swap_b32_e32 v109, v108
	v_cvt_pk_bf16_f32 v98, v104, v105
	v_cvt_pk_bf16_f32 v99, v106, v107
	global_store_dwordx4 v[122:123], v[96:99], off
	s_waitcnt lgkmcnt(0)
	s_nop 0
	v_add_f32_e32 v96, v108, v109
	v_mov_b32_e32 v97, v96
	s_nop 1
	v_permlane32_swap_b32_e32 v97, v96
	v_cvt_pk_bf16_f32 v98, v100, v101
	v_cvt_pk_bf16_f32 v99, v102, v103
	v_cvt_pk_bf16_f32 v100, v116, v117
	v_cvt_pk_bf16_f32 v101, v114, v115
	global_store_dwordx4 v[122:123], v[98:101], off offset:256
	s_and_saveexec_b64 s[56:57], s[6:7]
	s_cbranch_execz .LBB0_657
	s_waitcnt lgkmcnt(0)
	v_add_f32_e32 v96, v96, v97
	v_mul_f32_e32 v96, 0x4f800000, v96
	v_trunc_f32_e32 v96, v96
	v_mul_f32_e64 v97, |v96|, s87
	v_floor_f32_e32 v97, v97
	v_fma_f32 v98, v97, s88, |v96|
	v_cvt_u32_f32_e32 v96, v98
	v_cvt_u32_f32_e32 v97, v97
	v_lshl_add_u64 v[98:99], v[112:113], 3, s[10:11]
	global_atomic_add_x2 v[98:99], v[96:97], off
; __device__ __forceinline__ void fx_add(float* p, size_t idx, float s) { atomicAdd((unsigned long long*)p + idx, (unsigned long long)(long long)(s * 4294967296.0f)); }
; __device__ __forceinline__ unsigned cvtpk(float lo, float hi) { f32x2v_ v = {lo, hi}; bf16x2v_ b = __builtin_convertvector(v, bf16x2v_); return __builtin_bit_cast(unsigned, b); }
;     __device__ __forceinline__ void operator()(const f32x4 (&acc)[2][2][4][2], const Unit& u, int wr, int wc, int fr, int fq) const {
;     ...
;             for (int m = 0; m < 4; ++m) { const int row = row0 + ai * HALF + m * 16; const size_t off = (size_t)row * 1024 + col0; float s = 0.f;
; #pragma unroll
;                 for (int bj = 0; bj < 2; ++bj) { f32x4 a0, a1;
;                     if (xin32) { const float* p = xin32 + off + bj * HALF; a0 = *(const f32x4*)p; a1 = *(const f32x4*)(p + 4); }
;                     else { const u32x4 w = *(const u32x4*)(xb + off + bj * HALF);
;                         a0 = (f32x4){__uint_as_float(w.x << 16), __uint_as_float(w.x & 0xffff0000u), __uint_as_float(w.y << 16), __uint_as_float(w.y & 0xffff0000u)};
;                         a1 = (f32x4){__uint_as_float(w.z << 16), __uint_as_float(w.z & 0xffff0000u), __uint_as_float(w.w << 16), __uint_as_float(w.w & 0xffff0000u)}; }
;                     const f32x4 v0 = a0 + acc[ai][bj][m][0] * alpha, v1 = a1 + acc[ai][bj][m][1] * alpha;
;                     u32x4 w; w.x = cvtpk(v0[0], v0[1]); w.y = cvtpk(v0[2], v0[3]); w.z = cvtpk(v1[0], v1[1]); w.w = cvtpk(v1[2], v1[3]);
;                     *(u32x4*)(xb + off + bj * HALF) = w;
;                     s += (v0[0] * v0[0] + v0[1] * v0[1]) + (v0[2] * v0[2] + v0[3] * v0[3]) + (v1[0] * v1[0] + v1[1] * v1[1]) + (v1[2] * v1[2] + v1[3] * v1[3]); }
;                 s += __shfl_xor(s, 16); s += __shfl_xor(s, 32);
;                 if (fq == 0) fx_add(ssout, row, s); }
.LBB0_657:
	s_or_b64 exec, exec, s[56:57]
	v_or_b32_e32 v96, 32, v150
	s_waitcnt lgkmcnt(0)
	v_ashrrev_i32_e32 v97, 31, v96
	v_lshlrev_b64 v[98:99], 11, v[96:97]
	v_lshl_add_u64 v[98:99], s[22:23], 0, v[98:99]
	v_lshl_add_u64 v[106:107], v[148:149], 1, v[98:99]
	global_load_dwordx4 v[98:101], v[106:107], off
	global_load_dwordx4 v[102:105], v[106:107], off offset:256
	s_waitcnt vmcnt(1)
	v_lshlrev_b32_e32 v108, 16, v98
	v_and_b32_e32 v109, 0xffff0000, v98
	v_lshlrev_b32_e32 v98, 16, v99
	v_and_b32_e32 v99, 0xffff0000, v99
	s_waitcnt vmcnt(0)
	v_lshlrev_b32_e32 v112, 16, v102
	v_and_b32_e32 v113, 0xffff0000, v102
	v_lshlrev_b32_e32 v102, 16, v103
	v_and_b32_e32 v103, 0xffff0000, v103
	v_lshlrev_b32_e32 v110, 16, v100
	v_and_b32_e32 v111, 0xffff0000, v100
	v_lshlrev_b32_e32 v100, 16, v101
	v_and_b32_e32 v101, 0xffff0000, v101
	v_lshlrev_b32_e32 v114, 16, v104
	v_and_b32_e32 v115, 0xffff0000, v104
	v_lshlrev_b32_e32 v104, 16, v105
	v_and_b32_e32 v105, 0xffff0000, v105
	v_pk_add_f32 v[94:95], v[94:95], v[98:99]
	v_pk_add_f32 v[92:93], v[92:93], v[108:109]
	v_pk_add_f32 v[86:87], v[86:87], v[102:103]
	v_pk_add_f32 v[84:85], v[84:85], v[112:113]
	v_pk_add_f32 v[90:91], v[90:91], v[100:101]
	v_pk_add_f32 v[88:89], v[88:89], v[110:111]
	v_pk_add_f32 v[98:99], v[82:83], v[104:105]
	v_pk_add_f32 v[100:101], v[80:81], v[114:115]
	v_mul_f32_e32 v82, v93, v93
	v_mul_f32_e32 v83, v95, v95
	v_mul_f32_e32 v102, v85, v85
	v_mul_f32_e32 v103, v87, v87
	v_cvt_pk_bf16_f32 v80, v92, v93
	v_mul_f32_e32 v93, v89, v89
	v_mul_f32_e32 v104, v101, v101
	v_fmac_f32_e32 v82, v92, v92
	v_fmac_f32_e32 v83, v94, v94
	v_fmac_f32_e32 v102, v84, v84
	v_fmac_f32_e32 v103, v86, v86
	v_cvt_pk_bf16_f32 v81, v94, v95
	v_mul_f32_e32 v95, v91, v91
	v_mul_f32_e32 v105, v99, v99
	v_fmac_f32_e32 v93, v88, v88
	v_fmac_f32_e32 v104, v100, v100
	v_add_f32_e32 v82, v82, v83
	v_add_f32_e32 v83, v102, v103
	v_fmac_f32_e32 v95, v90, v90
	v_fmac_f32_e32 v105, v98, v98
	v_add_f32_e32 v82, v93, v82
	v_add_f32_e32 v83, v104, v83
	v_add_f32_e32 v82, v95, v82
	v_add_f32_e32 v83, v105, v83
	v_add_f32_e32 v92, v82, v83
	v_mov_b32_e32 v93, v92
	s_nop 1
	v_permlane16_swap_b32_e32 v93, v92
	v_cvt_pk_bf16_f32 v82, v88, v89
	v_cvt_pk_bf16_f32 v83, v90, v91
	global_store_dwordx4 v[106:107], v[80:83], off
	s_waitcnt lgkmcnt(0)
	s_nop 0
	v_add_f32_e32 v80, v92, v93
	v_mov_b32_e32 v81, v80
	s_nop 1
	v_permlane32_swap_b32_e32 v81, v80
	v_cvt_pk_bf16_f32 v82, v84, v85
	v_cvt_pk_bf16_f32 v83, v86, v87
	v_cvt_pk_bf16_f32 v84, v100, v101
	v_cvt_pk_bf16_f32 v85, v98, v99
	global_store_dwordx4 v[106:107], v[82:85], off offset:256
	s_and_saveexec_b64 s[56:57], s[6:7]
	s_cbranch_execz .LBB0_659
	s_waitcnt lgkmcnt(0)
	v_add_f32_e32 v80, v80, v81
	v_mul_f32_e32 v80, 0x4f800000, v80
	v_trunc_f32_e32 v80, v80
	v_mul_f32_e64 v81, |v80|, s87
	v_floor_f32_e32 v81, v81
	v_fma_f32 v82, v81, s88, |v80|
	v_cvt_u32_f32_e32 v80, v82
	v_cvt_u32_f32_e32 v81, v81
	v_lshl_add_u64 v[82:83], v[96:97], 3, s[10:11]
	global_atomic_add_x2 v[82:83], v[80:81], off
.LBB0_659:
	s_or_b64 exec, exec, s[56:57]
	v_or_b32_e32 v80, 48, v150
	s_waitcnt lgkmcnt(0)
	v_ashrrev_i32_e32 v81, 31, v80
	v_lshlrev_b64 v[82:83], 11, v[80:81]
	v_lshl_add_u64 v[82:83], s[22:23], 0, v[82:83]
	v_lshl_add_u64 v[90:91], v[148:149], 1, v[82:83]
	global_load_dwordx4 v[82:85], v[90:91], off
	global_load_dwordx4 v[86:89], v[90:91], off offset:256
	s_waitcnt vmcnt(1)
	v_lshlrev_b32_e32 v92, 16, v82
	v_and_b32_e32 v93, 0xffff0000, v82
	v_lshlrev_b32_e32 v82, 16, v83
	v_and_b32_e32 v83, 0xffff0000, v83
	s_waitcnt vmcnt(0)
	v_lshlrev_b32_e32 v96, 16, v86
	v_and_b32_e32 v97, 0xffff0000, v86
	v_lshlrev_b32_e32 v86, 16, v87
	v_and_b32_e32 v87, 0xffff0000, v87
	v_lshlrev_b32_e32 v94, 16, v84
	v_and_b32_e32 v95, 0xffff0000, v84
	v_lshlrev_b32_e32 v84, 16, v85
	v_and_b32_e32 v85, 0xffff0000, v85
	v_lshlrev_b32_e32 v98, 16, v88
	v_and_b32_e32 v99, 0xffff0000, v88
	v_lshlrev_b32_e32 v88, 16, v89
	v_and_b32_e32 v89, 0xffff0000, v89
	v_pk_add_f32 v[78:79], v[78:79], v[82:83]
	v_pk_add_f32 v[76:77], v[76:77], v[92:93]
	v_pk_add_f32 v[70:71], v[70:71], v[86:87]
	v_pk_add_f32 v[68:69], v[68:69], v[96:97]
	v_pk_add_f32 v[74:75], v[74:75], v[84:85]
	v_pk_add_f32 v[72:73], v[72:73], v[94:95]
	v_pk_add_f32 v[82:83], v[66:67], v[88:89]
	v_pk_add_f32 v[84:85], v[64:65], v[98:99]
	v_mul_f32_e32 v66, v77, v77
	v_mul_f32_e32 v67, v79, v79
	v_mul_f32_e32 v86, v69, v69
	v_mul_f32_e32 v87, v71, v71
	v_cvt_pk_bf16_f32 v64, v76, v77
	v_mul_f32_e32 v77, v73, v73
	v_mul_f32_e32 v88, v85, v85
	v_fmac_f32_e32 v66, v76, v76
	v_fmac_f32_e32 v67, v78, v78
	v_fmac_f32_e32 v86, v68, v68
	v_fmac_f32_e32 v87, v70, v70
	v_cvt_pk_bf16_f32 v65, v78, v79
	v_mul_f32_e32 v79, v75, v75
	v_mul_f32_e32 v89, v83, v83
	v_fmac_f32_e32 v77, v72, v72
	v_fmac_f32_e32 v88, v84, v84
	v_add_f32_e32 v66, v66, v67
	v_add_f32_e32 v67, v86, v87
	v_fmac_f32_e32 v79, v74, v74
	v_fmac_f32_e32 v89, v82, v82
	v_add_f32_e32 v66, v77, v66
	v_add_f32_e32 v67, v88, v67
	v_add_f32_e32 v66, v79, v66
	v_add_f32_e32 v67, v89, v67
	v_add_f32_e32 v76, v66, v67
	v_mov_b32_e32 v77, v76
	s_nop 1
	v_permlane16_swap_b32_e32 v77, v76
	v_cvt_pk_bf16_f32 v66, v72, v73
	v_cvt_pk_bf16_f32 v67, v74, v75
	global_store_dwordx4 v[90:91], v[64:67], off
	s_waitcnt lgkmcnt(0)
	s_nop 0
	v_add_f32_e32 v64, v76, v77
	v_mov_b32_e32 v65, v64
	s_nop 1
	v_permlane32_swap_b32_e32 v65, v64
	v_cvt_pk_bf16_f32 v66, v68, v69
	v_cvt_pk_bf16_f32 v67, v70, v71
	v_cvt_pk_bf16_f32 v68, v84, v85
	v_cvt_pk_bf16_f32 v69, v82, v83
	global_store_dwordx4 v[90:91], v[66:69], off offset:256
	s_and_saveexec_b64 s[56:57], s[6:7]
	s_cbranch_execz .LBB0_661
	s_waitcnt lgkmcnt(0)
	v_add_f32_e32 v64, v64, v65
	v_mul_f32_e32 v64, 0x4f800000, v64
	v_trunc_f32_e32 v64, v64
	v_mul_f32_e64 v65, |v64|, s87
	v_floor_f32_e32 v65, v65
	v_fma_f32 v66, v65, s88, |v64|
	v_cvt_u32_f32_e32 v64, v66
	v_cvt_u32_f32_e32 v65, v65
	v_lshl_add_u64 v[66:67], v[80:81], 3, s[10:11]
	global_atomic_add_x2 v[66:67], v[64:65], off
; __device__ __forceinline__ void fx_add(float* p, size_t idx, float s) { atomicAdd((unsigned long long*)p + idx, (unsigned long long)(long long)(s * 4294967296.0f)); }
; __device__ __forceinline__ unsigned cvtpk(float lo, float hi) { f32x2v_ v = {lo, hi}; bf16x2v_ b = __builtin_convertvector(v, bf16x2v_); return __builtin_bit_cast(unsigned, b); }
;     __device__ __forceinline__ void operator()(const f32x4 (&acc)[2][2][4][2], const Unit& u, int wr, int wc, int fr, int fq) const {
;     ...
;             for (int m = 0; m < 4; ++m) { const int row = row0 + ai * HALF + m * 16; const size_t off = (size_t)row * 1024 + col0; float s = 0.f;
; #pragma unroll
;                 for (int bj = 0; bj < 2; ++bj) { f32x4 a0, a1;
;                     if (xin32) { const float* p = xin32 + off + bj * HALF; a0 = *(const f32x4*)p; a1 = *(const f32x4*)(p + 4); }
;                     else { const u32x4 w = *(const u32x4*)(xb + off + bj * HALF);
;                         a0 = (f32x4){__uint_as_float(w.x << 16), __uint_as_float(w.x & 0xffff0000u), __uint_as_float(w.y << 16), __uint_as_float(w.y & 0xffff0000u)};
;                         a1 = (f32x4){__uint_as_float(w.z << 16), __uint_as_float(w.z & 0xffff0000u), __uint_as_float(w.w << 16), __uint_as_float(w.w & 0xffff0000u)}; }
;                     const f32x4 v0 = a0 + acc[ai][bj][m][0] * alpha, v1 = a1 + acc[ai][bj][m][1] * alpha;
;                     u32x4 w; w.x = cvtpk(v0[0], v0[1]); w.y = cvtpk(v0[2], v0[3]); w.z = cvtpk(v1[0], v1[1]); w.w = cvtpk(v1[2], v1[3]);
;                     *(u32x4*)(xb + off + bj * HALF) = w;
;                     s += (v0[0] * v0[0] + v0[1] * v0[1]) + (v0[2] * v0[2] + v0[3] * v0[3]) + (v1[0] * v1[0] + v1[1] * v1[1]) + (v1[2] * v1[2] + v1[3] * v1[3]); }
;                 s += __shfl_xor(s, 16); s += __shfl_xor(s, 32);
;                 if (fq == 0) fx_add(ssout, row, s); }
.LBB0_661:
	s_or_b64 exec, exec, s[56:57]
	v_add_u32_e32 v64, 0x80, v150
	s_waitcnt lgkmcnt(0)
	v_ashrrev_i32_e32 v65, 31, v64
	v_lshlrev_b64 v[66:67], 11, v[64:65]
	v_lshl_add_u64 v[66:67], s[22:23], 0, v[66:67]
	v_lshl_add_u64 v[74:75], v[148:149], 1, v[66:67]
	global_load_dwordx4 v[66:69], v[74:75], off
	global_load_dwordx4 v[70:73], v[74:75], off offset:256
	s_waitcnt vmcnt(1)
	v_lshlrev_b32_e32 v76, 16, v66
	v_and_b32_e32 v77, 0xffff0000, v66
	v_lshlrev_b32_e32 v66, 16, v67
	v_and_b32_e32 v67, 0xffff0000, v67
	s_waitcnt vmcnt(0)
	v_lshlrev_b32_e32 v80, 16, v70
	v_and_b32_e32 v81, 0xffff0000, v70
	v_lshlrev_b32_e32 v70, 16, v71
	v_and_b32_e32 v71, 0xffff0000, v71
	v_lshlrev_b32_e32 v78, 16, v68
	v_and_b32_e32 v79, 0xffff0000, v68
	v_lshlrev_b32_e32 v68, 16, v69
	v_and_b32_e32 v69, 0xffff0000, v69
	v_lshlrev_b32_e32 v82, 16, v72
	v_and_b32_e32 v83, 0xffff0000, v72
	v_lshlrev_b32_e32 v72, 16, v73
	v_and_b32_e32 v73, 0xffff0000, v73
	v_pk_add_f32 v[62:63], v[62:63], v[66:67]
	v_pk_add_f32 v[60:61], v[60:61], v[76:77]
	v_pk_add_f32 v[54:55], v[54:55], v[70:71]
	v_pk_add_f32 v[52:53], v[52:53], v[80:81]
	v_pk_add_f32 v[58:59], v[58:59], v[68:69]
	v_pk_add_f32 v[56:57], v[56:57], v[78:79]
	v_pk_add_f32 v[66:67], v[50:51], v[72:73]
	v_pk_add_f32 v[68:69], v[48:49], v[82:83]
	v_mul_f32_e32 v50, v61, v61
	v_mul_f32_e32 v51, v63, v63
	v_mul_f32_e32 v70, v53, v53
	v_mul_f32_e32 v71, v55, v55
	v_cvt_pk_bf16_f32 v48, v60, v61
	v_mul_f32_e32 v61, v57, v57
	v_mul_f32_e32 v72, v69, v69
	v_fmac_f32_e32 v50, v60, v60
	v_fmac_f32_e32 v51, v62, v62
	v_fmac_f32_e32 v70, v52, v52
	v_fmac_f32_e32 v71, v54, v54
	v_cvt_pk_bf16_f32 v49, v62, v63
	v_mul_f32_e32 v63, v59, v59
	v_mul_f32_e32 v73, v67, v67
	v_fmac_f32_e32 v61, v56, v56
	v_fmac_f32_e32 v72, v68, v68
	v_add_f32_e32 v50, v50, v51
	v_add_f32_e32 v51, v70, v71
	v_fmac_f32_e32 v63, v58, v58
	v_fmac_f32_e32 v73, v66, v66
	v_add_f32_e32 v50, v61, v50
	v_add_f32_e32 v51, v72, v51
	v_add_f32_e32 v50, v63, v50
	v_add_f32_e32 v51, v73, v51
	v_add_f32_e32 v60, v50, v51
	v_mov_b32_e32 v61, v60
	s_nop 1
	v_permlane16_swap_b32_e32 v61, v60
	v_cvt_pk_bf16_f32 v50, v56, v57
	v_cvt_pk_bf16_f32 v51, v58, v59
	global_store_dwordx4 v[74:75], v[48:51], off
	s_waitcnt lgkmcnt(0)
	s_nop 0
	v_add_f32_e32 v48, v60, v61
	v_mov_b32_e32 v49, v48
	s_nop 1
	v_permlane32_swap_b32_e32 v49, v48
	v_cvt_pk_bf16_f32 v50, v52, v53
	v_cvt_pk_bf16_f32 v51, v54, v55
	v_cvt_pk_bf16_f32 v52, v68, v69
	v_cvt_pk_bf16_f32 v53, v66, v67
	global_store_dwordx4 v[74:75], v[50:53], off offset:256
	s_and_saveexec_b64 s[56:57], s[6:7]
	s_cbranch_execz .LBB0_663
	s_waitcnt lgkmcnt(0)
	v_add_f32_e32 v48, v48, v49
	v_mul_f32_e32 v48, 0x4f800000, v48
	v_trunc_f32_e32 v48, v48
	v_mul_f32_e64 v49, |v48|, s87
	v_floor_f32_e32 v49, v49
	v_fma_f32 v50, v49, s88, |v48|
	v_cvt_u32_f32_e32 v48, v50
	v_cvt_u32_f32_e32 v49, v49
	v_lshl_add_u64 v[50:51], v[64:65], 3, s[10:11]
	global_atomic_add_x2 v[50:51], v[48:49], off
.LBB0_663:
	s_or_b64 exec, exec, s[56:57]
	v_add_u32_e32 v48, 0x90, v150
	s_waitcnt lgkmcnt(0)
	v_ashrrev_i32_e32 v49, 31, v48
	v_lshlrev_b64 v[50:51], 11, v[48:49]
	v_lshl_add_u64 v[50:51], s[22:23], 0, v[50:51]
	v_lshl_add_u64 v[58:59], v[148:149], 1, v[50:51]
	global_load_dwordx4 v[50:53], v[58:59], off
	global_load_dwordx4 v[54:57], v[58:59], off offset:256
	s_waitcnt vmcnt(1)
	v_lshlrev_b32_e32 v60, 16, v50
	v_and_b32_e32 v61, 0xffff0000, v50
	v_lshlrev_b32_e32 v50, 16, v51
	v_and_b32_e32 v51, 0xffff0000, v51
	s_waitcnt vmcnt(0)
	v_lshlrev_b32_e32 v64, 16, v54
	v_and_b32_e32 v65, 0xffff0000, v54
	v_lshlrev_b32_e32 v54, 16, v55
	v_and_b32_e32 v55, 0xffff0000, v55
	v_lshlrev_b32_e32 v62, 16, v52
	v_and_b32_e32 v63, 0xffff0000, v52
	v_lshlrev_b32_e32 v52, 16, v53
	v_and_b32_e32 v53, 0xffff0000, v53
	v_lshlrev_b32_e32 v66, 16, v56
	v_and_b32_e32 v67, 0xffff0000, v56
	v_lshlrev_b32_e32 v56, 16, v57
	v_and_b32_e32 v57, 0xffff0000, v57
	v_pk_add_f32 v[46:47], v[46:47], v[50:51]
	v_pk_add_f32 v[44:45], v[44:45], v[60:61]
	v_pk_add_f32 v[38:39], v[38:39], v[54:55]
	v_pk_add_f32 v[36:37], v[36:37], v[64:65]
	v_pk_add_f32 v[42:43], v[42:43], v[52:53]
	v_pk_add_f32 v[40:41], v[40:41], v[62:63]
	v_pk_add_f32 v[50:51], v[34:35], v[56:57]
	v_pk_add_f32 v[52:53], v[32:33], v[66:67]
	v_mul_f32_e32 v34, v45, v45
	v_mul_f32_e32 v35, v47, v47
	v_mul_f32_e32 v54, v37, v37
	v_mul_f32_e32 v55, v39, v39
	v_cvt_pk_bf16_f32 v32, v44, v45
	v_mul_f32_e32 v45, v41, v41
	v_mul_f32_e32 v56, v53, v53
	v_fmac_f32_e32 v34, v44, v44
	v_fmac_f32_e32 v35, v46, v46
	v_fmac_f32_e32 v54, v36, v36
	v_fmac_f32_e32 v55, v38, v38
	v_cvt_pk_bf16_f32 v33, v46, v47
	v_mul_f32_e32 v47, v43, v43
	v_mul_f32_e32 v57, v51, v51
	v_fmac_f32_e32 v45, v40, v40
	v_fmac_f32_e32 v56, v52, v52
	v_add_f32_e32 v34, v34, v35
	v_add_f32_e32 v35, v54, v55
	v_fmac_f32_e32 v47, v42, v42
	v_fmac_f32_e32 v57, v50, v50
	v_add_f32_e32 v34, v45, v34
	v_add_f32_e32 v35, v56, v35
	v_add_f32_e32 v34, v47, v34
	v_add_f32_e32 v35, v57, v35
	v_add_f32_e32 v44, v34, v35
	v_mov_b32_e32 v45, v44
	s_nop 1
	v_permlane16_swap_b32_e32 v45, v44
	v_cvt_pk_bf16_f32 v34, v40, v41
	v_cvt_pk_bf16_f32 v35, v42, v43
	global_store_dwordx4 v[58:59], v[32:35], off
	s_waitcnt lgkmcnt(0)
	s_nop 0
	v_add_f32_e32 v32, v44, v45
	v_mov_b32_e32 v33, v32
	s_nop 1
	v_permlane32_swap_b32_e32 v33, v32
	v_cvt_pk_bf16_f32 v34, v36, v37
	v_cvt_pk_bf16_f32 v35, v38, v39
	v_cvt_pk_bf16_f32 v36, v52, v53
	v_cvt_pk_bf16_f32 v37, v50, v51
	global_store_dwordx4 v[58:59], v[34:37], off offset:256
	s_and_saveexec_b64 s[56:57], s[6:7]
	s_cbranch_execz .LBB0_665
	s_waitcnt lgkmcnt(0)
	v_add_f32_e32 v32, v32, v33
	v_mul_f32_e32 v32, 0x4f800000, v32
	v_trunc_f32_e32 v32, v32
	v_mul_f32_e64 v33, |v32|, s87
	v_floor_f32_e32 v33, v33
	v_fma_f32 v34, v33, s88, |v32|
	v_cvt_u32_f32_e32 v32, v34
	v_cvt_u32_f32_e32 v33, v33
	v_lshl_add_u64 v[34:35], v[48:49], 3, s[10:11]
	global_atomic_add_x2 v[34:35], v[32:33], off
; __device__ __forceinline__ void fx_add(float* p, size_t idx, float s) { atomicAdd((unsigned long long*)p + idx, (unsigned long long)(long long)(s * 4294967296.0f)); }
; __device__ __forceinline__ unsigned cvtpk(float lo, float hi) { f32x2v_ v = {lo, hi}; bf16x2v_ b = __builtin_convertvector(v, bf16x2v_); return __builtin_bit_cast(unsigned, b); }
;     __device__ __forceinline__ void operator()(const f32x4 (&acc)[2][2][4][2], const Unit& u, int wr, int wc, int fr, int fq) const {
;     ...
;             for (int m = 0; m < 4; ++m) { const int row = row0 + ai * HALF + m * 16; const size_t off = (size_t)row * 1024 + col0; float s = 0.f;
; #pragma unroll
;                 for (int bj = 0; bj < 2; ++bj) { f32x4 a0, a1;
;                     if (xin32) { const float* p = xin32 + off + bj * HALF; a0 = *(const f32x4*)p; a1 = *(const f32x4*)(p + 4); }
;                     else { const u32x4 w = *(const u32x4*)(xb + off + bj * HALF);
;                         a0 = (f32x4){__uint_as_float(w.x << 16), __uint_as_float(w.x & 0xffff0000u), __uint_as_float(w.y << 16), __uint_as_float(w.y & 0xffff0000u)};
;                         a1 = (f32x4){__uint_as_float(w.z << 16), __uint_as_float(w.z & 0xffff0000u), __uint_as_float(w.w << 16), __uint_as_float(w.w & 0xffff0000u)}; }
;                     const f32x4 v0 = a0 + acc[ai][bj][m][0] * alpha, v1 = a1 + acc[ai][bj][m][1] * alpha;
;                     u32x4 w; w.x = cvtpk(v0[0], v0[1]); w.y = cvtpk(v0[2], v0[3]); w.z = cvtpk(v1[0], v1[1]); w.w = cvtpk(v1[2], v1[3]);
;                     *(u32x4*)(xb + off + bj * HALF) = w;
;                     s += (v0[0] * v0[0] + v0[1] * v0[1]) + (v0[2] * v0[2] + v0[3] * v0[3]) + (v1[0] * v1[0] + v1[1] * v1[1]) + (v1[2] * v1[2] + v1[3] * v1[3]); }
;                 s += __shfl_xor(s, 16); s += __shfl_xor(s, 32);
;                 if (fq == 0) fx_add(ssout, row, s); }
.LBB0_665:
	s_or_b64 exec, exec, s[56:57]
	v_add_u32_e32 v32, 0xa0, v150
	s_waitcnt lgkmcnt(0)
	v_ashrrev_i32_e32 v33, 31, v32
	v_lshlrev_b64 v[34:35], 11, v[32:33]
	v_lshl_add_u64 v[34:35], s[22:23], 0, v[34:35]
	v_lshl_add_u64 v[42:43], v[148:149], 1, v[34:35]
	global_load_dwordx4 v[34:37], v[42:43], off
	global_load_dwordx4 v[38:41], v[42:43], off offset:256
	s_waitcnt vmcnt(1)
	v_lshlrev_b32_e32 v44, 16, v34
	v_and_b32_e32 v45, 0xffff0000, v34
	v_lshlrev_b32_e32 v34, 16, v35
	v_and_b32_e32 v35, 0xffff0000, v35
	s_waitcnt vmcnt(0)
	v_lshlrev_b32_e32 v48, 16, v38
	v_and_b32_e32 v49, 0xffff0000, v38
	v_lshlrev_b32_e32 v38, 16, v39
	v_and_b32_e32 v39, 0xffff0000, v39
	v_lshlrev_b32_e32 v46, 16, v36
	v_and_b32_e32 v47, 0xffff0000, v36
	v_lshlrev_b32_e32 v36, 16, v37
	v_and_b32_e32 v37, 0xffff0000, v37
	v_lshlrev_b32_e32 v50, 16, v40
	v_and_b32_e32 v51, 0xffff0000, v40
	v_lshlrev_b32_e32 v40, 16, v41
	v_and_b32_e32 v41, 0xffff0000, v41
	v_pk_add_f32 v[30:31], v[30:31], v[34:35]
	v_pk_add_f32 v[28:29], v[28:29], v[44:45]
	v_pk_add_f32 v[22:23], v[22:23], v[38:39]
	v_pk_add_f32 v[20:21], v[20:21], v[48:49]
	v_pk_add_f32 v[26:27], v[26:27], v[36:37]
	v_pk_add_f32 v[24:25], v[24:25], v[46:47]
	v_pk_add_f32 v[34:35], v[18:19], v[40:41]
	v_pk_add_f32 v[36:37], v[16:17], v[50:51]
	v_mul_f32_e32 v18, v29, v29
	v_mul_f32_e32 v19, v31, v31
	v_mul_f32_e32 v38, v21, v21
	v_mul_f32_e32 v39, v23, v23
	v_cvt_pk_bf16_f32 v16, v28, v29
	v_mul_f32_e32 v29, v25, v25
	v_mul_f32_e32 v40, v37, v37
	v_fmac_f32_e32 v18, v28, v28
	v_fmac_f32_e32 v19, v30, v30
	v_fmac_f32_e32 v38, v20, v20
	v_fmac_f32_e32 v39, v22, v22
	v_cvt_pk_bf16_f32 v17, v30, v31
	v_mul_f32_e32 v31, v27, v27
	v_mul_f32_e32 v41, v35, v35
	v_fmac_f32_e32 v29, v24, v24
	v_fmac_f32_e32 v40, v36, v36
	v_add_f32_e32 v18, v18, v19
	v_add_f32_e32 v19, v38, v39
	v_fmac_f32_e32 v31, v26, v26
	v_fmac_f32_e32 v41, v34, v34
	v_add_f32_e32 v18, v29, v18
	v_add_f32_e32 v19, v40, v19
	v_add_f32_e32 v18, v31, v18
	v_add_f32_e32 v19, v41, v19
	v_add_f32_e32 v28, v18, v19
	v_mov_b32_e32 v29, v28
	s_nop 1
	v_permlane16_swap_b32_e32 v29, v28
	v_cvt_pk_bf16_f32 v18, v24, v25
	v_cvt_pk_bf16_f32 v19, v26, v27
	global_store_dwordx4 v[42:43], v[16:19], off
	s_waitcnt lgkmcnt(0)
	s_nop 0
	v_add_f32_e32 v16, v28, v29
	v_mov_b32_e32 v17, v16
	s_nop 1
	v_permlane32_swap_b32_e32 v17, v16
	v_cvt_pk_bf16_f32 v18, v20, v21
	v_cvt_pk_bf16_f32 v19, v22, v23
	v_cvt_pk_bf16_f32 v20, v36, v37
	v_cvt_pk_bf16_f32 v21, v34, v35
	global_store_dwordx4 v[42:43], v[18:21], off offset:256
	s_and_saveexec_b64 s[56:57], s[6:7]
	s_cbranch_execz .LBB0_667
	s_waitcnt lgkmcnt(0)
	v_add_f32_e32 v16, v16, v17
	v_mul_f32_e32 v16, 0x4f800000, v16
	v_trunc_f32_e32 v16, v16
	v_mul_f32_e64 v17, |v16|, s87
	v_floor_f32_e32 v17, v17
	v_fma_f32 v18, v17, s88, |v16|
	v_cvt_u32_f32_e32 v16, v18
	v_cvt_u32_f32_e32 v17, v17
	v_lshl_add_u64 v[18:19], v[32:33], 3, s[10:11]
	global_atomic_add_x2 v[18:19], v[16:17], off
.LBB0_667:
	s_or_b64 exec, exec, s[56:57]
	v_add_u32_e32 v16, 0xb0, v150
	s_waitcnt lgkmcnt(0)
	v_ashrrev_i32_e32 v17, 31, v16
	v_lshlrev_b64 v[18:19], 11, v[16:17]
	v_lshl_add_u64 v[18:19], s[22:23], 0, v[18:19]
	v_lshl_add_u64 v[26:27], v[148:149], 1, v[18:19]
	global_load_dwordx4 v[18:21], v[26:27], off
	global_load_dwordx4 v[22:25], v[26:27], off offset:256
	s_waitcnt vmcnt(1)
	v_lshlrev_b32_e32 v28, 16, v18
	v_and_b32_e32 v29, 0xffff0000, v18
	v_lshlrev_b32_e32 v18, 16, v19
	v_and_b32_e32 v19, 0xffff0000, v19
	s_waitcnt vmcnt(0)
	v_lshlrev_b32_e32 v32, 16, v22
	v_and_b32_e32 v33, 0xffff0000, v22
	v_lshlrev_b32_e32 v22, 16, v23
	v_and_b32_e32 v23, 0xffff0000, v23
	v_lshlrev_b32_e32 v30, 16, v20
	v_and_b32_e32 v31, 0xffff0000, v20
	v_lshlrev_b32_e32 v20, 16, v21
	v_and_b32_e32 v21, 0xffff0000, v21
	v_lshlrev_b32_e32 v34, 16, v24
	v_and_b32_e32 v35, 0xffff0000, v24
	v_lshlrev_b32_e32 v24, 16, v25
	v_and_b32_e32 v25, 0xffff0000, v25
	v_pk_add_f32 v[14:15], v[14:15], v[18:19]
	v_pk_add_f32 v[12:13], v[12:13], v[28:29]
	v_pk_add_f32 v[6:7], v[6:7], v[22:23]
	v_pk_add_f32 v[4:5], v[4:5], v[32:33]
	v_pk_add_f32 v[10:11], v[10:11], v[20:21]
	v_pk_add_f32 v[8:9], v[8:9], v[30:31]
	v_pk_add_f32 v[18:19], v[2:3], v[24:25]
	v_pk_add_f32 v[20:21], v[0:1], v[34:35]
	v_mul_f32_e32 v2, v13, v13
	v_mul_f32_e32 v3, v15, v15
	v_mul_f32_e32 v22, v5, v5
	v_mul_f32_e32 v23, v7, v7
	v_cvt_pk_bf16_f32 v0, v12, v13
	v_mul_f32_e32 v13, v9, v9
	v_mul_f32_e32 v24, v21, v21
	v_fmac_f32_e32 v2, v12, v12
	v_fmac_f32_e32 v3, v14, v14
	v_fmac_f32_e32 v22, v4, v4
	v_fmac_f32_e32 v23, v6, v6
	v_cvt_pk_bf16_f32 v1, v14, v15
	v_mul_f32_e32 v15, v11, v11
	v_mul_f32_e32 v25, v19, v19
	v_fmac_f32_e32 v13, v8, v8
	v_fmac_f32_e32 v24, v20, v20
	v_add_f32_e32 v2, v2, v3
	v_add_f32_e32 v3, v22, v23
	v_fmac_f32_e32 v15, v10, v10
	v_fmac_f32_e32 v25, v18, v18
	v_add_f32_e32 v2, v13, v2
	v_add_f32_e32 v3, v24, v3
	v_add_f32_e32 v2, v15, v2
	v_add_f32_e32 v3, v25, v3
	v_add_f32_e32 v12, v2, v3
	v_mov_b32_e32 v13, v12
	s_nop 1
	v_permlane16_swap_b32_e32 v13, v12
	v_cvt_pk_bf16_f32 v2, v8, v9
	v_cvt_pk_bf16_f32 v3, v10, v11
	global_store_dwordx4 v[26:27], v[0:3], off
	s_waitcnt lgkmcnt(0)
	s_nop 0
	v_add_f32_e32 v0, v12, v13
	v_mov_b32_e32 v1, v0
	s_nop 1
	v_permlane32_swap_b32_e32 v1, v0
	v_cvt_pk_bf16_f32 v2, v4, v5
	v_cvt_pk_bf16_f32 v3, v6, v7
	v_cvt_pk_bf16_f32 v4, v20, v21
	v_cvt_pk_bf16_f32 v5, v18, v19
	global_store_dwordx4 v[26:27], v[2:5], off offset:256
	s_and_saveexec_b64 s[56:57], s[6:7]
	s_cbranch_execz .LBB0_669
	s_waitcnt lgkmcnt(0)
	v_add_f32_e32 v0, v0, v1
	v_mul_f32_e32 v0, 0x4f800000, v0
	v_trunc_f32_e32 v0, v0
	v_mul_f32_e64 v1, |v0|, s87
	v_floor_f32_e32 v1, v1
	v_fma_f32 v2, v1, s88, |v0|
	v_cvt_u32_f32_e32 v0, v2
	v_cvt_u32_f32_e32 v1, v1
	v_lshl_add_u64 v[2:3], v[16:17], 3, s[10:11]
	global_atomic_add_x2 v[2:3], v[0:1], off

; __device__ __forceinline__ unsigned cvtpk(float lo, float hi) { f32x2v_ v = {lo, hi}; bf16x2v_ b = __builtin_convertvector(v, bf16x2v_); return __builtin_bit_cast(unsigned, b); }
; __device__ __forceinline__ void fx_add(float* p, size_t idx, float s) { atomicAdd((unsigned long long*)p + idx, (unsigned long long)(long long)(s * 4294967296.0f)); }
;     __device__ __forceinline__ void operator()(const f32x4 (&acc)[2][2][4][2], const Unit& u, int wr, int wc, int fr, int fq) const {
;         const int row0 = u.pm * BM + wr * 64 + fr, col0 = u.pn * BM + wc * 32 + 8 * fq;
; #pragma unroll
;         for (int ai = 0; ai < 2; ++ai)
; #pragma unroll
;             for (int m = 0; m < 4; ++m) { const int row = row0 + ai * HALF + m * 16; const size_t off = (size_t)row * 1024 + col0; float s = 0.f;
; #pragma unroll
;                 for (int bj = 0; bj < 2; ++bj) { f32x4 a0, a1;
;                     if (xin32) { const float* p = xin32 + off + bj * HALF; a0 = *(const f32x4*)p; a1 = *(const f32x4*)(p + 4); }
;                     else { const u32x4 w = *(const u32x4*)(xb + off + bj * HALF);
;                         a0 = (f32x4){__uint_as_float(w.x << 16), __uint_as_float(w.x & 0xffff0000u), __uint_as_float(w.y << 16), __uint_as_float(w.y & 0xffff0000u)};
;                         a1 = (f32x4){__uint_as_float(w.z << 16), __uint_as_float(w.z & 0xffff0000u), __uint_as_float(w.w << 16), __uint_as_float(w.w & 0xffff0000u)}; }
;                     const f32x4 v0 = a0 + acc[ai][bj][m][0] * alpha, v1 = a1 + acc[ai][bj][m][1] * alpha;
;                     u32x4 w; w.x = cvtpk(v0[0], v0[1]); w.y = cvtpk(v0[2], v0[3]); w.z = cvtpk(v1[0], v1[1]); w.w = cvtpk(v1[2], v1[3]);
;                     *(u32x4*)(xb + off + bj * HALF) = w;
;                     s += (v0[0] * v0[0] + v0[1] * v0[1]) + (v0[2] * v0[2] + v0[3] * v0[3]) + (v1[0] * v1[0] + v1[1] * v1[1]) + (v1[2] * v1[2] + v1[3] * v1[3]); }
;                 s += __shfl_xor(s, 16); s += __shfl_xor(s, 32);
;                 if (fq == 0) fx_add(ssout, row, s); }
.LBB0_876:
	v_lshl_add_u32 v146, s56, 8, v148
	v_ashrrev_i32_e32 v147, 31, v146
	v_lshl_or_b32 v144, s54, 8, v150
	v_lshlrev_b64 v[156:157], 11, v[146:147]
	v_ashrrev_i32_e32 v145, 31, v144
	v_lshl_add_u64 v[156:157], s[22:23], 0, v[156:157]
	v_lshl_add_u64 v[166:167], v[144:145], 1, v[156:157]
	global_load_dwordx4 v[158:161], v[166:167], off
	global_load_dwordx4 v[162:165], v[166:167], off offset:256
	v_and_b32_e32 v156, 64, v154
	v_xor_b32_e32 v155, 16, v154
	v_add_u32_e32 v156, 64, v156
	v_xor_b32_e32 v157, 32, v154
	v_cmp_lt_i32_e32 vcc, v155, v156
	s_waitcnt vmcnt(0)
	v_lshlrev_b32_e32 v168, 16, v158
	v_cndmask_b32_e32 v155, v154, v155, vcc
	v_cmp_lt_i32_e32 vcc, v157, v156
	v_and_b32_e32 v169, 0xffff0000, v158
	v_lshlrev_b32_e32 v158, 16, v159
	v_and_b32_e32 v159, 0xffff0000, v159
	v_lshlrev_b32_e32 v172, 16, v162
	v_and_b32_e32 v173, 0xffff0000, v162
	v_lshlrev_b32_e32 v162, 16, v163
	v_and_b32_e32 v163, 0xffff0000, v163
	v_cndmask_b32_e32 v157, v154, v157, vcc
	v_lshlrev_b32_e32 v170, 16, v160
	v_and_b32_e32 v171, 0xffff0000, v160
	v_lshlrev_b32_e32 v160, 16, v161
	v_and_b32_e32 v161, 0xffff0000, v161
	v_lshlrev_b32_e32 v174, 16, v164
	v_and_b32_e32 v175, 0xffff0000, v164
	v_lshlrev_b32_e32 v164, 16, v165
	v_and_b32_e32 v165, 0xffff0000, v165
	v_pk_add_f32 v[126:127], v[126:127], v[158:159]
	v_pk_add_f32 v[124:125], v[124:125], v[168:169]
	v_pk_add_f32 v[118:119], v[118:119], v[162:163]
	v_pk_add_f32 v[116:117], v[116:117], v[172:173]
	v_lshlrev_b32_e32 v156, 2, v155
	v_lshlrev_b32_e32 v155, 2, v157
	v_pk_add_f32 v[122:123], v[122:123], v[160:161]
	v_pk_add_f32 v[120:121], v[120:121], v[170:171]
	v_pk_add_f32 v[158:159], v[114:115], v[164:165]
	v_pk_add_f32 v[160:161], v[112:113], v[174:175]
	v_mul_f32_e32 v114, v125, v125
	v_mul_f32_e32 v115, v127, v127
	v_mul_f32_e32 v157, v117, v117
	v_mul_f32_e32 v162, v119, v119
	v_cvt_pk_bf16_f32 v112, v124, v125
	v_mul_f32_e32 v125, v121, v121
	v_mul_f32_e32 v163, v161, v161
	v_fmac_f32_e32 v114, v124, v124
	v_fmac_f32_e32 v115, v126, v126
	v_fmac_f32_e32 v157, v116, v116
	v_fmac_f32_e32 v162, v118, v118
	v_cvt_pk_bf16_f32 v113, v126, v127
	v_mul_f32_e32 v127, v123, v123
	v_mul_f32_e32 v164, v159, v159
	v_fmac_f32_e32 v125, v120, v120
	v_fmac_f32_e32 v163, v160, v160
	v_add_f32_e32 v114, v114, v115
	v_add_f32_e32 v115, v157, v162
	v_fmac_f32_e32 v127, v122, v122
	v_fmac_f32_e32 v164, v158, v158
	v_add_f32_e32 v114, v125, v114
	v_add_f32_e32 v115, v163, v115
	v_add_f32_e32 v114, v127, v114
	v_add_f32_e32 v115, v164, v115
	v_add_f32_e32 v124, v114, v115
	v_mov_b32_e32 v125, v124
	s_nop 1
	v_permlane16_swap_b32_e32 v125, v124
	v_cvt_pk_bf16_f32 v114, v120, v121
	v_cvt_pk_bf16_f32 v115, v122, v123
	global_store_dwordx4 v[166:167], v[112:115], off
	s_waitcnt lgkmcnt(0)
	s_nop 0
	v_add_f32_e32 v112, v124, v125
	v_mov_b32_e32 v113, v112
	s_nop 1
	v_permlane32_swap_b32_e32 v113, v112
	v_cvt_pk_bf16_f32 v114, v116, v117
	v_cvt_pk_bf16_f32 v115, v118, v119
	v_cvt_pk_bf16_f32 v116, v160, v161
	v_cvt_pk_bf16_f32 v117, v158, v159
	global_store_dwordx4 v[166:167], v[114:117], off offset:256
	s_and_saveexec_b64 s[54:55], s[8:9]
	s_cbranch_execz .LBB0_878
	s_waitcnt lgkmcnt(0)
	v_add_f32_e32 v112, v112, v113
	v_mul_f32_e32 v112, 0x4f800000, v112
	v_trunc_f32_e32 v112, v112
	v_mul_f32_e64 v113, |v112|, s82
	v_floor_f32_e32 v113, v113
	v_fma_f32 v114, v113, s83, |v112|
	v_cvt_u32_f32_e32 v112, v114
	v_cvt_u32_f32_e32 v113, v113
	v_lshl_add_u64 v[114:115], v[146:147], 3, s[0:1]
	global_atomic_add_x2 v[114:115], v[112:113], off
.LBB0_878:
	s_or_b64 exec, exec, s[54:55]
	v_or_b32_e32 v112, 16, v146
	s_waitcnt lgkmcnt(0)
	v_ashrrev_i32_e32 v113, 31, v112
	v_lshlrev_b64 v[114:115], 11, v[112:113]
	v_lshl_add_u64 v[114:115], s[22:23], 0, v[114:115]
	v_lshl_add_u64 v[122:123], v[144:145], 1, v[114:115]
	global_load_dwordx4 v[114:117], v[122:123], off
	global_load_dwordx4 v[118:121], v[122:123], off offset:256
	s_waitcnt vmcnt(1)
	v_lshlrev_b32_e32 v124, 16, v114
	v_and_b32_e32 v125, 0xffff0000, v114
	v_lshlrev_b32_e32 v114, 16, v115
	v_and_b32_e32 v115, 0xffff0000, v115
	s_waitcnt vmcnt(0)
	v_lshlrev_b32_e32 v158, 16, v118
	v_and_b32_e32 v159, 0xffff0000, v118
	v_lshlrev_b32_e32 v118, 16, v119
	v_and_b32_e32 v119, 0xffff0000, v119
	v_lshlrev_b32_e32 v126, 16, v116
	v_and_b32_e32 v127, 0xffff0000, v116
	v_lshlrev_b32_e32 v116, 16, v117
	v_and_b32_e32 v117, 0xffff0000, v117
	v_lshlrev_b32_e32 v160, 16, v120
	v_and_b32_e32 v161, 0xffff0000, v120
	v_lshlrev_b32_e32 v120, 16, v121
	v_and_b32_e32 v121, 0xffff0000, v121
	v_pk_add_f32 v[110:111], v[110:111], v[114:115]
	v_pk_add_f32 v[108:109], v[108:109], v[124:125]
	v_pk_add_f32 v[102:103], v[102:103], v[118:119]
	v_pk_add_f32 v[100:101], v[100:101], v[158:159]
	v_pk_add_f32 v[106:107], v[106:107], v[116:117]
	v_pk_add_f32 v[104:105], v[104:105], v[126:127]
	v_pk_add_f32 v[114:115], v[98:99], v[120:121]
	v_pk_add_f32 v[116:117], v[96:97], v[160:161]
	v_mul_f32_e32 v98, v109, v109
	v_mul_f32_e32 v99, v111, v111
	v_mul_f32_e32 v118, v101, v101
	v_mul_f32_e32 v119, v103, v103
	v_cvt_pk_bf16_f32 v96, v108, v109
	v_mul_f32_e32 v109, v105, v105
	v_mul_f32_e32 v120, v117, v117
	v_fmac_f32_e32 v98, v108, v108
	v_fmac_f32_e32 v99, v110, v110
	v_fmac_f32_e32 v118, v100, v100
	v_fmac_f32_e32 v119, v102, v102
	v_cvt_pk_bf16_f32 v97, v110, v111
	v_mul_f32_e32 v111, v107, v107
	v_mul_f32_e32 v121, v115, v115
	v_fmac_f32_e32 v109, v104, v104
	v_fmac_f32_e32 v120, v116, v116
	v_add_f32_e32 v98, v98, v99
	v_add_f32_e32 v99, v118, v119
	v_fmac_f32_e32 v111, v106, v106
	v_fmac_f32_e32 v121, v114, v114
	v_add_f32_e32 v98, v109, v98
	v_add_f32_e32 v99, v120, v99
	v_add_f32_e32 v98, v111, v98
	v_add_f32_e32 v99, v121, v99
	v_add_f32_e32 v108, v98, v99
	v_mov_b32_e32 v109, v108
	s_nop 1
	v_permlane16_swap_b32_e32 v109, v108
	v_cvt_pk_bf16_f32 v98, v104, v105
	v_cvt_pk_bf16_f32 v99, v106, v107
	global_store_dwordx4 v[122:123], v[96:99], off
	s_waitcnt lgkmcnt(0)
	s_nop 0
	v_add_f32_e32 v96, v108, v109
	v_mov_b32_e32 v97, v96
	s_nop 1
	v_permlane32_swap_b32_e32 v97, v96
	v_cvt_pk_bf16_f32 v98, v100, v101
	v_cvt_pk_bf16_f32 v99, v102, v103
	v_cvt_pk_bf16_f32 v100, v116, v117
	v_cvt_pk_bf16_f32 v101, v114, v115
	global_store_dwordx4 v[122:123], v[98:101], off offset:256
	s_and_saveexec_b64 s[54:55], s[8:9]
	s_cbranch_execz .LBB0_880
	s_waitcnt lgkmcnt(0)
	v_add_f32_e32 v96, v96, v97
	v_mul_f32_e32 v96, 0x4f800000, v96
	v_trunc_f32_e32 v96, v96
	v_mul_f32_e64 v97, |v96|, s82
	v_floor_f32_e32 v97, v97
	v_fma_f32 v98, v97, s83, |v96|
	v_cvt_u32_f32_e32 v96, v98
	v_cvt_u32_f32_e32 v97, v97
	v_lshl_add_u64 v[98:99], v[112:113], 3, s[0:1]
	global_atomic_add_x2 v[98:99], v[96:97], off
; __device__ __forceinline__ unsigned cvtpk(float lo, float hi) { f32x2v_ v = {lo, hi}; bf16x2v_ b = __builtin_convertvector(v, bf16x2v_); return __builtin_bit_cast(unsigned, b); }
; __device__ __forceinline__ void fx_add(float* p, size_t idx, float s) { atomicAdd((unsigned long long*)p + idx, (unsigned long long)(long long)(s * 4294967296.0f)); }
;     __device__ __forceinline__ void operator()(const f32x4 (&acc)[2][2][4][2], const Unit& u, int wr, int wc, int fr, int fq) const {
;     ...
;             for (int m = 0; m < 4; ++m) { const int row = row0 + ai * HALF + m * 16; const size_t off = (size_t)row * 1024 + col0; float s = 0.f;
; #pragma unroll
;                 for (int bj = 0; bj < 2; ++bj) { f32x4 a0, a1;
;                     if (xin32) { const float* p = xin32 + off + bj * HALF; a0 = *(const f32x4*)p; a1 = *(const f32x4*)(p + 4); }
;                     else { const u32x4 w = *(const u32x4*)(xb + off + bj * HALF);
;                         a0 = (f32x4){__uint_as_float(w.x << 16), __uint_as_float(w.x & 0xffff0000u), __uint_as_float(w.y << 16), __uint_as_float(w.y & 0xffff0000u)};
;                         a1 = (f32x4){__uint_as_float(w.z << 16), __uint_as_float(w.z & 0xffff0000u), __uint_as_float(w.w << 16), __uint_as_float(w.w & 0xffff0000u)}; }
;                     const f32x4 v0 = a0 + acc[ai][bj][m][0] * alpha, v1 = a1 + acc[ai][bj][m][1] * alpha;
;                     u32x4 w; w.x = cvtpk(v0[0], v0[1]); w.y = cvtpk(v0[2], v0[3]); w.z = cvtpk(v1[0], v1[1]); w.w = cvtpk(v1[2], v1[3]);
;                     *(u32x4*)(xb + off + bj * HALF) = w;
;                     s += (v0[0] * v0[0] + v0[1] * v0[1]) + (v0[2] * v0[2] + v0[3] * v0[3]) + (v1[0] * v1[0] + v1[1] * v1[1]) + (v1[2] * v1[2] + v1[3] * v1[3]); }
;                 s += __shfl_xor(s, 16); s += __shfl_xor(s, 32);
;                 if (fq == 0) fx_add(ssout, row, s); }
.LBB0_880:
	s_or_b64 exec, exec, s[54:55]
	v_or_b32_e32 v96, 32, v146
	s_waitcnt lgkmcnt(0)
	v_ashrrev_i32_e32 v97, 31, v96
	v_lshlrev_b64 v[98:99], 11, v[96:97]
	v_lshl_add_u64 v[98:99], s[22:23], 0, v[98:99]
	v_lshl_add_u64 v[106:107], v[144:145], 1, v[98:99]
	global_load_dwordx4 v[98:101], v[106:107], off
	global_load_dwordx4 v[102:105], v[106:107], off offset:256
	s_waitcnt vmcnt(1)
	v_lshlrev_b32_e32 v108, 16, v98
	v_and_b32_e32 v109, 0xffff0000, v98
	v_lshlrev_b32_e32 v98, 16, v99
	v_and_b32_e32 v99, 0xffff0000, v99
	s_waitcnt vmcnt(0)
	v_lshlrev_b32_e32 v112, 16, v102
	v_and_b32_e32 v113, 0xffff0000, v102
	v_lshlrev_b32_e32 v102, 16, v103
	v_and_b32_e32 v103, 0xffff0000, v103
	v_lshlrev_b32_e32 v110, 16, v100
	v_and_b32_e32 v111, 0xffff0000, v100
	v_lshlrev_b32_e32 v100, 16, v101
	v_and_b32_e32 v101, 0xffff0000, v101
	v_lshlrev_b32_e32 v114, 16, v104
	v_and_b32_e32 v115, 0xffff0000, v104
	v_lshlrev_b32_e32 v104, 16, v105
	v_and_b32_e32 v105, 0xffff0000, v105
	v_pk_add_f32 v[94:95], v[94:95], v[98:99]
	v_pk_add_f32 v[92:93], v[92:93], v[108:109]
	v_pk_add_f32 v[86:87], v[86:87], v[102:103]
	v_pk_add_f32 v[84:85], v[84:85], v[112:113]
	v_pk_add_f32 v[90:91], v[90:91], v[100:101]
	v_pk_add_f32 v[88:89], v[88:89], v[110:111]
	v_pk_add_f32 v[98:99], v[82:83], v[104:105]
	v_pk_add_f32 v[100:101], v[80:81], v[114:115]
	v_mul_f32_e32 v82, v93, v93
	v_mul_f32_e32 v83, v95, v95
	v_mul_f32_e32 v102, v85, v85
	v_mul_f32_e32 v103, v87, v87
	v_cvt_pk_bf16_f32 v80, v92, v93
	v_mul_f32_e32 v93, v89, v89
	v_mul_f32_e32 v104, v101, v101
	v_fmac_f32_e32 v82, v92, v92
	v_fmac_f32_e32 v83, v94, v94
	v_fmac_f32_e32 v102, v84, v84
	v_fmac_f32_e32 v103, v86, v86
	v_cvt_pk_bf16_f32 v81, v94, v95
	v_mul_f32_e32 v95, v91, v91
	v_mul_f32_e32 v105, v99, v99
	v_fmac_f32_e32 v93, v88, v88
	v_fmac_f32_e32 v104, v100, v100
	v_add_f32_e32 v82, v82, v83
	v_add_f32_e32 v83, v102, v103
	v_fmac_f32_e32 v95, v90, v90
	v_fmac_f32_e32 v105, v98, v98
	v_add_f32_e32 v82, v93, v82
	v_add_f32_e32 v83, v104, v83
	v_add_f32_e32 v82, v95, v82
	v_add_f32_e32 v83, v105, v83
	v_add_f32_e32 v92, v82, v83
	v_mov_b32_e32 v93, v92
	s_nop 1
	v_permlane16_swap_b32_e32 v93, v92
	v_cvt_pk_bf16_f32 v82, v88, v89
	v_cvt_pk_bf16_f32 v83, v90, v91
	global_store_dwordx4 v[106:107], v[80:83], off
	s_waitcnt lgkmcnt(0)
	s_nop 0
	v_add_f32_e32 v80, v92, v93
	v_mov_b32_e32 v81, v80
	s_nop 1
	v_permlane32_swap_b32_e32 v81, v80
	v_cvt_pk_bf16_f32 v82, v84, v85
	v_cvt_pk_bf16_f32 v83, v86, v87
	v_cvt_pk_bf16_f32 v84, v100, v101
	v_cvt_pk_bf16_f32 v85, v98, v99
	global_store_dwordx4 v[106:107], v[82:85], off offset:256
	s_and_saveexec_b64 s[54:55], s[8:9]
	s_cbranch_execz .LBB0_882
	s_waitcnt lgkmcnt(0)
	v_add_f32_e32 v80, v80, v81
	v_mul_f32_e32 v80, 0x4f800000, v80
	v_trunc_f32_e32 v80, v80
	v_mul_f32_e64 v81, |v80|, s82
	v_floor_f32_e32 v81, v81
	v_fma_f32 v82, v81, s83, |v80|
	v_cvt_u32_f32_e32 v80, v82
	v_cvt_u32_f32_e32 v81, v81
	v_lshl_add_u64 v[82:83], v[96:97], 3, s[0:1]
	global_atomic_add_x2 v[82:83], v[80:81], off
.LBB0_882:
	s_or_b64 exec, exec, s[54:55]
	v_or_b32_e32 v80, 48, v146
	s_waitcnt lgkmcnt(0)
	v_ashrrev_i32_e32 v81, 31, v80
	v_lshlrev_b64 v[82:83], 11, v[80:81]
	v_lshl_add_u64 v[82:83], s[22:23], 0, v[82:83]
	v_lshl_add_u64 v[90:91], v[144:145], 1, v[82:83]
	global_load_dwordx4 v[82:85], v[90:91], off
	global_load_dwordx4 v[86:89], v[90:91], off offset:256
	s_waitcnt vmcnt(1)
	v_lshlrev_b32_e32 v92, 16, v82
	v_and_b32_e32 v93, 0xffff0000, v82
	v_lshlrev_b32_e32 v82, 16, v83
	v_and_b32_e32 v83, 0xffff0000, v83
	s_waitcnt vmcnt(0)
	v_lshlrev_b32_e32 v96, 16, v86
	v_and_b32_e32 v97, 0xffff0000, v86
	v_lshlrev_b32_e32 v86, 16, v87
	v_and_b32_e32 v87, 0xffff0000, v87
	v_lshlrev_b32_e32 v94, 16, v84
	v_and_b32_e32 v95, 0xffff0000, v84
	v_lshlrev_b32_e32 v84, 16, v85
	v_and_b32_e32 v85, 0xffff0000, v85
	v_lshlrev_b32_e32 v98, 16, v88
	v_and_b32_e32 v99, 0xffff0000, v88
	v_lshlrev_b32_e32 v88, 16, v89
	v_and_b32_e32 v89, 0xffff0000, v89
	v_pk_add_f32 v[78:79], v[78:79], v[82:83]
	v_pk_add_f32 v[76:77], v[76:77], v[92:93]
	v_pk_add_f32 v[70:71], v[70:71], v[86:87]
	v_pk_add_f32 v[68:69], v[68:69], v[96:97]
	v_pk_add_f32 v[74:75], v[74:75], v[84:85]
	v_pk_add_f32 v[72:73], v[72:73], v[94:95]
	v_pk_add_f32 v[82:83], v[66:67], v[88:89]
	v_pk_add_f32 v[84:85], v[64:65], v[98:99]
	v_mul_f32_e32 v66, v77, v77
	v_mul_f32_e32 v67, v79, v79
	v_mul_f32_e32 v86, v69, v69
	v_mul_f32_e32 v87, v71, v71
	v_cvt_pk_bf16_f32 v64, v76, v77
	v_mul_f32_e32 v77, v73, v73
	v_mul_f32_e32 v88, v85, v85
	v_fmac_f32_e32 v66, v76, v76
	v_fmac_f32_e32 v67, v78, v78
	v_fmac_f32_e32 v86, v68, v68
	v_fmac_f32_e32 v87, v70, v70
	v_cvt_pk_bf16_f32 v65, v78, v79
	v_mul_f32_e32 v79, v75, v75
	v_mul_f32_e32 v89, v83, v83
	v_fmac_f32_e32 v77, v72, v72
	v_fmac_f32_e32 v88, v84, v84
	v_add_f32_e32 v66, v66, v67
	v_add_f32_e32 v67, v86, v87
	v_fmac_f32_e32 v79, v74, v74
	v_fmac_f32_e32 v89, v82, v82
	v_add_f32_e32 v66, v77, v66
	v_add_f32_e32 v67, v88, v67
	v_add_f32_e32 v66, v79, v66
	v_add_f32_e32 v67, v89, v67
	v_add_f32_e32 v76, v66, v67
	v_mov_b32_e32 v77, v76
	s_nop 1
	v_permlane16_swap_b32_e32 v77, v76
	v_cvt_pk_bf16_f32 v66, v72, v73
	v_cvt_pk_bf16_f32 v67, v74, v75
	global_store_dwordx4 v[90:91], v[64:67], off
	s_waitcnt lgkmcnt(0)
	s_nop 0
	v_add_f32_e32 v64, v76, v77
	v_mov_b32_e32 v65, v64
	s_nop 1
	v_permlane32_swap_b32_e32 v65, v64
	v_cvt_pk_bf16_f32 v66, v68, v69
	v_cvt_pk_bf16_f32 v67, v70, v71
	v_cvt_pk_bf16_f32 v68, v84, v85
	v_cvt_pk_bf16_f32 v69, v82, v83
	global_store_dwordx4 v[90:91], v[66:69], off offset:256
	s_and_saveexec_b64 s[54:55], s[8:9]
	s_cbranch_execz .LBB0_884
	s_waitcnt lgkmcnt(0)
	v_add_f32_e32 v64, v64, v65
	v_mul_f32_e32 v64, 0x4f800000, v64
	v_trunc_f32_e32 v64, v64
	v_mul_f32_e64 v65, |v64|, s82
	v_floor_f32_e32 v65, v65
	v_fma_f32 v66, v65, s83, |v64|
	v_cvt_u32_f32_e32 v64, v66
	v_cvt_u32_f32_e32 v65, v65
	v_lshl_add_u64 v[66:67], v[80:81], 3, s[0:1]
	global_atomic_add_x2 v[66:67], v[64:65], off
; __device__ __forceinline__ unsigned cvtpk(float lo, float hi) { f32x2v_ v = {lo, hi}; bf16x2v_ b = __builtin_convertvector(v, bf16x2v_); return __builtin_bit_cast(unsigned, b); }
; __device__ __forceinline__ void fx_add(float* p, size_t idx, float s) { atomicAdd((unsigned long long*)p + idx, (unsigned long long)(long long)(s * 4294967296.0f)); }
;     __device__ __forceinline__ void operator()(const f32x4 (&acc)[2][2][4][2], const Unit& u, int wr, int wc, int fr, int fq) const {
;     ...
;             for (int m = 0; m < 4; ++m) { const int row = row0 + ai * HALF + m * 16; const size_t off = (size_t)row * 1024 + col0; float s = 0.f;
; #pragma unroll
;                 for (int bj = 0; bj < 2; ++bj) { f32x4 a0, a1;
;                     if (xin32) { const float* p = xin32 + off + bj * HALF; a0 = *(const f32x4*)p; a1 = *(const f32x4*)(p + 4); }
;                     else { const u32x4 w = *(const u32x4*)(xb + off + bj * HALF);
;                         a0 = (f32x4){__uint_as_float(w.x << 16), __uint_as_float(w.x & 0xffff0000u), __uint_as_float(w.y << 16), __uint_as_float(w.y & 0xffff0000u)};
;                         a1 = (f32x4){__uint_as_float(w.z << 16), __uint_as_float(w.z & 0xffff0000u), __uint_as_float(w.w << 16), __uint_as_float(w.w & 0xffff0000u)}; }
;                     const f32x4 v0 = a0 + acc[ai][bj][m][0] * alpha, v1 = a1 + acc[ai][bj][m][1] * alpha;
;                     u32x4 w; w.x = cvtpk(v0[0], v0[1]); w.y = cvtpk(v0[2], v0[3]); w.z = cvtpk(v1[0], v1[1]); w.w = cvtpk(v1[2], v1[3]);
;                     *(u32x4*)(xb + off + bj * HALF) = w;
;                     s += (v0[0] * v0[0] + v0[1] * v0[1]) + (v0[2] * v0[2] + v0[3] * v0[3]) + (v1[0] * v1[0] + v1[1] * v1[1]) + (v1[2] * v1[2] + v1[3] * v1[3]); }
;                 s += __shfl_xor(s, 16); s += __shfl_xor(s, 32);
;                 if (fq == 0) fx_add(ssout, row, s); }
.LBB0_884:
	s_or_b64 exec, exec, s[54:55]
	v_add_u32_e32 v64, 0x80, v146
	s_waitcnt lgkmcnt(0)
	v_ashrrev_i32_e32 v65, 31, v64
	v_lshlrev_b64 v[66:67], 11, v[64:65]
	v_lshl_add_u64 v[66:67], s[22:23], 0, v[66:67]
	v_lshl_add_u64 v[74:75], v[144:145], 1, v[66:67]
	global_load_dwordx4 v[66:69], v[74:75], off
	global_load_dwordx4 v[70:73], v[74:75], off offset:256
	s_waitcnt vmcnt(1)
	v_lshlrev_b32_e32 v76, 16, v66
	v_and_b32_e32 v77, 0xffff0000, v66
	v_lshlrev_b32_e32 v66, 16, v67
	v_and_b32_e32 v67, 0xffff0000, v67
	s_waitcnt vmcnt(0)
	v_lshlrev_b32_e32 v80, 16, v70
	v_and_b32_e32 v81, 0xffff0000, v70
	v_lshlrev_b32_e32 v70, 16, v71
	v_and_b32_e32 v71, 0xffff0000, v71
	v_lshlrev_b32_e32 v78, 16, v68
	v_and_b32_e32 v79, 0xffff0000, v68
	v_lshlrev_b32_e32 v68, 16, v69
	v_and_b32_e32 v69, 0xffff0000, v69
	v_lshlrev_b32_e32 v82, 16, v72
	v_and_b32_e32 v83, 0xffff0000, v72
	v_lshlrev_b32_e32 v72, 16, v73
	v_and_b32_e32 v73, 0xffff0000, v73
	v_pk_add_f32 v[62:63], v[62:63], v[66:67]
	v_pk_add_f32 v[60:61], v[60:61], v[76:77]
	v_pk_add_f32 v[54:55], v[54:55], v[70:71]
	v_pk_add_f32 v[52:53], v[52:53], v[80:81]
	v_pk_add_f32 v[58:59], v[58:59], v[68:69]
	v_pk_add_f32 v[56:57], v[56:57], v[78:79]
	v_pk_add_f32 v[66:67], v[50:51], v[72:73]
	v_pk_add_f32 v[68:69], v[48:49], v[82:83]
	v_mul_f32_e32 v50, v61, v61
	v_mul_f32_e32 v51, v63, v63
	v_mul_f32_e32 v70, v53, v53
	v_mul_f32_e32 v71, v55, v55
	v_cvt_pk_bf16_f32 v48, v60, v61
	v_mul_f32_e32 v61, v57, v57
	v_mul_f32_e32 v72, v69, v69
	v_fmac_f32_e32 v50, v60, v60
	v_fmac_f32_e32 v51, v62, v62
	v_fmac_f32_e32 v70, v52, v52
	v_fmac_f32_e32 v71, v54, v54
	v_cvt_pk_bf16_f32 v49, v62, v63
	v_mul_f32_e32 v63, v59, v59
	v_mul_f32_e32 v73, v67, v67
	v_fmac_f32_e32 v61, v56, v56
	v_fmac_f32_e32 v72, v68, v68
	v_add_f32_e32 v50, v50, v51
	v_add_f32_e32 v51, v70, v71
	v_fmac_f32_e32 v63, v58, v58
	v_fmac_f32_e32 v73, v66, v66
	v_add_f32_e32 v50, v61, v50
	v_add_f32_e32 v51, v72, v51
	v_add_f32_e32 v50, v63, v50
	v_add_f32_e32 v51, v73, v51
	v_add_f32_e32 v60, v50, v51
	v_mov_b32_e32 v61, v60
	s_nop 1
	v_permlane16_swap_b32_e32 v61, v60
	v_cvt_pk_bf16_f32 v50, v56, v57
	v_cvt_pk_bf16_f32 v51, v58, v59
	global_store_dwordx4 v[74:75], v[48:51], off
	s_waitcnt lgkmcnt(0)
	s_nop 0
	v_add_f32_e32 v48, v60, v61
	v_mov_b32_e32 v49, v48
	s_nop 1
	v_permlane32_swap_b32_e32 v49, v48
	v_cvt_pk_bf16_f32 v50, v52, v53
	v_cvt_pk_bf16_f32 v51, v54, v55
	v_cvt_pk_bf16_f32 v52, v68, v69
	v_cvt_pk_bf16_f32 v53, v66, v67
	global_store_dwordx4 v[74:75], v[50:53], off offset:256
	s_and_saveexec_b64 s[54:55], s[8:9]
	s_cbranch_execz .LBB0_886
	s_waitcnt lgkmcnt(0)
	v_add_f32_e32 v48, v48, v49
	v_mul_f32_e32 v48, 0x4f800000, v48
	v_trunc_f32_e32 v48, v48
	v_mul_f32_e64 v49, |v48|, s82
	v_floor_f32_e32 v49, v49
	v_fma_f32 v50, v49, s83, |v48|
	v_cvt_u32_f32_e32 v48, v50
	v_cvt_u32_f32_e32 v49, v49
	v_lshl_add_u64 v[50:51], v[64:65], 3, s[0:1]
	global_atomic_add_x2 v[50:51], v[48:49], off
.LBB0_886:
	s_or_b64 exec, exec, s[54:55]
	v_add_u32_e32 v48, 0x90, v146
	s_waitcnt lgkmcnt(0)
	v_ashrrev_i32_e32 v49, 31, v48
	v_lshlrev_b64 v[50:51], 11, v[48:49]
	v_lshl_add_u64 v[50:51], s[22:23], 0, v[50:51]
	v_lshl_add_u64 v[58:59], v[144:145], 1, v[50:51]
	global_load_dwordx4 v[50:53], v[58:59], off
	global_load_dwordx4 v[54:57], v[58:59], off offset:256
	s_waitcnt vmcnt(1)
	v_lshlrev_b32_e32 v60, 16, v50
	v_and_b32_e32 v61, 0xffff0000, v50
	v_lshlrev_b32_e32 v50, 16, v51
	v_and_b32_e32 v51, 0xffff0000, v51
	s_waitcnt vmcnt(0)
	v_lshlrev_b32_e32 v64, 16, v54
	v_and_b32_e32 v65, 0xffff0000, v54
	v_lshlrev_b32_e32 v54, 16, v55
	v_and_b32_e32 v55, 0xffff0000, v55
	v_lshlrev_b32_e32 v62, 16, v52
	v_and_b32_e32 v63, 0xffff0000, v52
	v_lshlrev_b32_e32 v52, 16, v53
	v_and_b32_e32 v53, 0xffff0000, v53
	v_lshlrev_b32_e32 v66, 16, v56
	v_and_b32_e32 v67, 0xffff0000, v56
	v_lshlrev_b32_e32 v56, 16, v57
	v_and_b32_e32 v57, 0xffff0000, v57
	v_pk_add_f32 v[46:47], v[46:47], v[50:51]
	v_pk_add_f32 v[44:45], v[44:45], v[60:61]
	v_pk_add_f32 v[38:39], v[38:39], v[54:55]
	v_pk_add_f32 v[36:37], v[36:37], v[64:65]
	v_pk_add_f32 v[42:43], v[42:43], v[52:53]
	v_pk_add_f32 v[40:41], v[40:41], v[62:63]
	v_pk_add_f32 v[50:51], v[34:35], v[56:57]
	v_pk_add_f32 v[52:53], v[32:33], v[66:67]
	v_mul_f32_e32 v34, v45, v45
	v_mul_f32_e32 v35, v47, v47
	v_mul_f32_e32 v54, v37, v37
	v_mul_f32_e32 v55, v39, v39
	v_cvt_pk_bf16_f32 v32, v44, v45
	v_mul_f32_e32 v45, v41, v41
	v_mul_f32_e32 v56, v53, v53
	v_fmac_f32_e32 v34, v44, v44
	v_fmac_f32_e32 v35, v46, v46
	v_fmac_f32_e32 v54, v36, v36
	v_fmac_f32_e32 v55, v38, v38
	v_cvt_pk_bf16_f32 v33, v46, v47
	v_mul_f32_e32 v47, v43, v43
	v_mul_f32_e32 v57, v51, v51
	v_fmac_f32_e32 v45, v40, v40
	v_fmac_f32_e32 v56, v52, v52
	v_add_f32_e32 v34, v34, v35
	v_add_f32_e32 v35, v54, v55
	v_fmac_f32_e32 v47, v42, v42
	v_fmac_f32_e32 v57, v50, v50
	v_add_f32_e32 v34, v45, v34
	v_add_f32_e32 v35, v56, v35
	v_add_f32_e32 v34, v47, v34
	v_add_f32_e32 v35, v57, v35
	v_add_f32_e32 v44, v34, v35
	v_mov_b32_e32 v45, v44
	s_nop 1
	v_permlane16_swap_b32_e32 v45, v44
	v_cvt_pk_bf16_f32 v34, v40, v41
	v_cvt_pk_bf16_f32 v35, v42, v43
	global_store_dwordx4 v[58:59], v[32:35], off
	s_waitcnt lgkmcnt(0)
	s_nop 0
	v_add_f32_e32 v32, v44, v45
	v_mov_b32_e32 v33, v32
	s_nop 1
	v_permlane32_swap_b32_e32 v33, v32
	v_cvt_pk_bf16_f32 v34, v36, v37
	v_cvt_pk_bf16_f32 v35, v38, v39
	v_cvt_pk_bf16_f32 v36, v52, v53
	v_cvt_pk_bf16_f32 v37, v50, v51
	global_store_dwordx4 v[58:59], v[34:37], off offset:256
	s_and_saveexec_b64 s[54:55], s[8:9]
	s_cbranch_execz .LBB0_888
	s_waitcnt lgkmcnt(0)
	v_add_f32_e32 v32, v32, v33
	v_mul_f32_e32 v32, 0x4f800000, v32
	v_trunc_f32_e32 v32, v32
	v_mul_f32_e64 v33, |v32|, s82
	v_floor_f32_e32 v33, v33
	v_fma_f32 v34, v33, s83, |v32|
	v_cvt_u32_f32_e32 v32, v34
	v_cvt_u32_f32_e32 v33, v33
	v_lshl_add_u64 v[34:35], v[48:49], 3, s[0:1]
	global_atomic_add_x2 v[34:35], v[32:33], off
; __device__ __forceinline__ unsigned cvtpk(float lo, float hi) { f32x2v_ v = {lo, hi}; bf16x2v_ b = __builtin_convertvector(v, bf16x2v_); return __builtin_bit_cast(unsigned, b); }
; __device__ __forceinline__ void fx_add(float* p, size_t idx, float s) { atomicAdd((unsigned long long*)p + idx, (unsigned long long)(long long)(s * 4294967296.0f)); }
;     __device__ __forceinline__ void operator()(const f32x4 (&acc)[2][2][4][2], const Unit& u, int wr, int wc, int fr, int fq) const {
;     ...
;             for (int m = 0; m < 4; ++m) { const int row = row0 + ai * HALF + m * 16; const size_t off = (size_t)row * 1024 + col0; float s = 0.f;
; #pragma unroll
;                 for (int bj = 0; bj < 2; ++bj) { f32x4 a0, a1;
;                     if (xin32) { const float* p = xin32 + off + bj * HALF; a0 = *(const f32x4*)p; a1 = *(const f32x4*)(p + 4); }
;                     else { const u32x4 w = *(const u32x4*)(xb + off + bj * HALF);
;                         a0 = (f32x4){__uint_as_float(w.x << 16), __uint_as_float(w.x & 0xffff0000u), __uint_as_float(w.y << 16), __uint_as_float(w.y & 0xffff0000u)};
;                         a1 = (f32x4){__uint_as_float(w.z << 16), __uint_as_float(w.z & 0xffff0000u), __uint_as_float(w.w << 16), __uint_as_float(w.w & 0xffff0000u)}; }
;                     const f32x4 v0 = a0 + acc[ai][bj][m][0] * alpha, v1 = a1 + acc[ai][bj][m][1] * alpha;
;                     u32x4 w; w.x = cvtpk(v0[0], v0[1]); w.y = cvtpk(v0[2], v0[3]); w.z = cvtpk(v1[0], v1[1]); w.w = cvtpk(v1[2], v1[3]);
;                     *(u32x4*)(xb + off + bj * HALF) = w;
;                     s += (v0[0] * v0[0] + v0[1] * v0[1]) + (v0[2] * v0[2] + v0[3] * v0[3]) + (v1[0] * v1[0] + v1[1] * v1[1]) + (v1[2] * v1[2] + v1[3] * v1[3]); }
;                 s += __shfl_xor(s, 16); s += __shfl_xor(s, 32);
;                 if (fq == 0) fx_add(ssout, row, s); }
.LBB0_888:
	s_or_b64 exec, exec, s[54:55]
	v_add_u32_e32 v32, 0xa0, v146
	s_waitcnt lgkmcnt(0)
	v_ashrrev_i32_e32 v33, 31, v32
	v_lshlrev_b64 v[34:35], 11, v[32:33]
	v_lshl_add_u64 v[34:35], s[22:23], 0, v[34:35]
	v_lshl_add_u64 v[42:43], v[144:145], 1, v[34:35]
	global_load_dwordx4 v[34:37], v[42:43], off
	global_load_dwordx4 v[38:41], v[42:43], off offset:256
	s_waitcnt vmcnt(1)
	v_lshlrev_b32_e32 v44, 16, v34
	v_and_b32_e32 v45, 0xffff0000, v34
	v_lshlrev_b32_e32 v34, 16, v35
	v_and_b32_e32 v35, 0xffff0000, v35
	s_waitcnt vmcnt(0)
	v_lshlrev_b32_e32 v48, 16, v38
	v_and_b32_e32 v49, 0xffff0000, v38
	v_lshlrev_b32_e32 v38, 16, v39
	v_and_b32_e32 v39, 0xffff0000, v39
	v_lshlrev_b32_e32 v46, 16, v36
	v_and_b32_e32 v47, 0xffff0000, v36
	v_lshlrev_b32_e32 v36, 16, v37
	v_and_b32_e32 v37, 0xffff0000, v37
	v_lshlrev_b32_e32 v50, 16, v40
	v_and_b32_e32 v51, 0xffff0000, v40
	v_lshlrev_b32_e32 v40, 16, v41
	v_and_b32_e32 v41, 0xffff0000, v41
	v_pk_add_f32 v[30:31], v[30:31], v[34:35]
	v_pk_add_f32 v[28:29], v[28:29], v[44:45]
	v_pk_add_f32 v[22:23], v[22:23], v[38:39]
	v_pk_add_f32 v[20:21], v[20:21], v[48:49]
	v_pk_add_f32 v[26:27], v[26:27], v[36:37]
	v_pk_add_f32 v[24:25], v[24:25], v[46:47]
	v_pk_add_f32 v[34:35], v[18:19], v[40:41]
	v_pk_add_f32 v[36:37], v[16:17], v[50:51]
	v_mul_f32_e32 v18, v29, v29
	v_mul_f32_e32 v19, v31, v31
	v_mul_f32_e32 v38, v21, v21
	v_mul_f32_e32 v39, v23, v23
	v_cvt_pk_bf16_f32 v16, v28, v29
	v_mul_f32_e32 v29, v25, v25
	v_mul_f32_e32 v40, v37, v37
	v_fmac_f32_e32 v18, v28, v28
	v_fmac_f32_e32 v19, v30, v30
	v_fmac_f32_e32 v38, v20, v20
	v_fmac_f32_e32 v39, v22, v22
	v_cvt_pk_bf16_f32 v17, v30, v31
	v_mul_f32_e32 v31, v27, v27
	v_mul_f32_e32 v41, v35, v35
	v_fmac_f32_e32 v29, v24, v24
	v_fmac_f32_e32 v40, v36, v36
	v_add_f32_e32 v18, v18, v19
	v_add_f32_e32 v19, v38, v39
	v_fmac_f32_e32 v31, v26, v26
	v_fmac_f32_e32 v41, v34, v34
	v_add_f32_e32 v18, v29, v18
	v_add_f32_e32 v19, v40, v19
	v_add_f32_e32 v18, v31, v18
	v_add_f32_e32 v19, v41, v19
	v_add_f32_e32 v28, v18, v19
	v_mov_b32_e32 v29, v28
	s_nop 1
	v_permlane16_swap_b32_e32 v29, v28
	v_cvt_pk_bf16_f32 v18, v24, v25
	v_cvt_pk_bf16_f32 v19, v26, v27
	global_store_dwordx4 v[42:43], v[16:19], off
	s_waitcnt lgkmcnt(0)
	s_nop 0
	v_add_f32_e32 v16, v28, v29
	v_mov_b32_e32 v17, v16
	s_nop 1
	v_permlane32_swap_b32_e32 v17, v16
	v_cvt_pk_bf16_f32 v18, v20, v21
	v_cvt_pk_bf16_f32 v19, v22, v23
	v_cvt_pk_bf16_f32 v20, v36, v37
	v_cvt_pk_bf16_f32 v21, v34, v35
	global_store_dwordx4 v[42:43], v[18:21], off offset:256
	s_and_saveexec_b64 s[54:55], s[8:9]
	s_cbranch_execz .LBB0_890
	s_waitcnt lgkmcnt(0)
	v_add_f32_e32 v16, v16, v17
	v_mul_f32_e32 v16, 0x4f800000, v16
	v_trunc_f32_e32 v16, v16
	v_mul_f32_e64 v17, |v16|, s82
	v_floor_f32_e32 v17, v17
	v_fma_f32 v18, v17, s83, |v16|
	v_cvt_u32_f32_e32 v16, v18
	v_cvt_u32_f32_e32 v17, v17
	v_lshl_add_u64 v[18:19], v[32:33], 3, s[0:1]
	global_atomic_add_x2 v[18:19], v[16:17], off
.LBB0_890:
	s_or_b64 exec, exec, s[54:55]
	v_add_u32_e32 v16, 0xb0, v146
	s_waitcnt lgkmcnt(0)
	v_ashrrev_i32_e32 v17, 31, v16
	v_lshlrev_b64 v[18:19], 11, v[16:17]
	v_lshl_add_u64 v[18:19], s[22:23], 0, v[18:19]
	v_lshl_add_u64 v[26:27], v[144:145], 1, v[18:19]
	global_load_dwordx4 v[18:21], v[26:27], off
	global_load_dwordx4 v[22:25], v[26:27], off offset:256
	s_waitcnt vmcnt(1)
	v_lshlrev_b32_e32 v28, 16, v18
	v_and_b32_e32 v29, 0xffff0000, v18
	v_lshlrev_b32_e32 v18, 16, v19
	v_and_b32_e32 v19, 0xffff0000, v19
	s_waitcnt vmcnt(0)
	v_lshlrev_b32_e32 v32, 16, v22
	v_and_b32_e32 v33, 0xffff0000, v22
	v_lshlrev_b32_e32 v22, 16, v23
	v_and_b32_e32 v23, 0xffff0000, v23
	v_lshlrev_b32_e32 v30, 16, v20
	v_and_b32_e32 v31, 0xffff0000, v20
	v_lshlrev_b32_e32 v20, 16, v21
	v_and_b32_e32 v21, 0xffff0000, v21
	v_lshlrev_b32_e32 v34, 16, v24
	v_and_b32_e32 v35, 0xffff0000, v24
	v_lshlrev_b32_e32 v24, 16, v25
	v_and_b32_e32 v25, 0xffff0000, v25
	v_pk_add_f32 v[14:15], v[14:15], v[18:19]
	v_pk_add_f32 v[12:13], v[12:13], v[28:29]
	v_pk_add_f32 v[6:7], v[6:7], v[22:23]
	v_pk_add_f32 v[4:5], v[4:5], v[32:33]
	v_pk_add_f32 v[10:11], v[10:11], v[20:21]
	v_pk_add_f32 v[8:9], v[8:9], v[30:31]
	v_pk_add_f32 v[18:19], v[2:3], v[24:25]
	v_pk_add_f32 v[20:21], v[0:1], v[34:35]
	v_mul_f32_e32 v2, v13, v13
	v_mul_f32_e32 v3, v15, v15
	v_mul_f32_e32 v22, v5, v5
	v_mul_f32_e32 v23, v7, v7
	v_cvt_pk_bf16_f32 v0, v12, v13
	v_mul_f32_e32 v13, v9, v9
	v_mul_f32_e32 v24, v21, v21
	v_fmac_f32_e32 v2, v12, v12
	v_fmac_f32_e32 v3, v14, v14
	v_fmac_f32_e32 v22, v4, v4
	v_fmac_f32_e32 v23, v6, v6
	v_cvt_pk_bf16_f32 v1, v14, v15
	v_mul_f32_e32 v15, v11, v11
	v_mul_f32_e32 v25, v19, v19
	v_fmac_f32_e32 v13, v8, v8
	v_fmac_f32_e32 v24, v20, v20
	v_add_f32_e32 v2, v2, v3
	v_add_f32_e32 v3, v22, v23
	v_fmac_f32_e32 v15, v10, v10
	v_fmac_f32_e32 v25, v18, v18
	v_add_f32_e32 v2, v13, v2
	v_add_f32_e32 v3, v24, v3
	v_add_f32_e32 v2, v15, v2
	v_add_f32_e32 v3, v25, v3
	v_add_f32_e32 v12, v2, v3
	v_mov_b32_e32 v13, v12
	s_nop 1
	v_permlane16_swap_b32_e32 v13, v12
	v_cvt_pk_bf16_f32 v2, v8, v9
	v_cvt_pk_bf16_f32 v3, v10, v11
	global_store_dwordx4 v[26:27], v[0:3], off
	s_waitcnt lgkmcnt(0)
	s_nop 0
	v_add_f32_e32 v0, v12, v13
	v_mov_b32_e32 v1, v0
	s_nop 1
	v_permlane32_swap_b32_e32 v1, v0
	v_cvt_pk_bf16_f32 v2, v4, v5
	v_cvt_pk_bf16_f32 v3, v6, v7
	v_cvt_pk_bf16_f32 v4, v20, v21
	v_cvt_pk_bf16_f32 v5, v18, v19
	global_store_dwordx4 v[26:27], v[2:5], off offset:256
	s_and_saveexec_b64 s[54:55], s[8:9]
	s_cbranch_execz .LBB0_892
	s_waitcnt lgkmcnt(0)
	v_add_f32_e32 v0, v0, v1
	v_mul_f32_e32 v0, 0x4f800000, v0
	v_trunc_f32_e32 v0, v0
	v_mul_f32_e64 v1, |v0|, s82
	v_floor_f32_e32 v1, v1
	v_fma_f32 v2, v1, s83, |v0|
	v_cvt_u32_f32_e32 v0, v2
	v_cvt_u32_f32_e32 v1, v1
	v_lshl_add_u64 v[2:3], v[16:17], 3, s[0:1]
	global_atomic_add_x2 v[2:3], v[0:1], off

; __device__ __forceinline__ unsigned cvtpk(float lo, float hi) { f32x2v_ v = {lo, hi}; bf16x2v_ b = __builtin_convertvector(v, bf16x2v_); return __builtin_bit_cast(unsigned, b); }
; __device__ __forceinline__ void fx_add(float* p, size_t idx, float s) { atomicAdd((unsigned long long*)p + idx, (unsigned long long)(long long)(s * 4294967296.0f)); }
;     __device__ __forceinline__ void operator()(const f32x4 (&acc)[2][2][4][2], const Unit& u, int wr, int wc, int fr, int fq) const {
;         const int row0 = u.pm * BM + wr * 64 + fr, col0 = u.pn * BM + wc * 32 + 8 * fq;
; #pragma unroll
;         for (int ai = 0; ai < 2; ++ai)
; #pragma unroll
;             for (int m = 0; m < 4; ++m) { const int row = row0 + ai * HALF + m * 16; const size_t off = (size_t)row * 1024 + col0; float s = 0.f;
; #pragma unroll
;                 for (int bj = 0; bj < 2; ++bj) { f32x4 a0, a1;
;                     if (xin32) { const float* p = xin32 + off + bj * HALF; a0 = *(const f32x4*)p; a1 = *(const f32x4*)(p + 4); }
;                     else { const u32x4 w = *(const u32x4*)(xb + off + bj * HALF);
;                         a0 = (f32x4){__uint_as_float(w.x << 16), __uint_as_float(w.x & 0xffff0000u), __uint_as_float(w.y << 16), __uint_as_float(w.y & 0xffff0000u)};
;                         a1 = (f32x4){__uint_as_float(w.z << 16), __uint_as_float(w.z & 0xffff0000u), __uint_as_float(w.w << 16), __uint_as_float(w.w & 0xffff0000u)}; }
;                     const f32x4 v0 = a0 + acc[ai][bj][m][0] * alpha, v1 = a1 + acc[ai][bj][m][1] * alpha;
;                     u32x4 w; w.x = cvtpk(v0[0], v0[1]); w.y = cvtpk(v0[2], v0[3]); w.z = cvtpk(v1[0], v1[1]); w.w = cvtpk(v1[2], v1[3]);
;                     *(u32x4*)(xb + off + bj * HALF) = w;
;                     s += (v0[0] * v0[0] + v0[1] * v0[1]) + (v0[2] * v0[2] + v0[3] * v0[3]) + (v1[0] * v1[0] + v1[1] * v1[1]) + (v1[2] * v1[2] + v1[3] * v1[3]); }
;                 s += __shfl_xor(s, 16); s += __shfl_xor(s, 32);
;                 if (fq == 0) fx_add(ssout, row, s); }
.LBB0_1038:
	v_lshl_add_u32 v146, s74, 8, v148
	v_ashrrev_i32_e32 v147, 31, v146
	v_lshl_or_b32 v144, s67, 8, v150
	v_lshlrev_b64 v[156:157], 11, v[146:147]
	v_ashrrev_i32_e32 v145, 31, v144
	v_lshl_add_u64 v[156:157], s[22:23], 0, v[156:157]
	v_lshl_add_u64 v[166:167], v[144:145], 1, v[156:157]
	global_load_dwordx4 v[158:161], v[166:167], off
	global_load_dwordx4 v[162:165], v[166:167], off offset:256
	v_and_b32_e32 v156, 64, v154
	v_xor_b32_e32 v155, 16, v154
	v_add_u32_e32 v156, 64, v156
	v_xor_b32_e32 v157, 32, v154
	v_cmp_lt_i32_e32 vcc, v155, v156
	s_waitcnt vmcnt(0)
	v_lshlrev_b32_e32 v168, 16, v158
	v_cndmask_b32_e32 v155, v154, v155, vcc
	v_cmp_lt_i32_e32 vcc, v157, v156
	v_and_b32_e32 v169, 0xffff0000, v158
	v_lshlrev_b32_e32 v158, 16, v159
	v_and_b32_e32 v159, 0xffff0000, v159
	v_lshlrev_b32_e32 v172, 16, v162
	v_and_b32_e32 v173, 0xffff0000, v162
	v_lshlrev_b32_e32 v162, 16, v163
	v_and_b32_e32 v163, 0xffff0000, v163
	v_cndmask_b32_e32 v157, v154, v157, vcc
	v_lshlrev_b32_e32 v170, 16, v160
	v_and_b32_e32 v171, 0xffff0000, v160
	v_lshlrev_b32_e32 v160, 16, v161
	v_and_b32_e32 v161, 0xffff0000, v161
	v_lshlrev_b32_e32 v174, 16, v164
	v_and_b32_e32 v175, 0xffff0000, v164
	v_lshlrev_b32_e32 v164, 16, v165
	v_and_b32_e32 v165, 0xffff0000, v165
	v_pk_fma_f32 v[126:127], v[126:127], 0.5, v[158:159] op_sel_hi:[1,0,1]
	v_pk_fma_f32 v[124:125], v[124:125], 0.5, v[168:169] op_sel_hi:[1,0,1]
	v_pk_fma_f32 v[118:119], v[118:119], 0.5, v[162:163] op_sel_hi:[1,0,1]
	v_pk_fma_f32 v[116:117], v[116:117], 0.5, v[172:173] op_sel_hi:[1,0,1]
	v_lshlrev_b32_e32 v156, 2, v155
	v_lshlrev_b32_e32 v155, 2, v157
	v_pk_fma_f32 v[122:123], v[122:123], 0.5, v[160:161] op_sel_hi:[1,0,1]
	v_pk_fma_f32 v[120:121], v[120:121], 0.5, v[170:171] op_sel_hi:[1,0,1]
	v_pk_fma_f32 v[158:159], v[114:115], 0.5, v[164:165] op_sel_hi:[1,0,1]
	v_pk_fma_f32 v[160:161], v[112:113], 0.5, v[174:175] op_sel_hi:[1,0,1]
	v_mul_f32_e32 v114, v125, v125
	v_mul_f32_e32 v115, v127, v127
	v_mul_f32_e32 v157, v117, v117
	v_mul_f32_e32 v162, v119, v119
	v_cvt_pk_bf16_f32 v112, v124, v125
	v_mul_f32_e32 v125, v121, v121
	v_mul_f32_e32 v163, v161, v161
	v_fmac_f32_e32 v114, v124, v124
	v_fmac_f32_e32 v115, v126, v126
	v_fmac_f32_e32 v157, v116, v116
	v_fmac_f32_e32 v162, v118, v118
	v_cvt_pk_bf16_f32 v113, v126, v127
	v_mul_f32_e32 v127, v123, v123
	v_mul_f32_e32 v164, v159, v159
	v_fmac_f32_e32 v125, v120, v120
	v_fmac_f32_e32 v163, v160, v160
	v_add_f32_e32 v114, v114, v115
	v_add_f32_e32 v115, v157, v162
	v_fmac_f32_e32 v127, v122, v122
	v_fmac_f32_e32 v164, v158, v158
	v_add_f32_e32 v114, v125, v114
	v_add_f32_e32 v115, v163, v115
	v_add_f32_e32 v114, v127, v114
	v_add_f32_e32 v115, v164, v115
	v_add_f32_e32 v124, v114, v115
	v_mov_b32_e32 v125, v124
	s_nop 1
	v_permlane16_swap_b32_e32 v125, v124
	v_cvt_pk_bf16_f32 v114, v120, v121
	v_cvt_pk_bf16_f32 v115, v122, v123
	global_store_dwordx4 v[166:167], v[112:115], off
	s_waitcnt lgkmcnt(0)
	s_nop 0
	v_add_f32_e32 v112, v124, v125
	v_mov_b32_e32 v113, v112
	s_nop 1
	v_permlane32_swap_b32_e32 v113, v112
	v_cvt_pk_bf16_f32 v114, v116, v117
	v_cvt_pk_bf16_f32 v115, v118, v119
	v_cvt_pk_bf16_f32 v116, v160, v161
	v_cvt_pk_bf16_f32 v117, v158, v159
	global_store_dwordx4 v[166:167], v[114:117], off offset:256
	s_and_saveexec_b64 s[50:51], s[10:11]
	s_cbranch_execz .LBB0_1040
	s_waitcnt lgkmcnt(0)
	v_add_f32_e32 v112, v112, v113
	v_mul_f32_e32 v112, 0x4f800000, v112
	v_trunc_f32_e32 v112, v112
	v_mul_f32_e64 v113, |v112|, s63
	v_floor_f32_e32 v113, v113
	v_fma_f32 v114, v113, s64, |v112|
	v_cvt_u32_f32_e32 v112, v114
	v_cvt_u32_f32_e32 v113, v113
	v_lshl_add_u64 v[114:115], v[146:147], 3, s[36:37]
	global_atomic_add_x2 v[114:115], v[112:113], off
.LBB0_1040:
	s_or_b64 exec, exec, s[50:51]
	v_or_b32_e32 v112, 16, v146
	s_waitcnt lgkmcnt(0)
	v_ashrrev_i32_e32 v113, 31, v112
	v_lshlrev_b64 v[114:115], 11, v[112:113]
	v_lshl_add_u64 v[114:115], s[22:23], 0, v[114:115]
	v_lshl_add_u64 v[122:123], v[144:145], 1, v[114:115]
	global_load_dwordx4 v[114:117], v[122:123], off
	global_load_dwordx4 v[118:121], v[122:123], off offset:256
	s_waitcnt vmcnt(1)
	v_lshlrev_b32_e32 v124, 16, v114
	v_and_b32_e32 v125, 0xffff0000, v114
	v_lshlrev_b32_e32 v114, 16, v115
	v_and_b32_e32 v115, 0xffff0000, v115
	s_waitcnt vmcnt(0)
	v_lshlrev_b32_e32 v158, 16, v118
	v_and_b32_e32 v159, 0xffff0000, v118
	v_lshlrev_b32_e32 v118, 16, v119
	v_and_b32_e32 v119, 0xffff0000, v119
	v_lshlrev_b32_e32 v126, 16, v116
	v_and_b32_e32 v127, 0xffff0000, v116
	v_lshlrev_b32_e32 v116, 16, v117
	v_and_b32_e32 v117, 0xffff0000, v117
	v_lshlrev_b32_e32 v160, 16, v120
	v_and_b32_e32 v161, 0xffff0000, v120
	v_lshlrev_b32_e32 v120, 16, v121
	v_and_b32_e32 v121, 0xffff0000, v121
	v_pk_fma_f32 v[110:111], v[110:111], 0.5, v[114:115] op_sel_hi:[1,0,1]
	v_pk_fma_f32 v[108:109], v[108:109], 0.5, v[124:125] op_sel_hi:[1,0,1]
	v_pk_fma_f32 v[102:103], v[102:103], 0.5, v[118:119] op_sel_hi:[1,0,1]
	v_pk_fma_f32 v[100:101], v[100:101], 0.5, v[158:159] op_sel_hi:[1,0,1]
	v_pk_fma_f32 v[106:107], v[106:107], 0.5, v[116:117] op_sel_hi:[1,0,1]
	v_pk_fma_f32 v[104:105], v[104:105], 0.5, v[126:127] op_sel_hi:[1,0,1]
	v_pk_fma_f32 v[114:115], v[98:99], 0.5, v[120:121] op_sel_hi:[1,0,1]
	v_pk_fma_f32 v[116:117], v[96:97], 0.5, v[160:161] op_sel_hi:[1,0,1]
	v_mul_f32_e32 v98, v109, v109
	v_mul_f32_e32 v99, v111, v111
	v_mul_f32_e32 v118, v101, v101
	v_mul_f32_e32 v119, v103, v103
	v_cvt_pk_bf16_f32 v96, v108, v109
	v_mul_f32_e32 v109, v105, v105
	v_mul_f32_e32 v120, v117, v117
	v_fmac_f32_e32 v98, v108, v108
	v_fmac_f32_e32 v99, v110, v110
	v_fmac_f32_e32 v118, v100, v100
	v_fmac_f32_e32 v119, v102, v102
	v_cvt_pk_bf16_f32 v97, v110, v111
	v_mul_f32_e32 v111, v107, v107
	v_mul_f32_e32 v121, v115, v115
	v_fmac_f32_e32 v109, v104, v104
	v_fmac_f32_e32 v120, v116, v116
	v_add_f32_e32 v98, v98, v99
	v_add_f32_e32 v99, v118, v119
	v_fmac_f32_e32 v111, v106, v106
	v_fmac_f32_e32 v121, v114, v114
	v_add_f32_e32 v98, v109, v98
	v_add_f32_e32 v99, v120, v99
	v_add_f32_e32 v98, v111, v98
	v_add_f32_e32 v99, v121, v99
	v_add_f32_e32 v108, v98, v99
	v_mov_b32_e32 v109, v108
	s_nop 1
	v_permlane16_swap_b32_e32 v109, v108
	v_cvt_pk_bf16_f32 v98, v104, v105
	v_cvt_pk_bf16_f32 v99, v106, v107
	global_store_dwordx4 v[122:123], v[96:99], off
	s_waitcnt lgkmcnt(0)
	s_nop 0
	v_add_f32_e32 v96, v108, v109
	v_mov_b32_e32 v97, v96
	s_nop 1
	v_permlane32_swap_b32_e32 v97, v96
	v_cvt_pk_bf16_f32 v98, v100, v101
	v_cvt_pk_bf16_f32 v99, v102, v103
	v_cvt_pk_bf16_f32 v100, v116, v117
	v_cvt_pk_bf16_f32 v101, v114, v115
	global_store_dwordx4 v[122:123], v[98:101], off offset:256
	s_and_saveexec_b64 s[50:51], s[10:11]
	s_cbranch_execz .LBB0_1042
	s_waitcnt lgkmcnt(0)
	v_add_f32_e32 v96, v96, v97
	v_mul_f32_e32 v96, 0x4f800000, v96
	v_trunc_f32_e32 v96, v96
	v_mul_f32_e64 v97, |v96|, s63
	v_floor_f32_e32 v97, v97
	v_fma_f32 v98, v97, s64, |v96|
	v_cvt_u32_f32_e32 v96, v98
	v_cvt_u32_f32_e32 v97, v97
	v_lshl_add_u64 v[98:99], v[112:113], 3, s[36:37]
	global_atomic_add_x2 v[98:99], v[96:97], off
; __device__ __forceinline__ unsigned cvtpk(float lo, float hi) { f32x2v_ v = {lo, hi}; bf16x2v_ b = __builtin_convertvector(v, bf16x2v_); return __builtin_bit_cast(unsigned, b); }
; __device__ __forceinline__ void fx_add(float* p, size_t idx, float s) { atomicAdd((unsigned long long*)p + idx, (unsigned long long)(long long)(s * 4294967296.0f)); }
;     __device__ __forceinline__ void operator()(const f32x4 (&acc)[2][2][4][2], const Unit& u, int wr, int wc, int fr, int fq) const {
;     ...
;             for (int m = 0; m < 4; ++m) { const int row = row0 + ai * HALF + m * 16; const size_t off = (size_t)row * 1024 + col0; float s = 0.f;
; #pragma unroll
;                 for (int bj = 0; bj < 2; ++bj) { f32x4 a0, a1;
;                     if (xin32) { const float* p = xin32 + off + bj * HALF; a0 = *(const f32x4*)p; a1 = *(const f32x4*)(p + 4); }
;                     else { const u32x4 w = *(const u32x4*)(xb + off + bj * HALF);
;                         a0 = (f32x4){__uint_as_float(w.x << 16), __uint_as_float(w.x & 0xffff0000u), __uint_as_float(w.y << 16), __uint_as_float(w.y & 0xffff0000u)};
;                         a1 = (f32x4){__uint_as_float(w.z << 16), __uint_as_float(w.z & 0xffff0000u), __uint_as_float(w.w << 16), __uint_as_float(w.w & 0xffff0000u)}; }
;                     const f32x4 v0 = a0 + acc[ai][bj][m][0] * alpha, v1 = a1 + acc[ai][bj][m][1] * alpha;
;                     u32x4 w; w.x = cvtpk(v0[0], v0[1]); w.y = cvtpk(v0[2], v0[3]); w.z = cvtpk(v1[0], v1[1]); w.w = cvtpk(v1[2], v1[3]);
;                     *(u32x4*)(xb + off + bj * HALF) = w;
;                     s += (v0[0] * v0[0] + v0[1] * v0[1]) + (v0[2] * v0[2] + v0[3] * v0[3]) + (v1[0] * v1[0] + v1[1] * v1[1]) + (v1[2] * v1[2] + v1[3] * v1[3]); }
;                 s += __shfl_xor(s, 16); s += __shfl_xor(s, 32);
;                 if (fq == 0) fx_add(ssout, row, s); }
.LBB0_1042:
	s_or_b64 exec, exec, s[50:51]
	v_or_b32_e32 v96, 32, v146
	s_waitcnt lgkmcnt(0)
	v_ashrrev_i32_e32 v97, 31, v96
	v_lshlrev_b64 v[98:99], 11, v[96:97]
	v_lshl_add_u64 v[98:99], s[22:23], 0, v[98:99]
	v_lshl_add_u64 v[106:107], v[144:145], 1, v[98:99]
	global_load_dwordx4 v[98:101], v[106:107], off
	global_load_dwordx4 v[102:105], v[106:107], off offset:256
	s_waitcnt vmcnt(1)
	v_lshlrev_b32_e32 v108, 16, v98
	v_and_b32_e32 v109, 0xffff0000, v98
	v_lshlrev_b32_e32 v98, 16, v99
	v_and_b32_e32 v99, 0xffff0000, v99
	s_waitcnt vmcnt(0)
	v_lshlrev_b32_e32 v112, 16, v102
	v_and_b32_e32 v113, 0xffff0000, v102
	v_lshlrev_b32_e32 v102, 16, v103
	v_and_b32_e32 v103, 0xffff0000, v103
	v_lshlrev_b32_e32 v110, 16, v100
	v_and_b32_e32 v111, 0xffff0000, v100
	v_lshlrev_b32_e32 v100, 16, v101
	v_and_b32_e32 v101, 0xffff0000, v101
	v_lshlrev_b32_e32 v114, 16, v104
	v_and_b32_e32 v115, 0xffff0000, v104
	v_lshlrev_b32_e32 v104, 16, v105
	v_and_b32_e32 v105, 0xffff0000, v105
	v_pk_fma_f32 v[94:95], v[94:95], 0.5, v[98:99] op_sel_hi:[1,0,1]
	v_pk_fma_f32 v[92:93], v[92:93], 0.5, v[108:109] op_sel_hi:[1,0,1]
	v_pk_fma_f32 v[86:87], v[86:87], 0.5, v[102:103] op_sel_hi:[1,0,1]
	v_pk_fma_f32 v[84:85], v[84:85], 0.5, v[112:113] op_sel_hi:[1,0,1]
	v_pk_fma_f32 v[90:91], v[90:91], 0.5, v[100:101] op_sel_hi:[1,0,1]
	v_pk_fma_f32 v[88:89], v[88:89], 0.5, v[110:111] op_sel_hi:[1,0,1]
	v_pk_fma_f32 v[98:99], v[82:83], 0.5, v[104:105] op_sel_hi:[1,0,1]
	v_pk_fma_f32 v[100:101], v[80:81], 0.5, v[114:115] op_sel_hi:[1,0,1]
	v_mul_f32_e32 v82, v93, v93
	v_mul_f32_e32 v83, v95, v95
	v_mul_f32_e32 v102, v85, v85
	v_mul_f32_e32 v103, v87, v87
	v_cvt_pk_bf16_f32 v80, v92, v93
	v_mul_f32_e32 v93, v89, v89
	v_mul_f32_e32 v104, v101, v101
	v_fmac_f32_e32 v82, v92, v92
	v_fmac_f32_e32 v83, v94, v94
	v_fmac_f32_e32 v102, v84, v84
	v_fmac_f32_e32 v103, v86, v86
	v_cvt_pk_bf16_f32 v81, v94, v95
	v_mul_f32_e32 v95, v91, v91
	v_mul_f32_e32 v105, v99, v99
	v_fmac_f32_e32 v93, v88, v88
	v_fmac_f32_e32 v104, v100, v100
	v_add_f32_e32 v82, v82, v83
	v_add_f32_e32 v83, v102, v103
	v_fmac_f32_e32 v95, v90, v90
	v_fmac_f32_e32 v105, v98, v98
	v_add_f32_e32 v82, v93, v82
	v_add_f32_e32 v83, v104, v83
	v_add_f32_e32 v82, v95, v82
	v_add_f32_e32 v83, v105, v83
	v_add_f32_e32 v92, v82, v83
	v_mov_b32_e32 v93, v92
	s_nop 1
	v_permlane16_swap_b32_e32 v93, v92
	v_cvt_pk_bf16_f32 v82, v88, v89
	v_cvt_pk_bf16_f32 v83, v90, v91
	global_store_dwordx4 v[106:107], v[80:83], off
	s_waitcnt lgkmcnt(0)
	s_nop 0
	v_add_f32_e32 v80, v92, v93
	v_mov_b32_e32 v81, v80
	s_nop 1
	v_permlane32_swap_b32_e32 v81, v80
	v_cvt_pk_bf16_f32 v82, v84, v85
	v_cvt_pk_bf16_f32 v83, v86, v87
	v_cvt_pk_bf16_f32 v84, v100, v101
	v_cvt_pk_bf16_f32 v85, v98, v99
	global_store_dwordx4 v[106:107], v[82:85], off offset:256
	s_and_saveexec_b64 s[50:51], s[10:11]
	s_cbranch_execz .LBB0_1044
	s_waitcnt lgkmcnt(0)
	v_add_f32_e32 v80, v80, v81
	v_mul_f32_e32 v80, 0x4f800000, v80
	v_trunc_f32_e32 v80, v80
	v_mul_f32_e64 v81, |v80|, s63
	v_floor_f32_e32 v81, v81
	v_fma_f32 v82, v81, s64, |v80|
	v_cvt_u32_f32_e32 v80, v82
	v_cvt_u32_f32_e32 v81, v81
	v_lshl_add_u64 v[82:83], v[96:97], 3, s[36:37]
	global_atomic_add_x2 v[82:83], v[80:81], off
.LBB0_1044:
	s_or_b64 exec, exec, s[50:51]
	v_or_b32_e32 v80, 48, v146
	s_waitcnt lgkmcnt(0)
	v_ashrrev_i32_e32 v81, 31, v80
	v_lshlrev_b64 v[82:83], 11, v[80:81]
	v_lshl_add_u64 v[82:83], s[22:23], 0, v[82:83]
	v_lshl_add_u64 v[90:91], v[144:145], 1, v[82:83]
	global_load_dwordx4 v[82:85], v[90:91], off
	global_load_dwordx4 v[86:89], v[90:91], off offset:256
	s_waitcnt vmcnt(1)
	v_lshlrev_b32_e32 v92, 16, v82
	v_and_b32_e32 v93, 0xffff0000, v82
	v_lshlrev_b32_e32 v82, 16, v83
	v_and_b32_e32 v83, 0xffff0000, v83
	s_waitcnt vmcnt(0)
	v_lshlrev_b32_e32 v96, 16, v86
	v_and_b32_e32 v97, 0xffff0000, v86
	v_lshlrev_b32_e32 v86, 16, v87
	v_and_b32_e32 v87, 0xffff0000, v87
	v_lshlrev_b32_e32 v94, 16, v84
	v_and_b32_e32 v95, 0xffff0000, v84
	v_lshlrev_b32_e32 v84, 16, v85
	v_and_b32_e32 v85, 0xffff0000, v85
	v_lshlrev_b32_e32 v98, 16, v88
	v_and_b32_e32 v99, 0xffff0000, v88
	v_lshlrev_b32_e32 v88, 16, v89
	v_and_b32_e32 v89, 0xffff0000, v89
	v_pk_fma_f32 v[78:79], v[78:79], 0.5, v[82:83] op_sel_hi:[1,0,1]
	v_pk_fma_f32 v[76:77], v[76:77], 0.5, v[92:93] op_sel_hi:[1,0,1]
	v_pk_fma_f32 v[70:71], v[70:71], 0.5, v[86:87] op_sel_hi:[1,0,1]
	v_pk_fma_f32 v[68:69], v[68:69], 0.5, v[96:97] op_sel_hi:[1,0,1]
	v_pk_fma_f32 v[74:75], v[74:75], 0.5, v[84:85] op_sel_hi:[1,0,1]
	v_pk_fma_f32 v[72:73], v[72:73], 0.5, v[94:95] op_sel_hi:[1,0,1]
	v_pk_fma_f32 v[82:83], v[66:67], 0.5, v[88:89] op_sel_hi:[1,0,1]
	v_pk_fma_f32 v[84:85], v[64:65], 0.5, v[98:99] op_sel_hi:[1,0,1]
	v_mul_f32_e32 v66, v77, v77
	v_mul_f32_e32 v67, v79, v79
	v_mul_f32_e32 v86, v69, v69
	v_mul_f32_e32 v87, v71, v71
	v_cvt_pk_bf16_f32 v64, v76, v77
	v_mul_f32_e32 v77, v73, v73
	v_mul_f32_e32 v88, v85, v85
	v_fmac_f32_e32 v66, v76, v76
	v_fmac_f32_e32 v67, v78, v78
	v_fmac_f32_e32 v86, v68, v68
	v_fmac_f32_e32 v87, v70, v70
	v_cvt_pk_bf16_f32 v65, v78, v79
	v_mul_f32_e32 v79, v75, v75
	v_mul_f32_e32 v89, v83, v83
	v_fmac_f32_e32 v77, v72, v72
	v_fmac_f32_e32 v88, v84, v84
	v_add_f32_e32 v66, v66, v67
	v_add_f32_e32 v67, v86, v87
	v_fmac_f32_e32 v79, v74, v74
	v_fmac_f32_e32 v89, v82, v82
	v_add_f32_e32 v66, v77, v66
	v_add_f32_e32 v67, v88, v67
	v_add_f32_e32 v66, v79, v66
	v_add_f32_e32 v67, v89, v67
	v_add_f32_e32 v76, v66, v67
	v_mov_b32_e32 v77, v76
	s_nop 1
	v_permlane16_swap_b32_e32 v77, v76
	v_cvt_pk_bf16_f32 v66, v72, v73
	v_cvt_pk_bf16_f32 v67, v74, v75
	global_store_dwordx4 v[90:91], v[64:67], off
	s_waitcnt lgkmcnt(0)
	s_nop 0
	v_add_f32_e32 v64, v76, v77
	v_mov_b32_e32 v65, v64
	s_nop 1
	v_permlane32_swap_b32_e32 v65, v64
	v_cvt_pk_bf16_f32 v66, v68, v69
	v_cvt_pk_bf16_f32 v67, v70, v71
	v_cvt_pk_bf16_f32 v68, v84, v85
	v_cvt_pk_bf16_f32 v69, v82, v83
	global_store_dwordx4 v[90:91], v[66:69], off offset:256
	s_and_saveexec_b64 s[50:51], s[10:11]
	s_cbranch_execz .LBB0_1046
	s_waitcnt lgkmcnt(0)
	v_add_f32_e32 v64, v64, v65
	v_mul_f32_e32 v64, 0x4f800000, v64
	v_trunc_f32_e32 v64, v64
	v_mul_f32_e64 v65, |v64|, s63
	v_floor_f32_e32 v65, v65
	v_fma_f32 v66, v65, s64, |v64|
	v_cvt_u32_f32_e32 v64, v66
	v_cvt_u32_f32_e32 v65, v65
	v_lshl_add_u64 v[66:67], v[80:81], 3, s[36:37]
	global_atomic_add_x2 v[66:67], v[64:65], off
; __device__ __forceinline__ unsigned cvtpk(float lo, float hi) { f32x2v_ v = {lo, hi}; bf16x2v_ b = __builtin_convertvector(v, bf16x2v_); return __builtin_bit_cast(unsigned, b); }
; __device__ __forceinline__ void fx_add(float* p, size_t idx, float s) { atomicAdd((unsigned long long*)p + idx, (unsigned long long)(long long)(s * 4294967296.0f)); }
;     __device__ __forceinline__ void operator()(const f32x4 (&acc)[2][2][4][2], const Unit& u, int wr, int wc, int fr, int fq) const {
;     ...
;             for (int m = 0; m < 4; ++m) { const int row = row0 + ai * HALF + m * 16; const size_t off = (size_t)row * 1024 + col0; float s = 0.f;
; #pragma unroll
;                 for (int bj = 0; bj < 2; ++bj) { f32x4 a0, a1;
;                     if (xin32) { const float* p = xin32 + off + bj * HALF; a0 = *(const f32x4*)p; a1 = *(const f32x4*)(p + 4); }
;                     else { const u32x4 w = *(const u32x4*)(xb + off + bj * HALF);
;                         a0 = (f32x4){__uint_as_float(w.x << 16), __uint_as_float(w.x & 0xffff0000u), __uint_as_float(w.y << 16), __uint_as_float(w.y & 0xffff0000u)};
;                         a1 = (f32x4){__uint_as_float(w.z << 16), __uint_as_float(w.z & 0xffff0000u), __uint_as_float(w.w << 16), __uint_as_float(w.w & 0xffff0000u)}; }
;                     const f32x4 v0 = a0 + acc[ai][bj][m][0] * alpha, v1 = a1 + acc[ai][bj][m][1] * alpha;
;                     u32x4 w; w.x = cvtpk(v0[0], v0[1]); w.y = cvtpk(v0[2], v0[3]); w.z = cvtpk(v1[0], v1[1]); w.w = cvtpk(v1[2], v1[3]);
;                     *(u32x4*)(xb + off + bj * HALF) = w;
;                     s += (v0[0] * v0[0] + v0[1] * v0[1]) + (v0[2] * v0[2] + v0[3] * v0[3]) + (v1[0] * v1[0] + v1[1] * v1[1]) + (v1[2] * v1[2] + v1[3] * v1[3]); }
;                 s += __shfl_xor(s, 16); s += __shfl_xor(s, 32);
;                 if (fq == 0) fx_add(ssout, row, s); }
.LBB0_1046:
	s_or_b64 exec, exec, s[50:51]
	v_add_u32_e32 v64, 0x80, v146
	s_waitcnt lgkmcnt(0)
	v_ashrrev_i32_e32 v65, 31, v64
	v_lshlrev_b64 v[66:67], 11, v[64:65]
	v_lshl_add_u64 v[66:67], s[22:23], 0, v[66:67]
	v_lshl_add_u64 v[74:75], v[144:145], 1, v[66:67]
	global_load_dwordx4 v[66:69], v[74:75], off
	global_load_dwordx4 v[70:73], v[74:75], off offset:256
	s_waitcnt vmcnt(1)
	v_lshlrev_b32_e32 v76, 16, v66
	v_and_b32_e32 v77, 0xffff0000, v66
	v_lshlrev_b32_e32 v66, 16, v67
	v_and_b32_e32 v67, 0xffff0000, v67
	s_waitcnt vmcnt(0)
	v_lshlrev_b32_e32 v80, 16, v70
	v_and_b32_e32 v81, 0xffff0000, v70
	v_lshlrev_b32_e32 v70, 16, v71
	v_and_b32_e32 v71, 0xffff0000, v71
	v_lshlrev_b32_e32 v78, 16, v68
	v_and_b32_e32 v79, 0xffff0000, v68
	v_lshlrev_b32_e32 v68, 16, v69
	v_and_b32_e32 v69, 0xffff0000, v69
	v_lshlrev_b32_e32 v82, 16, v72
	v_and_b32_e32 v83, 0xffff0000, v72
	v_lshlrev_b32_e32 v72, 16, v73
	v_and_b32_e32 v73, 0xffff0000, v73
	v_pk_fma_f32 v[62:63], v[62:63], 0.5, v[66:67] op_sel_hi:[1,0,1]
	v_pk_fma_f32 v[60:61], v[60:61], 0.5, v[76:77] op_sel_hi:[1,0,1]
	v_pk_fma_f32 v[54:55], v[54:55], 0.5, v[70:71] op_sel_hi:[1,0,1]
	v_pk_fma_f32 v[52:53], v[52:53], 0.5, v[80:81] op_sel_hi:[1,0,1]
	v_pk_fma_f32 v[58:59], v[58:59], 0.5, v[68:69] op_sel_hi:[1,0,1]
	v_pk_fma_f32 v[56:57], v[56:57], 0.5, v[78:79] op_sel_hi:[1,0,1]
	v_pk_fma_f32 v[66:67], v[50:51], 0.5, v[72:73] op_sel_hi:[1,0,1]
	v_pk_fma_f32 v[68:69], v[48:49], 0.5, v[82:83] op_sel_hi:[1,0,1]
	v_mul_f32_e32 v50, v61, v61
	v_mul_f32_e32 v51, v63, v63
	v_mul_f32_e32 v70, v53, v53
	v_mul_f32_e32 v71, v55, v55
	v_cvt_pk_bf16_f32 v48, v60, v61
	v_mul_f32_e32 v61, v57, v57
	v_mul_f32_e32 v72, v69, v69
	v_fmac_f32_e32 v50, v60, v60
	v_fmac_f32_e32 v51, v62, v62
	v_fmac_f32_e32 v70, v52, v52
	v_fmac_f32_e32 v71, v54, v54
	v_cvt_pk_bf16_f32 v49, v62, v63
	v_mul_f32_e32 v63, v59, v59
	v_mul_f32_e32 v73, v67, v67
	v_fmac_f32_e32 v61, v56, v56
	v_fmac_f32_e32 v72, v68, v68
	v_add_f32_e32 v50, v50, v51
	v_add_f32_e32 v51, v70, v71
	v_fmac_f32_e32 v63, v58, v58
	v_fmac_f32_e32 v73, v66, v66
	v_add_f32_e32 v50, v61, v50
	v_add_f32_e32 v51, v72, v51
	v_add_f32_e32 v50, v63, v50
	v_add_f32_e32 v51, v73, v51
	v_add_f32_e32 v60, v50, v51
	v_mov_b32_e32 v61, v60
	s_nop 1
	v_permlane16_swap_b32_e32 v61, v60
	v_cvt_pk_bf16_f32 v50, v56, v57
	v_cvt_pk_bf16_f32 v51, v58, v59
	global_store_dwordx4 v[74:75], v[48:51], off
	s_waitcnt lgkmcnt(0)
	s_nop 0
	v_add_f32_e32 v48, v60, v61
	v_mov_b32_e32 v49, v48
	s_nop 1
	v_permlane32_swap_b32_e32 v49, v48
	v_cvt_pk_bf16_f32 v50, v52, v53
	v_cvt_pk_bf16_f32 v51, v54, v55
	v_cvt_pk_bf16_f32 v52, v68, v69
	v_cvt_pk_bf16_f32 v53, v66, v67
	global_store_dwordx4 v[74:75], v[50:53], off offset:256
	s_and_saveexec_b64 s[50:51], s[10:11]
	s_cbranch_execz .LBB0_1048
	s_waitcnt lgkmcnt(0)
	v_add_f32_e32 v48, v48, v49
	v_mul_f32_e32 v48, 0x4f800000, v48
	v_trunc_f32_e32 v48, v48
	v_mul_f32_e64 v49, |v48|, s63
	v_floor_f32_e32 v49, v49
	v_fma_f32 v50, v49, s64, |v48|
	v_cvt_u32_f32_e32 v48, v50
	v_cvt_u32_f32_e32 v49, v49
	v_lshl_add_u64 v[50:51], v[64:65], 3, s[36:37]
	global_atomic_add_x2 v[50:51], v[48:49], off
.LBB0_1048:
	s_or_b64 exec, exec, s[50:51]
	v_add_u32_e32 v48, 0x90, v146
	s_waitcnt lgkmcnt(0)
	v_ashrrev_i32_e32 v49, 31, v48
	v_lshlrev_b64 v[50:51], 11, v[48:49]
	v_lshl_add_u64 v[50:51], s[22:23], 0, v[50:51]
	v_lshl_add_u64 v[58:59], v[144:145], 1, v[50:51]
	global_load_dwordx4 v[50:53], v[58:59], off
	global_load_dwordx4 v[54:57], v[58:59], off offset:256
	s_waitcnt vmcnt(1)
	v_lshlrev_b32_e32 v60, 16, v50
	v_and_b32_e32 v61, 0xffff0000, v50
	v_lshlrev_b32_e32 v50, 16, v51
	v_and_b32_e32 v51, 0xffff0000, v51
	s_waitcnt vmcnt(0)
	v_lshlrev_b32_e32 v64, 16, v54
	v_and_b32_e32 v65, 0xffff0000, v54
	v_lshlrev_b32_e32 v54, 16, v55
	v_and_b32_e32 v55, 0xffff0000, v55
	v_lshlrev_b32_e32 v62, 16, v52
	v_and_b32_e32 v63, 0xffff0000, v52
	v_lshlrev_b32_e32 v52, 16, v53
	v_and_b32_e32 v53, 0xffff0000, v53
	v_lshlrev_b32_e32 v66, 16, v56
	v_and_b32_e32 v67, 0xffff0000, v56
	v_lshlrev_b32_e32 v56, 16, v57
	v_and_b32_e32 v57, 0xffff0000, v57
	v_pk_fma_f32 v[46:47], v[46:47], 0.5, v[50:51] op_sel_hi:[1,0,1]
	v_pk_fma_f32 v[44:45], v[44:45], 0.5, v[60:61] op_sel_hi:[1,0,1]
	v_pk_fma_f32 v[38:39], v[38:39], 0.5, v[54:55] op_sel_hi:[1,0,1]
	v_pk_fma_f32 v[36:37], v[36:37], 0.5, v[64:65] op_sel_hi:[1,0,1]
	v_pk_fma_f32 v[42:43], v[42:43], 0.5, v[52:53] op_sel_hi:[1,0,1]
	v_pk_fma_f32 v[40:41], v[40:41], 0.5, v[62:63] op_sel_hi:[1,0,1]
	v_pk_fma_f32 v[50:51], v[34:35], 0.5, v[56:57] op_sel_hi:[1,0,1]
	v_pk_fma_f32 v[52:53], v[32:33], 0.5, v[66:67] op_sel_hi:[1,0,1]
	v_mul_f32_e32 v34, v45, v45
	v_mul_f32_e32 v35, v47, v47
	v_mul_f32_e32 v54, v37, v37
	v_mul_f32_e32 v55, v39, v39
	v_cvt_pk_bf16_f32 v32, v44, v45
	v_mul_f32_e32 v45, v41, v41
	v_mul_f32_e32 v56, v53, v53
	v_fmac_f32_e32 v34, v44, v44
	v_fmac_f32_e32 v35, v46, v46
	v_fmac_f32_e32 v54, v36, v36
	v_fmac_f32_e32 v55, v38, v38
	v_cvt_pk_bf16_f32 v33, v46, v47
	v_mul_f32_e32 v47, v43, v43
	v_mul_f32_e32 v57, v51, v51
	v_fmac_f32_e32 v45, v40, v40
	v_fmac_f32_e32 v56, v52, v52
	v_add_f32_e32 v34, v34, v35
	v_add_f32_e32 v35, v54, v55
	v_fmac_f32_e32 v47, v42, v42
	v_fmac_f32_e32 v57, v50, v50
	v_add_f32_e32 v34, v45, v34
	v_add_f32_e32 v35, v56, v35
	v_add_f32_e32 v34, v47, v34
	v_add_f32_e32 v35, v57, v35
	v_add_f32_e32 v44, v34, v35
	v_mov_b32_e32 v45, v44
	s_nop 1
	v_permlane16_swap_b32_e32 v45, v44
	v_cvt_pk_bf16_f32 v34, v40, v41
	v_cvt_pk_bf16_f32 v35, v42, v43
	global_store_dwordx4 v[58:59], v[32:35], off
	s_waitcnt lgkmcnt(0)
	s_nop 0
	v_add_f32_e32 v32, v44, v45
	v_mov_b32_e32 v33, v32
	s_nop 1
	v_permlane32_swap_b32_e32 v33, v32
	v_cvt_pk_bf16_f32 v34, v36, v37
	v_cvt_pk_bf16_f32 v35, v38, v39
	v_cvt_pk_bf16_f32 v36, v52, v53
	v_cvt_pk_bf16_f32 v37, v50, v51
	global_store_dwordx4 v[58:59], v[34:37], off offset:256
	s_and_saveexec_b64 s[50:51], s[10:11]
	s_cbranch_execz .LBB0_1050
	s_waitcnt lgkmcnt(0)
	v_add_f32_e32 v32, v32, v33
	v_mul_f32_e32 v32, 0x4f800000, v32
	v_trunc_f32_e32 v32, v32
	v_mul_f32_e64 v33, |v32|, s63
	v_floor_f32_e32 v33, v33
	v_fma_f32 v34, v33, s64, |v32|
	v_cvt_u32_f32_e32 v32, v34
	v_cvt_u32_f32_e32 v33, v33
	v_lshl_add_u64 v[34:35], v[48:49], 3, s[36:37]
	global_atomic_add_x2 v[34:35], v[32:33], off
; __device__ __forceinline__ unsigned cvtpk(float lo, float hi) { f32x2v_ v = {lo, hi}; bf16x2v_ b = __builtin_convertvector(v, bf16x2v_); return __builtin_bit_cast(unsigned, b); }
; __device__ __forceinline__ void fx_add(float* p, size_t idx, float s) { atomicAdd((unsigned long long*)p + idx, (unsigned long long)(long long)(s * 4294967296.0f)); }
;     __device__ __forceinline__ void operator()(const f32x4 (&acc)[2][2][4][2], const Unit& u, int wr, int wc, int fr, int fq) const {
;     ...
;             for (int m = 0; m < 4; ++m) { const int row = row0 + ai * HALF + m * 16; const size_t off = (size_t)row * 1024 + col0; float s = 0.f;
; #pragma unroll
;                 for (int bj = 0; bj < 2; ++bj) { f32x4 a0, a1;
;                     if (xin32) { const float* p = xin32 + off + bj * HALF; a0 = *(const f32x4*)p; a1 = *(const f32x4*)(p + 4); }
;                     else { const u32x4 w = *(const u32x4*)(xb + off + bj * HALF);
;                         a0 = (f32x4){__uint_as_float(w.x << 16), __uint_as_float(w.x & 0xffff0000u), __uint_as_float(w.y << 16), __uint_as_float(w.y & 0xffff0000u)};
;                         a1 = (f32x4){__uint_as_float(w.z << 16), __uint_as_float(w.z & 0xffff0000u), __uint_as_float(w.w << 16), __uint_as_float(w.w & 0xffff0000u)}; }
;                     const f32x4 v0 = a0 + acc[ai][bj][m][0] * alpha, v1 = a1 + acc[ai][bj][m][1] * alpha;
;                     u32x4 w; w.x = cvtpk(v0[0], v0[1]); w.y = cvtpk(v0[2], v0[3]); w.z = cvtpk(v1[0], v1[1]); w.w = cvtpk(v1[2], v1[3]);
;                     *(u32x4*)(xb + off + bj * HALF) = w;
;                     s += (v0[0] * v0[0] + v0[1] * v0[1]) + (v0[2] * v0[2] + v0[3] * v0[3]) + (v1[0] * v1[0] + v1[1] * v1[1]) + (v1[2] * v1[2] + v1[3] * v1[3]); }
;                 s += __shfl_xor(s, 16); s += __shfl_xor(s, 32);
;                 if (fq == 0) fx_add(ssout, row, s); }
.LBB0_1050:
	s_or_b64 exec, exec, s[50:51]
	v_add_u32_e32 v32, 0xa0, v146
	s_waitcnt lgkmcnt(0)
	v_ashrrev_i32_e32 v33, 31, v32
	v_lshlrev_b64 v[34:35], 11, v[32:33]
	v_lshl_add_u64 v[34:35], s[22:23], 0, v[34:35]
	v_lshl_add_u64 v[42:43], v[144:145], 1, v[34:35]
	global_load_dwordx4 v[34:37], v[42:43], off
	global_load_dwordx4 v[38:41], v[42:43], off offset:256
	s_waitcnt vmcnt(1)
	v_lshlrev_b32_e32 v44, 16, v34
	v_and_b32_e32 v45, 0xffff0000, v34
	v_lshlrev_b32_e32 v34, 16, v35
	v_and_b32_e32 v35, 0xffff0000, v35
	s_waitcnt vmcnt(0)
	v_lshlrev_b32_e32 v48, 16, v38
	v_and_b32_e32 v49, 0xffff0000, v38
	v_lshlrev_b32_e32 v38, 16, v39
	v_and_b32_e32 v39, 0xffff0000, v39
	v_lshlrev_b32_e32 v46, 16, v36
	v_and_b32_e32 v47, 0xffff0000, v36
	v_lshlrev_b32_e32 v36, 16, v37
	v_and_b32_e32 v37, 0xffff0000, v37
	v_lshlrev_b32_e32 v50, 16, v40
	v_and_b32_e32 v51, 0xffff0000, v40
	v_lshlrev_b32_e32 v40, 16, v41
	v_and_b32_e32 v41, 0xffff0000, v41
	v_pk_fma_f32 v[30:31], v[30:31], 0.5, v[34:35] op_sel_hi:[1,0,1]
	v_pk_fma_f32 v[28:29], v[28:29], 0.5, v[44:45] op_sel_hi:[1,0,1]
	v_pk_fma_f32 v[22:23], v[22:23], 0.5, v[38:39] op_sel_hi:[1,0,1]
	v_pk_fma_f32 v[20:21], v[20:21], 0.5, v[48:49] op_sel_hi:[1,0,1]
	v_pk_fma_f32 v[26:27], v[26:27], 0.5, v[36:37] op_sel_hi:[1,0,1]
	v_pk_fma_f32 v[24:25], v[24:25], 0.5, v[46:47] op_sel_hi:[1,0,1]
	v_pk_fma_f32 v[34:35], v[18:19], 0.5, v[40:41] op_sel_hi:[1,0,1]
	v_pk_fma_f32 v[36:37], v[16:17], 0.5, v[50:51] op_sel_hi:[1,0,1]
	v_mul_f32_e32 v18, v29, v29
	v_mul_f32_e32 v19, v31, v31
	v_mul_f32_e32 v38, v21, v21
	v_mul_f32_e32 v39, v23, v23
	v_cvt_pk_bf16_f32 v16, v28, v29
	v_mul_f32_e32 v29, v25, v25
	v_mul_f32_e32 v40, v37, v37
	v_fmac_f32_e32 v18, v28, v28
	v_fmac_f32_e32 v19, v30, v30
	v_fmac_f32_e32 v38, v20, v20
	v_fmac_f32_e32 v39, v22, v22
	v_cvt_pk_bf16_f32 v17, v30, v31
	v_mul_f32_e32 v31, v27, v27
	v_mul_f32_e32 v41, v35, v35
	v_fmac_f32_e32 v29, v24, v24
	v_fmac_f32_e32 v40, v36, v36
	v_add_f32_e32 v18, v18, v19
	v_add_f32_e32 v19, v38, v39
	v_fmac_f32_e32 v31, v26, v26
	v_fmac_f32_e32 v41, v34, v34
	v_add_f32_e32 v18, v29, v18
	v_add_f32_e32 v19, v40, v19
	v_add_f32_e32 v18, v31, v18
	v_add_f32_e32 v19, v41, v19
	v_add_f32_e32 v28, v18, v19
	v_mov_b32_e32 v29, v28
	s_nop 1
	v_permlane16_swap_b32_e32 v29, v28
	v_cvt_pk_bf16_f32 v18, v24, v25
	v_cvt_pk_bf16_f32 v19, v26, v27
	global_store_dwordx4 v[42:43], v[16:19], off
	s_waitcnt lgkmcnt(0)
	s_nop 0
	v_add_f32_e32 v16, v28, v29
	v_mov_b32_e32 v17, v16
	s_nop 1
	v_permlane32_swap_b32_e32 v17, v16
	v_cvt_pk_bf16_f32 v18, v20, v21
	v_cvt_pk_bf16_f32 v19, v22, v23
	v_cvt_pk_bf16_f32 v20, v36, v37
	v_cvt_pk_bf16_f32 v21, v34, v35
	global_store_dwordx4 v[42:43], v[18:21], off offset:256
	s_and_saveexec_b64 s[50:51], s[10:11]
	s_cbranch_execz .LBB0_1052
	s_waitcnt lgkmcnt(0)
	v_add_f32_e32 v16, v16, v17
	v_mul_f32_e32 v16, 0x4f800000, v16
	v_trunc_f32_e32 v16, v16
	v_mul_f32_e64 v17, |v16|, s63
	v_floor_f32_e32 v17, v17
	v_fma_f32 v18, v17, s64, |v16|
	v_cvt_u32_f32_e32 v16, v18
	v_cvt_u32_f32_e32 v17, v17
	v_lshl_add_u64 v[18:19], v[32:33], 3, s[36:37]
	global_atomic_add_x2 v[18:19], v[16:17], off
.LBB0_1052:
	s_or_b64 exec, exec, s[50:51]
	v_add_u32_e32 v16, 0xb0, v146
	s_waitcnt lgkmcnt(0)
	v_ashrrev_i32_e32 v17, 31, v16
	v_lshlrev_b64 v[18:19], 11, v[16:17]
	v_lshl_add_u64 v[18:19], s[22:23], 0, v[18:19]
	v_lshl_add_u64 v[26:27], v[144:145], 1, v[18:19]
	global_load_dwordx4 v[18:21], v[26:27], off
	global_load_dwordx4 v[22:25], v[26:27], off offset:256
	s_waitcnt vmcnt(1)
	v_lshlrev_b32_e32 v28, 16, v18
	v_and_b32_e32 v29, 0xffff0000, v18
	v_lshlrev_b32_e32 v18, 16, v19
	v_and_b32_e32 v19, 0xffff0000, v19
	s_waitcnt vmcnt(0)
	v_lshlrev_b32_e32 v32, 16, v22
	v_and_b32_e32 v33, 0xffff0000, v22
	v_lshlrev_b32_e32 v22, 16, v23
	v_and_b32_e32 v23, 0xffff0000, v23
	v_lshlrev_b32_e32 v30, 16, v20
	v_and_b32_e32 v31, 0xffff0000, v20
	v_lshlrev_b32_e32 v20, 16, v21
	v_and_b32_e32 v21, 0xffff0000, v21
	v_lshlrev_b32_e32 v34, 16, v24
	v_and_b32_e32 v35, 0xffff0000, v24
	v_lshlrev_b32_e32 v24, 16, v25
	v_and_b32_e32 v25, 0xffff0000, v25
	v_pk_fma_f32 v[14:15], v[14:15], 0.5, v[18:19] op_sel_hi:[1,0,1]
	v_pk_fma_f32 v[12:13], v[12:13], 0.5, v[28:29] op_sel_hi:[1,0,1]
	v_pk_fma_f32 v[6:7], v[6:7], 0.5, v[22:23] op_sel_hi:[1,0,1]
	v_pk_fma_f32 v[4:5], v[4:5], 0.5, v[32:33] op_sel_hi:[1,0,1]
	v_pk_fma_f32 v[10:11], v[10:11], 0.5, v[20:21] op_sel_hi:[1,0,1]
	v_pk_fma_f32 v[8:9], v[8:9], 0.5, v[30:31] op_sel_hi:[1,0,1]
	v_pk_fma_f32 v[18:19], v[2:3], 0.5, v[24:25] op_sel_hi:[1,0,1]
	v_pk_fma_f32 v[20:21], v[0:1], 0.5, v[34:35] op_sel_hi:[1,0,1]
	v_mul_f32_e32 v2, v13, v13
	v_mul_f32_e32 v3, v15, v15
	v_mul_f32_e32 v22, v5, v5
	v_mul_f32_e32 v23, v7, v7
	v_cvt_pk_bf16_f32 v0, v12, v13
	v_mul_f32_e32 v13, v9, v9
	v_mul_f32_e32 v24, v21, v21
	v_fmac_f32_e32 v2, v12, v12
	v_fmac_f32_e32 v3, v14, v14
	v_fmac_f32_e32 v22, v4, v4
	v_fmac_f32_e32 v23, v6, v6
	v_cvt_pk_bf16_f32 v1, v14, v15
	v_mul_f32_e32 v15, v11, v11
	v_mul_f32_e32 v25, v19, v19
	v_fmac_f32_e32 v13, v8, v8
	v_fmac_f32_e32 v24, v20, v20
	v_add_f32_e32 v2, v2, v3
	v_add_f32_e32 v3, v22, v23
	v_fmac_f32_e32 v15, v10, v10
	v_fmac_f32_e32 v25, v18, v18
	v_add_f32_e32 v2, v13, v2
	v_add_f32_e32 v3, v24, v3
	v_add_f32_e32 v2, v15, v2
	v_add_f32_e32 v3, v25, v3
	v_add_f32_e32 v12, v2, v3
	v_mov_b32_e32 v13, v12
	s_nop 1
	v_permlane16_swap_b32_e32 v13, v12
	v_cvt_pk_bf16_f32 v2, v8, v9
	v_cvt_pk_bf16_f32 v3, v10, v11
	global_store_dwordx4 v[26:27], v[0:3], off
	s_waitcnt lgkmcnt(0)
	s_nop 0
	v_add_f32_e32 v0, v12, v13
	v_mov_b32_e32 v1, v0
	s_nop 1
	v_permlane32_swap_b32_e32 v1, v0
	v_cvt_pk_bf16_f32 v2, v4, v5
	v_cvt_pk_bf16_f32 v3, v6, v7
	v_cvt_pk_bf16_f32 v4, v20, v21
	v_cvt_pk_bf16_f32 v5, v18, v19
	global_store_dwordx4 v[26:27], v[2:5], off offset:256
	s_and_saveexec_b64 s[50:51], s[10:11]
	s_cbranch_execz .LBB0_1054
	s_waitcnt lgkmcnt(0)
	v_add_f32_e32 v0, v0, v1
	v_mul_f32_e32 v0, 0x4f800000, v0
	v_trunc_f32_e32 v0, v0
	v_mul_f32_e64 v1, |v0|, s63
	v_floor_f32_e32 v1, v1
	v_fma_f32 v2, v1, s64, |v0|
	v_cvt_u32_f32_e32 v0, v2
	v_cvt_u32_f32_e32 v1, v1
	v_lshl_add_u64 v[2:3], v[16:17], 3, s[36:37]
	global_atomic_add_x2 v[2:3], v[0:1], off

; __device__ __forceinline__ unsigned cvtpk(float lo, float hi) { f32x2v_ v = {lo, hi}; bf16x2v_ b = __builtin_convertvector(v, bf16x2v_); return __builtin_bit_cast(unsigned, b); }
; __device__ __forceinline__ void fx_add(float* p, size_t idx, float s) { atomicAdd((unsigned long long*)p + idx, (unsigned long long)(long long)(s * 4294967296.0f)); }
;     __device__ __forceinline__ void operator()(const f32x4 (&acc)[2][2][4][2], const Unit& u, int wr, int wc, int fr, int fq) const {
;         const int row0 = u.pm * BM + wr * 64 + fr, col0 = u.pn * BM + wc * 32 + 8 * fq;
; #pragma unroll
;         for (int ai = 0; ai < 2; ++ai)
; #pragma unroll
;             for (int m = 0; m < 4; ++m) { const int row = row0 + ai * HALF + m * 16; const size_t off = (size_t)row * 1024 + col0; float s = 0.f;
; #pragma unroll
;                 for (int bj = 0; bj < 2; ++bj) { f32x4 a0, a1;
;                     if (xin32) { const float* p = xin32 + off + bj * HALF; a0 = *(const f32x4*)p; a1 = *(const f32x4*)(p + 4); }
;                     else { const u32x4 w = *(const u32x4*)(xb + off + bj * HALF);
;                         a0 = (f32x4){__uint_as_float(w.x << 16), __uint_as_float(w.x & 0xffff0000u), __uint_as_float(w.y << 16), __uint_as_float(w.y & 0xffff0000u)};
;                         a1 = (f32x4){__uint_as_float(w.z << 16), __uint_as_float(w.z & 0xffff0000u), __uint_as_float(w.w << 16), __uint_as_float(w.w & 0xffff0000u)}; }
;                     const f32x4 v0 = a0 + acc[ai][bj][m][0] * alpha, v1 = a1 + acc[ai][bj][m][1] * alpha;
;                     u32x4 w; w.x = cvtpk(v0[0], v0[1]); w.y = cvtpk(v0[2], v0[3]); w.z = cvtpk(v1[0], v1[1]); w.w = cvtpk(v1[2], v1[3]);
;                     *(u32x4*)(xb + off + bj * HALF) = w;
;                     s += (v0[0] * v0[0] + v0[1] * v0[1]) + (v0[2] * v0[2] + v0[3] * v0[3]) + (v1[0] * v1[0] + v1[1] * v1[1]) + (v1[2] * v1[2] + v1[3] * v1[3]); }
;                 s += __shfl_xor(s, 16); s += __shfl_xor(s, 32);
;                 if (fq == 0) fx_add(ssout, row, s); }
.LBB0_1200:
	v_lshl_add_u32 v146, s77, 8, v148
	v_ashrrev_i32_e32 v147, 31, v146
	v_lshl_or_b32 v144, s76, 8, v150
	v_lshlrev_b64 v[156:157], 11, v[146:147]
	v_ashrrev_i32_e32 v145, 31, v144
	v_lshl_add_u64 v[156:157], s[22:23], 0, v[156:157]
	v_lshl_add_u64 v[166:167], v[144:145], 1, v[156:157]
	global_load_dwordx4 v[158:161], v[166:167], off
	global_load_dwordx4 v[162:165], v[166:167], off offset:256
	v_and_b32_e32 v156, 64, v154
	v_xor_b32_e32 v155, 16, v154
	v_add_u32_e32 v156, 64, v156
	v_xor_b32_e32 v157, 32, v154
	v_cmp_lt_i32_e32 vcc, v155, v156
	s_waitcnt vmcnt(0)
	v_lshlrev_b32_e32 v168, 16, v158
	v_cndmask_b32_e32 v155, v154, v155, vcc
	v_cmp_lt_i32_e32 vcc, v157, v156
	v_and_b32_e32 v169, 0xffff0000, v158
	v_lshlrev_b32_e32 v158, 16, v159
	v_and_b32_e32 v159, 0xffff0000, v159
	v_lshlrev_b32_e32 v172, 16, v162
	v_and_b32_e32 v173, 0xffff0000, v162
	v_lshlrev_b32_e32 v162, 16, v163
	v_and_b32_e32 v163, 0xffff0000, v163
	v_cndmask_b32_e32 v157, v154, v157, vcc
	v_lshlrev_b32_e32 v170, 16, v160
	v_and_b32_e32 v171, 0xffff0000, v160
	v_lshlrev_b32_e32 v160, 16, v161
	v_and_b32_e32 v161, 0xffff0000, v161
	v_lshlrev_b32_e32 v174, 16, v164
	v_and_b32_e32 v175, 0xffff0000, v164
	v_lshlrev_b32_e32 v164, 16, v165
	v_and_b32_e32 v165, 0xffff0000, v165
	v_pk_fma_f32 v[126:127], v[126:127], 0.5, v[158:159] op_sel_hi:[1,0,1]
	v_pk_fma_f32 v[124:125], v[124:125], 0.5, v[168:169] op_sel_hi:[1,0,1]
	v_pk_fma_f32 v[118:119], v[118:119], 0.5, v[162:163] op_sel_hi:[1,0,1]
	v_pk_fma_f32 v[116:117], v[116:117], 0.5, v[172:173] op_sel_hi:[1,0,1]
	v_lshlrev_b32_e32 v156, 2, v155
	v_lshlrev_b32_e32 v155, 2, v157
	v_pk_fma_f32 v[122:123], v[122:123], 0.5, v[160:161] op_sel_hi:[1,0,1]
	v_pk_fma_f32 v[120:121], v[120:121], 0.5, v[170:171] op_sel_hi:[1,0,1]
	v_pk_fma_f32 v[158:159], v[114:115], 0.5, v[164:165] op_sel_hi:[1,0,1]
	v_pk_fma_f32 v[160:161], v[112:113], 0.5, v[174:175] op_sel_hi:[1,0,1]
	v_mul_f32_e32 v114, v125, v125
	v_mul_f32_e32 v115, v127, v127
	v_mul_f32_e32 v157, v117, v117
	v_mul_f32_e32 v162, v119, v119
	v_cvt_pk_bf16_f32 v112, v124, v125
	v_mul_f32_e32 v125, v121, v121
	v_mul_f32_e32 v163, v161, v161
	v_fmac_f32_e32 v114, v124, v124
	v_fmac_f32_e32 v115, v126, v126
	v_fmac_f32_e32 v157, v116, v116
	v_fmac_f32_e32 v162, v118, v118
	v_cvt_pk_bf16_f32 v113, v126, v127
	v_mul_f32_e32 v127, v123, v123
	v_mul_f32_e32 v164, v159, v159
	v_fmac_f32_e32 v125, v120, v120
	v_fmac_f32_e32 v163, v160, v160
	v_add_f32_e32 v114, v114, v115
	v_add_f32_e32 v115, v157, v162
	v_fmac_f32_e32 v127, v122, v122
	v_fmac_f32_e32 v164, v158, v158
	v_add_f32_e32 v114, v125, v114
	v_add_f32_e32 v115, v163, v115
	v_add_f32_e32 v114, v127, v114
	v_add_f32_e32 v115, v164, v115
	v_add_f32_e32 v124, v114, v115
	v_mov_b32_e32 v125, v124
	s_nop 1
	v_permlane16_swap_b32_e32 v125, v124
	v_cvt_pk_bf16_f32 v114, v120, v121
	v_cvt_pk_bf16_f32 v115, v122, v123
	global_store_dwordx4 v[166:167], v[112:115], off
	s_waitcnt lgkmcnt(0)
	s_nop 0
	v_add_f32_e32 v112, v124, v125
	v_mov_b32_e32 v113, v112
	s_nop 1
	v_permlane32_swap_b32_e32 v113, v112
	v_cvt_pk_bf16_f32 v114, v116, v117
	v_cvt_pk_bf16_f32 v115, v118, v119
	v_cvt_pk_bf16_f32 v116, v160, v161
	v_cvt_pk_bf16_f32 v117, v158, v159
	global_store_dwordx4 v[166:167], v[114:117], off offset:256
	s_and_saveexec_b64 s[50:51], s[10:11]
	s_cbranch_execz .LBB0_1202
	s_waitcnt lgkmcnt(0)
	v_add_f32_e32 v112, v112, v113
	v_mul_f32_e32 v112, 0x4f800000, v112
	v_trunc_f32_e32 v112, v112
	v_mul_f32_e64 v113, |v112|, s66
	v_floor_f32_e32 v113, v113
	v_fma_f32 v114, v113, s67, |v112|
	v_cvt_u32_f32_e32 v112, v114
	v_cvt_u32_f32_e32 v113, v113
	v_lshl_add_u64 v[114:115], v[146:147], 3, s[36:37]
	global_atomic_add_x2 v[114:115], v[112:113], off
.LBB0_1202:
	s_or_b64 exec, exec, s[50:51]
	v_or_b32_e32 v112, 16, v146
	s_waitcnt lgkmcnt(0)
	v_ashrrev_i32_e32 v113, 31, v112
	v_lshlrev_b64 v[114:115], 11, v[112:113]
	v_lshl_add_u64 v[114:115], s[22:23], 0, v[114:115]
	v_lshl_add_u64 v[122:123], v[144:145], 1, v[114:115]
	global_load_dwordx4 v[114:117], v[122:123], off
	global_load_dwordx4 v[118:121], v[122:123], off offset:256
	s_waitcnt vmcnt(1)
	v_lshlrev_b32_e32 v124, 16, v114
	v_and_b32_e32 v125, 0xffff0000, v114
	v_lshlrev_b32_e32 v114, 16, v115
	v_and_b32_e32 v115, 0xffff0000, v115
	s_waitcnt vmcnt(0)
	v_lshlrev_b32_e32 v158, 16, v118
	v_and_b32_e32 v159, 0xffff0000, v118
	v_lshlrev_b32_e32 v118, 16, v119
	v_and_b32_e32 v119, 0xffff0000, v119
	v_lshlrev_b32_e32 v126, 16, v116
	v_and_b32_e32 v127, 0xffff0000, v116
	v_lshlrev_b32_e32 v116, 16, v117
	v_and_b32_e32 v117, 0xffff0000, v117
	v_lshlrev_b32_e32 v160, 16, v120
	v_and_b32_e32 v161, 0xffff0000, v120
	v_lshlrev_b32_e32 v120, 16, v121
	v_and_b32_e32 v121, 0xffff0000, v121
	v_pk_fma_f32 v[110:111], v[110:111], 0.5, v[114:115] op_sel_hi:[1,0,1]
	v_pk_fma_f32 v[108:109], v[108:109], 0.5, v[124:125] op_sel_hi:[1,0,1]
	v_pk_fma_f32 v[102:103], v[102:103], 0.5, v[118:119] op_sel_hi:[1,0,1]
	v_pk_fma_f32 v[100:101], v[100:101], 0.5, v[158:159] op_sel_hi:[1,0,1]
	v_pk_fma_f32 v[106:107], v[106:107], 0.5, v[116:117] op_sel_hi:[1,0,1]
	v_pk_fma_f32 v[104:105], v[104:105], 0.5, v[126:127] op_sel_hi:[1,0,1]
	v_pk_fma_f32 v[114:115], v[98:99], 0.5, v[120:121] op_sel_hi:[1,0,1]
	v_pk_fma_f32 v[116:117], v[96:97], 0.5, v[160:161] op_sel_hi:[1,0,1]
	v_mul_f32_e32 v98, v109, v109
	v_mul_f32_e32 v99, v111, v111
	v_mul_f32_e32 v118, v101, v101
	v_mul_f32_e32 v119, v103, v103
	v_cvt_pk_bf16_f32 v96, v108, v109
	v_mul_f32_e32 v109, v105, v105
	v_mul_f32_e32 v120, v117, v117
	v_fmac_f32_e32 v98, v108, v108
	v_fmac_f32_e32 v99, v110, v110
	v_fmac_f32_e32 v118, v100, v100
	v_fmac_f32_e32 v119, v102, v102
	v_cvt_pk_bf16_f32 v97, v110, v111
	v_mul_f32_e32 v111, v107, v107
	v_mul_f32_e32 v121, v115, v115
	v_fmac_f32_e32 v109, v104, v104
	v_fmac_f32_e32 v120, v116, v116
	v_add_f32_e32 v98, v98, v99
	v_add_f32_e32 v99, v118, v119
	v_fmac_f32_e32 v111, v106, v106
	v_fmac_f32_e32 v121, v114, v114
	v_add_f32_e32 v98, v109, v98
	v_add_f32_e32 v99, v120, v99
	v_add_f32_e32 v98, v111, v98
	v_add_f32_e32 v99, v121, v99
	v_add_f32_e32 v108, v98, v99
	v_mov_b32_e32 v109, v108
	s_nop 1
	v_permlane16_swap_b32_e32 v109, v108
	v_cvt_pk_bf16_f32 v98, v104, v105
	v_cvt_pk_bf16_f32 v99, v106, v107
	global_store_dwordx4 v[122:123], v[96:99], off
	s_waitcnt lgkmcnt(0)
	s_nop 0
	v_add_f32_e32 v96, v108, v109
	v_mov_b32_e32 v97, v96
	s_nop 1
	v_permlane32_swap_b32_e32 v97, v96
	v_cvt_pk_bf16_f32 v98, v100, v101
	v_cvt_pk_bf16_f32 v99, v102, v103
	v_cvt_pk_bf16_f32 v100, v116, v117
	v_cvt_pk_bf16_f32 v101, v114, v115
	global_store_dwordx4 v[122:123], v[98:101], off offset:256
	s_and_saveexec_b64 s[50:51], s[10:11]
	s_cbranch_execz .LBB0_1204
	s_waitcnt lgkmcnt(0)
	v_add_f32_e32 v96, v96, v97
	v_mul_f32_e32 v96, 0x4f800000, v96
	v_trunc_f32_e32 v96, v96
	v_mul_f32_e64 v97, |v96|, s66
	v_floor_f32_e32 v97, v97
	v_fma_f32 v98, v97, s67, |v96|
	v_cvt_u32_f32_e32 v96, v98
	v_cvt_u32_f32_e32 v97, v97
	v_lshl_add_u64 v[98:99], v[112:113], 3, s[36:37]
	global_atomic_add_x2 v[98:99], v[96:97], off
; __device__ __forceinline__ unsigned cvtpk(float lo, float hi) { f32x2v_ v = {lo, hi}; bf16x2v_ b = __builtin_convertvector(v, bf16x2v_); return __builtin_bit_cast(unsigned, b); }
; __device__ __forceinline__ void fx_add(float* p, size_t idx, float s) { atomicAdd((unsigned long long*)p + idx, (unsigned long long)(long long)(s * 4294967296.0f)); }
;     __device__ __forceinline__ void operator()(const f32x4 (&acc)[2][2][4][2], const Unit& u, int wr, int wc, int fr, int fq) const {
;     ...
;             for (int m = 0; m < 4; ++m) { const int row = row0 + ai * HALF + m * 16; const size_t off = (size_t)row * 1024 + col0; float s = 0.f;
; #pragma unroll
;                 for (int bj = 0; bj < 2; ++bj) { f32x4 a0, a1;
;                     if (xin32) { const float* p = xin32 + off + bj * HALF; a0 = *(const f32x4*)p; a1 = *(const f32x4*)(p + 4); }
;                     else { const u32x4 w = *(const u32x4*)(xb + off + bj * HALF);
;                         a0 = (f32x4){__uint_as_float(w.x << 16), __uint_as_float(w.x & 0xffff0000u), __uint_as_float(w.y << 16), __uint_as_float(w.y & 0xffff0000u)};
;                         a1 = (f32x4){__uint_as_float(w.z << 16), __uint_as_float(w.z & 0xffff0000u), __uint_as_float(w.w << 16), __uint_as_float(w.w & 0xffff0000u)}; }
;                     const f32x4 v0 = a0 + acc[ai][bj][m][0] * alpha, v1 = a1 + acc[ai][bj][m][1] * alpha;
;                     u32x4 w; w.x = cvtpk(v0[0], v0[1]); w.y = cvtpk(v0[2], v0[3]); w.z = cvtpk(v1[0], v1[1]); w.w = cvtpk(v1[2], v1[3]);
;                     *(u32x4*)(xb + off + bj * HALF) = w;
;                     s += (v0[0] * v0[0] + v0[1] * v0[1]) + (v0[2] * v0[2] + v0[3] * v0[3]) + (v1[0] * v1[0] + v1[1] * v1[1]) + (v1[2] * v1[2] + v1[3] * v1[3]); }
;                 s += __shfl_xor(s, 16); s += __shfl_xor(s, 32);
;                 if (fq == 0) fx_add(ssout, row, s); }
.LBB0_1204:
	s_or_b64 exec, exec, s[50:51]
	v_or_b32_e32 v96, 32, v146
	s_waitcnt lgkmcnt(0)
	v_ashrrev_i32_e32 v97, 31, v96
	v_lshlrev_b64 v[98:99], 11, v[96:97]
	v_lshl_add_u64 v[98:99], s[22:23], 0, v[98:99]
	v_lshl_add_u64 v[106:107], v[144:145], 1, v[98:99]
	global_load_dwordx4 v[98:101], v[106:107], off
	global_load_dwordx4 v[102:105], v[106:107], off offset:256
	s_waitcnt vmcnt(1)
	v_lshlrev_b32_e32 v108, 16, v98
	v_and_b32_e32 v109, 0xffff0000, v98
	v_lshlrev_b32_e32 v98, 16, v99
	v_and_b32_e32 v99, 0xffff0000, v99
	s_waitcnt vmcnt(0)
	v_lshlrev_b32_e32 v112, 16, v102
	v_and_b32_e32 v113, 0xffff0000, v102
	v_lshlrev_b32_e32 v102, 16, v103
	v_and_b32_e32 v103, 0xffff0000, v103
	v_lshlrev_b32_e32 v110, 16, v100
	v_and_b32_e32 v111, 0xffff0000, v100
	v_lshlrev_b32_e32 v100, 16, v101
	v_and_b32_e32 v101, 0xffff0000, v101
	v_lshlrev_b32_e32 v114, 16, v104
	v_and_b32_e32 v115, 0xffff0000, v104
	v_lshlrev_b32_e32 v104, 16, v105
	v_and_b32_e32 v105, 0xffff0000, v105
	v_pk_fma_f32 v[94:95], v[94:95], 0.5, v[98:99] op_sel_hi:[1,0,1]
	v_pk_fma_f32 v[92:93], v[92:93], 0.5, v[108:109] op_sel_hi:[1,0,1]
	v_pk_fma_f32 v[86:87], v[86:87], 0.5, v[102:103] op_sel_hi:[1,0,1]
	v_pk_fma_f32 v[84:85], v[84:85], 0.5, v[112:113] op_sel_hi:[1,0,1]
	v_pk_fma_f32 v[90:91], v[90:91], 0.5, v[100:101] op_sel_hi:[1,0,1]
	v_pk_fma_f32 v[88:89], v[88:89], 0.5, v[110:111] op_sel_hi:[1,0,1]
	v_pk_fma_f32 v[98:99], v[82:83], 0.5, v[104:105] op_sel_hi:[1,0,1]
	v_pk_fma_f32 v[100:101], v[80:81], 0.5, v[114:115] op_sel_hi:[1,0,1]
	v_mul_f32_e32 v82, v93, v93
	v_mul_f32_e32 v83, v95, v95
	v_mul_f32_e32 v102, v85, v85
	v_mul_f32_e32 v103, v87, v87
	v_cvt_pk_bf16_f32 v80, v92, v93
	v_mul_f32_e32 v93, v89, v89
	v_mul_f32_e32 v104, v101, v101
	v_fmac_f32_e32 v82, v92, v92
	v_fmac_f32_e32 v83, v94, v94
	v_fmac_f32_e32 v102, v84, v84
	v_fmac_f32_e32 v103, v86, v86
	v_cvt_pk_bf16_f32 v81, v94, v95
	v_mul_f32_e32 v95, v91, v91
	v_mul_f32_e32 v105, v99, v99
	v_fmac_f32_e32 v93, v88, v88
	v_fmac_f32_e32 v104, v100, v100
	v_add_f32_e32 v82, v82, v83
	v_add_f32_e32 v83, v102, v103
	v_fmac_f32_e32 v95, v90, v90
	v_fmac_f32_e32 v105, v98, v98
	v_add_f32_e32 v82, v93, v82
	v_add_f32_e32 v83, v104, v83
	v_add_f32_e32 v82, v95, v82
	v_add_f32_e32 v83, v105, v83
	v_add_f32_e32 v92, v82, v83
	v_mov_b32_e32 v93, v92
	s_nop 1
	v_permlane16_swap_b32_e32 v93, v92
	v_cvt_pk_bf16_f32 v82, v88, v89
	v_cvt_pk_bf16_f32 v83, v90, v91
	global_store_dwordx4 v[106:107], v[80:83], off
	s_waitcnt lgkmcnt(0)
	s_nop 0
	v_add_f32_e32 v80, v92, v93
	v_mov_b32_e32 v81, v80
	s_nop 1
	v_permlane32_swap_b32_e32 v81, v80
	v_cvt_pk_bf16_f32 v82, v84, v85
	v_cvt_pk_bf16_f32 v83, v86, v87
	v_cvt_pk_bf16_f32 v84, v100, v101
	v_cvt_pk_bf16_f32 v85, v98, v99
	global_store_dwordx4 v[106:107], v[82:85], off offset:256
	s_and_saveexec_b64 s[50:51], s[10:11]
	s_cbranch_execz .LBB0_1206
	s_waitcnt lgkmcnt(0)
	v_add_f32_e32 v80, v80, v81
	v_mul_f32_e32 v80, 0x4f800000, v80
	v_trunc_f32_e32 v80, v80
	v_mul_f32_e64 v81, |v80|, s66
	v_floor_f32_e32 v81, v81
	v_fma_f32 v82, v81, s67, |v80|
	v_cvt_u32_f32_e32 v80, v82
	v_cvt_u32_f32_e32 v81, v81
	v_lshl_add_u64 v[82:83], v[96:97], 3, s[36:37]
	global_atomic_add_x2 v[82:83], v[80:81], off
.LBB0_1206:
	s_or_b64 exec, exec, s[50:51]
	v_or_b32_e32 v80, 48, v146
	s_waitcnt lgkmcnt(0)
	v_ashrrev_i32_e32 v81, 31, v80
	v_lshlrev_b64 v[82:83], 11, v[80:81]
	v_lshl_add_u64 v[82:83], s[22:23], 0, v[82:83]
	v_lshl_add_u64 v[90:91], v[144:145], 1, v[82:83]
	global_load_dwordx4 v[82:85], v[90:91], off
	global_load_dwordx4 v[86:89], v[90:91], off offset:256
	s_waitcnt vmcnt(1)
	v_lshlrev_b32_e32 v92, 16, v82
	v_and_b32_e32 v93, 0xffff0000, v82
	v_lshlrev_b32_e32 v82, 16, v83
	v_and_b32_e32 v83, 0xffff0000, v83
	s_waitcnt vmcnt(0)
	v_lshlrev_b32_e32 v96, 16, v86
	v_and_b32_e32 v97, 0xffff0000, v86
	v_lshlrev_b32_e32 v86, 16, v87
	v_and_b32_e32 v87, 0xffff0000, v87
	v_lshlrev_b32_e32 v94, 16, v84
	v_and_b32_e32 v95, 0xffff0000, v84
	v_lshlrev_b32_e32 v84, 16, v85
	v_and_b32_e32 v85, 0xffff0000, v85
	v_lshlrev_b32_e32 v98, 16, v88
	v_and_b32_e32 v99, 0xffff0000, v88
	v_lshlrev_b32_e32 v88, 16, v89
	v_and_b32_e32 v89, 0xffff0000, v89
	v_pk_fma_f32 v[78:79], v[78:79], 0.5, v[82:83] op_sel_hi:[1,0,1]
	v_pk_fma_f32 v[76:77], v[76:77], 0.5, v[92:93] op_sel_hi:[1,0,1]
	v_pk_fma_f32 v[70:71], v[70:71], 0.5, v[86:87] op_sel_hi:[1,0,1]
	v_pk_fma_f32 v[68:69], v[68:69], 0.5, v[96:97] op_sel_hi:[1,0,1]
	v_pk_fma_f32 v[74:75], v[74:75], 0.5, v[84:85] op_sel_hi:[1,0,1]
	v_pk_fma_f32 v[72:73], v[72:73], 0.5, v[94:95] op_sel_hi:[1,0,1]
	v_pk_fma_f32 v[82:83], v[66:67], 0.5, v[88:89] op_sel_hi:[1,0,1]
	v_pk_fma_f32 v[84:85], v[64:65], 0.5, v[98:99] op_sel_hi:[1,0,1]
	v_mul_f32_e32 v66, v77, v77
	v_mul_f32_e32 v67, v79, v79
	v_mul_f32_e32 v86, v69, v69
	v_mul_f32_e32 v87, v71, v71
	v_cvt_pk_bf16_f32 v64, v76, v77
	v_mul_f32_e32 v77, v73, v73
	v_mul_f32_e32 v88, v85, v85
	v_fmac_f32_e32 v66, v76, v76
	v_fmac_f32_e32 v67, v78, v78
	v_fmac_f32_e32 v86, v68, v68
	v_fmac_f32_e32 v87, v70, v70
	v_cvt_pk_bf16_f32 v65, v78, v79
	v_mul_f32_e32 v79, v75, v75
	v_mul_f32_e32 v89, v83, v83
	v_fmac_f32_e32 v77, v72, v72
	v_fmac_f32_e32 v88, v84, v84
	v_add_f32_e32 v66, v66, v67
	v_add_f32_e32 v67, v86, v87
	v_fmac_f32_e32 v79, v74, v74
	v_fmac_f32_e32 v89, v82, v82
	v_add_f32_e32 v66, v77, v66
	v_add_f32_e32 v67, v88, v67
	v_add_f32_e32 v66, v79, v66
	v_add_f32_e32 v67, v89, v67
	v_add_f32_e32 v76, v66, v67
	v_mov_b32_e32 v77, v76
	s_nop 1
	v_permlane16_swap_b32_e32 v77, v76
	v_cvt_pk_bf16_f32 v66, v72, v73
	v_cvt_pk_bf16_f32 v67, v74, v75
	global_store_dwordx4 v[90:91], v[64:67], off
	s_waitcnt lgkmcnt(0)
	s_nop 0
	v_add_f32_e32 v64, v76, v77
	v_mov_b32_e32 v65, v64
	s_nop 1
	v_permlane32_swap_b32_e32 v65, v64
	v_cvt_pk_bf16_f32 v66, v68, v69
	v_cvt_pk_bf16_f32 v67, v70, v71
	v_cvt_pk_bf16_f32 v68, v84, v85
	v_cvt_pk_bf16_f32 v69, v82, v83
	global_store_dwordx4 v[90:91], v[66:69], off offset:256
	s_and_saveexec_b64 s[50:51], s[10:11]
	s_cbranch_execz .LBB0_1208
	s_waitcnt lgkmcnt(0)
	v_add_f32_e32 v64, v64, v65
	v_mul_f32_e32 v64, 0x4f800000, v64
	v_trunc_f32_e32 v64, v64
	v_mul_f32_e64 v65, |v64|, s66
	v_floor_f32_e32 v65, v65
	v_fma_f32 v66, v65, s67, |v64|
	v_cvt_u32_f32_e32 v64, v66
	v_cvt_u32_f32_e32 v65, v65
	v_lshl_add_u64 v[66:67], v[80:81], 3, s[36:37]
	global_atomic_add_x2 v[66:67], v[64:65], off
; __device__ __forceinline__ unsigned cvtpk(float lo, float hi) { f32x2v_ v = {lo, hi}; bf16x2v_ b = __builtin_convertvector(v, bf16x2v_); return __builtin_bit_cast(unsigned, b); }
; __device__ __forceinline__ void fx_add(float* p, size_t idx, float s) { atomicAdd((unsigned long long*)p + idx, (unsigned long long)(long long)(s * 4294967296.0f)); }
;     __device__ __forceinline__ void operator()(const f32x4 (&acc)[2][2][4][2], const Unit& u, int wr, int wc, int fr, int fq) const {
;     ...
;             for (int m = 0; m < 4; ++m) { const int row = row0 + ai * HALF + m * 16; const size_t off = (size_t)row * 1024 + col0; float s = 0.f;
; #pragma unroll
;                 for (int bj = 0; bj < 2; ++bj) { f32x4 a0, a1;
;                     if (xin32) { const float* p = xin32 + off + bj * HALF; a0 = *(const f32x4*)p; a1 = *(const f32x4*)(p + 4); }
;                     else { const u32x4 w = *(const u32x4*)(xb + off + bj * HALF);
;                         a0 = (f32x4){__uint_as_float(w.x << 16), __uint_as_float(w.x & 0xffff0000u), __uint_as_float(w.y << 16), __uint_as_float(w.y & 0xffff0000u)};
;                         a1 = (f32x4){__uint_as_float(w.z << 16), __uint_as_float(w.z & 0xffff0000u), __uint_as_float(w.w << 16), __uint_as_float(w.w & 0xffff0000u)}; }
;                     const f32x4 v0 = a0 + acc[ai][bj][m][0] * alpha, v1 = a1 + acc[ai][bj][m][1] * alpha;
;                     u32x4 w; w.x = cvtpk(v0[0], v0[1]); w.y = cvtpk(v0[2], v0[3]); w.z = cvtpk(v1[0], v1[1]); w.w = cvtpk(v1[2], v1[3]);
;                     *(u32x4*)(xb + off + bj * HALF) = w;
;                     s += (v0[0] * v0[0] + v0[1] * v0[1]) + (v0[2] * v0[2] + v0[3] * v0[3]) + (v1[0] * v1[0] + v1[1] * v1[1]) + (v1[2] * v1[2] + v1[3] * v1[3]); }
;                 s += __shfl_xor(s, 16); s += __shfl_xor(s, 32);
;                 if (fq == 0) fx_add(ssout, row, s); }
.LBB0_1208:
	s_or_b64 exec, exec, s[50:51]
	v_add_u32_e32 v64, 0x80, v146
	s_waitcnt lgkmcnt(0)
	v_ashrrev_i32_e32 v65, 31, v64
	v_lshlrev_b64 v[66:67], 11, v[64:65]
	v_lshl_add_u64 v[66:67], s[22:23], 0, v[66:67]
	v_lshl_add_u64 v[74:75], v[144:145], 1, v[66:67]
	global_load_dwordx4 v[66:69], v[74:75], off
	global_load_dwordx4 v[70:73], v[74:75], off offset:256
	s_waitcnt vmcnt(1)
	v_lshlrev_b32_e32 v76, 16, v66
	v_and_b32_e32 v77, 0xffff0000, v66
	v_lshlrev_b32_e32 v66, 16, v67
	v_and_b32_e32 v67, 0xffff0000, v67
	s_waitcnt vmcnt(0)
	v_lshlrev_b32_e32 v80, 16, v70
	v_and_b32_e32 v81, 0xffff0000, v70
	v_lshlrev_b32_e32 v70, 16, v71
	v_and_b32_e32 v71, 0xffff0000, v71
	v_lshlrev_b32_e32 v78, 16, v68
	v_and_b32_e32 v79, 0xffff0000, v68
	v_lshlrev_b32_e32 v68, 16, v69
	v_and_b32_e32 v69, 0xffff0000, v69
	v_lshlrev_b32_e32 v82, 16, v72
	v_and_b32_e32 v83, 0xffff0000, v72
	v_lshlrev_b32_e32 v72, 16, v73
	v_and_b32_e32 v73, 0xffff0000, v73
	v_pk_fma_f32 v[62:63], v[62:63], 0.5, v[66:67] op_sel_hi:[1,0,1]
	v_pk_fma_f32 v[60:61], v[60:61], 0.5, v[76:77] op_sel_hi:[1,0,1]
	v_pk_fma_f32 v[54:55], v[54:55], 0.5, v[70:71] op_sel_hi:[1,0,1]
	v_pk_fma_f32 v[52:53], v[52:53], 0.5, v[80:81] op_sel_hi:[1,0,1]
	v_pk_fma_f32 v[58:59], v[58:59], 0.5, v[68:69] op_sel_hi:[1,0,1]
	v_pk_fma_f32 v[56:57], v[56:57], 0.5, v[78:79] op_sel_hi:[1,0,1]
	v_pk_fma_f32 v[66:67], v[50:51], 0.5, v[72:73] op_sel_hi:[1,0,1]
	v_pk_fma_f32 v[68:69], v[48:49], 0.5, v[82:83] op_sel_hi:[1,0,1]
	v_mul_f32_e32 v50, v61, v61
	v_mul_f32_e32 v51, v63, v63
	v_mul_f32_e32 v70, v53, v53
	v_mul_f32_e32 v71, v55, v55
	v_cvt_pk_bf16_f32 v48, v60, v61
	v_mul_f32_e32 v61, v57, v57
	v_mul_f32_e32 v72, v69, v69
	v_fmac_f32_e32 v50, v60, v60
	v_fmac_f32_e32 v51, v62, v62
	v_fmac_f32_e32 v70, v52, v52
	v_fmac_f32_e32 v71, v54, v54
	v_cvt_pk_bf16_f32 v49, v62, v63
	v_mul_f32_e32 v63, v59, v59
	v_mul_f32_e32 v73, v67, v67
	v_fmac_f32_e32 v61, v56, v56
	v_fmac_f32_e32 v72, v68, v68
	v_add_f32_e32 v50, v50, v51
	v_add_f32_e32 v51, v70, v71
	v_fmac_f32_e32 v63, v58, v58
	v_fmac_f32_e32 v73, v66, v66
	v_add_f32_e32 v50, v61, v50
	v_add_f32_e32 v51, v72, v51
	v_add_f32_e32 v50, v63, v50
	v_add_f32_e32 v51, v73, v51
	v_add_f32_e32 v60, v50, v51
	v_mov_b32_e32 v61, v60
	s_nop 1
	v_permlane16_swap_b32_e32 v61, v60
	v_cvt_pk_bf16_f32 v50, v56, v57
	v_cvt_pk_bf16_f32 v51, v58, v59
	global_store_dwordx4 v[74:75], v[48:51], off
	s_waitcnt lgkmcnt(0)
	s_nop 0
	v_add_f32_e32 v48, v60, v61
	v_mov_b32_e32 v49, v48
	s_nop 1
	v_permlane32_swap_b32_e32 v49, v48
	v_cvt_pk_bf16_f32 v50, v52, v53
	v_cvt_pk_bf16_f32 v51, v54, v55
	v_cvt_pk_bf16_f32 v52, v68, v69
	v_cvt_pk_bf16_f32 v53, v66, v67
	global_store_dwordx4 v[74:75], v[50:53], off offset:256
	s_and_saveexec_b64 s[50:51], s[10:11]
	s_cbranch_execz .LBB0_1210
	s_waitcnt lgkmcnt(0)
	v_add_f32_e32 v48, v48, v49
	v_mul_f32_e32 v48, 0x4f800000, v48
	v_trunc_f32_e32 v48, v48
	v_mul_f32_e64 v49, |v48|, s66
	v_floor_f32_e32 v49, v49
	v_fma_f32 v50, v49, s67, |v48|
	v_cvt_u32_f32_e32 v48, v50
	v_cvt_u32_f32_e32 v49, v49
	v_lshl_add_u64 v[50:51], v[64:65], 3, s[36:37]
	global_atomic_add_x2 v[50:51], v[48:49], off
.LBB0_1210:
	s_or_b64 exec, exec, s[50:51]
	v_add_u32_e32 v48, 0x90, v146
	s_waitcnt lgkmcnt(0)
	v_ashrrev_i32_e32 v49, 31, v48
	v_lshlrev_b64 v[50:51], 11, v[48:49]
	v_lshl_add_u64 v[50:51], s[22:23], 0, v[50:51]
	v_lshl_add_u64 v[58:59], v[144:145], 1, v[50:51]
	global_load_dwordx4 v[50:53], v[58:59], off
	global_load_dwordx4 v[54:57], v[58:59], off offset:256
	s_waitcnt vmcnt(1)
	v_lshlrev_b32_e32 v60, 16, v50
	v_and_b32_e32 v61, 0xffff0000, v50
	v_lshlrev_b32_e32 v50, 16, v51
	v_and_b32_e32 v51, 0xffff0000, v51
	s_waitcnt vmcnt(0)
	v_lshlrev_b32_e32 v64, 16, v54
	v_and_b32_e32 v65, 0xffff0000, v54
	v_lshlrev_b32_e32 v54, 16, v55
	v_and_b32_e32 v55, 0xffff0000, v55
	v_lshlrev_b32_e32 v62, 16, v52
	v_and_b32_e32 v63, 0xffff0000, v52
	v_lshlrev_b32_e32 v52, 16, v53
	v_and_b32_e32 v53, 0xffff0000, v53
	v_lshlrev_b32_e32 v66, 16, v56
	v_and_b32_e32 v67, 0xffff0000, v56
	v_lshlrev_b32_e32 v56, 16, v57
	v_and_b32_e32 v57, 0xffff0000, v57
	v_pk_fma_f32 v[46:47], v[46:47], 0.5, v[50:51] op_sel_hi:[1,0,1]
	v_pk_fma_f32 v[44:45], v[44:45], 0.5, v[60:61] op_sel_hi:[1,0,1]
	v_pk_fma_f32 v[38:39], v[38:39], 0.5, v[54:55] op_sel_hi:[1,0,1]
	v_pk_fma_f32 v[36:37], v[36:37], 0.5, v[64:65] op_sel_hi:[1,0,1]
	v_pk_fma_f32 v[42:43], v[42:43], 0.5, v[52:53] op_sel_hi:[1,0,1]
	v_pk_fma_f32 v[40:41], v[40:41], 0.5, v[62:63] op_sel_hi:[1,0,1]
	v_pk_fma_f32 v[50:51], v[34:35], 0.5, v[56:57] op_sel_hi:[1,0,1]
	v_pk_fma_f32 v[52:53], v[32:33], 0.5, v[66:67] op_sel_hi:[1,0,1]
	v_mul_f32_e32 v34, v45, v45
	v_mul_f32_e32 v35, v47, v47
	v_mul_f32_e32 v54, v37, v37
	v_mul_f32_e32 v55, v39, v39
	v_cvt_pk_bf16_f32 v32, v44, v45
	v_mul_f32_e32 v45, v41, v41
	v_mul_f32_e32 v56, v53, v53
	v_fmac_f32_e32 v34, v44, v44
	v_fmac_f32_e32 v35, v46, v46
	v_fmac_f32_e32 v54, v36, v36
	v_fmac_f32_e32 v55, v38, v38
	v_cvt_pk_bf16_f32 v33, v46, v47
	v_mul_f32_e32 v47, v43, v43
	v_mul_f32_e32 v57, v51, v51
	v_fmac_f32_e32 v45, v40, v40
	v_fmac_f32_e32 v56, v52, v52
	v_add_f32_e32 v34, v34, v35
	v_add_f32_e32 v35, v54, v55
	v_fmac_f32_e32 v47, v42, v42
	v_fmac_f32_e32 v57, v50, v50
	v_add_f32_e32 v34, v45, v34
	v_add_f32_e32 v35, v56, v35
	v_add_f32_e32 v34, v47, v34
	v_add_f32_e32 v35, v57, v35
	v_add_f32_e32 v44, v34, v35
	v_mov_b32_e32 v45, v44
	s_nop 1
	v_permlane16_swap_b32_e32 v45, v44
	v_cvt_pk_bf16_f32 v34, v40, v41
	v_cvt_pk_bf16_f32 v35, v42, v43
	global_store_dwordx4 v[58:59], v[32:35], off
	s_waitcnt lgkmcnt(0)
	s_nop 0
	v_add_f32_e32 v32, v44, v45
	v_mov_b32_e32 v33, v32
	s_nop 1
	v_permlane32_swap_b32_e32 v33, v32
	v_cvt_pk_bf16_f32 v34, v36, v37
	v_cvt_pk_bf16_f32 v35, v38, v39
	v_cvt_pk_bf16_f32 v36, v52, v53
	v_cvt_pk_bf16_f32 v37, v50, v51
	global_store_dwordx4 v[58:59], v[34:37], off offset:256
	s_and_saveexec_b64 s[50:51], s[10:11]
	s_cbranch_execz .LBB0_1212
	s_waitcnt lgkmcnt(0)
	v_add_f32_e32 v32, v32, v33
	v_mul_f32_e32 v32, 0x4f800000, v32
	v_trunc_f32_e32 v32, v32
	v_mul_f32_e64 v33, |v32|, s66
	v_floor_f32_e32 v33, v33
	v_fma_f32 v34, v33, s67, |v32|
	v_cvt_u32_f32_e32 v32, v34
	v_cvt_u32_f32_e32 v33, v33
	v_lshl_add_u64 v[34:35], v[48:49], 3, s[36:37]
	global_atomic_add_x2 v[34:35], v[32:33], off
; __device__ __forceinline__ unsigned cvtpk(float lo, float hi) { f32x2v_ v = {lo, hi}; bf16x2v_ b = __builtin_convertvector(v, bf16x2v_); return __builtin_bit_cast(unsigned, b); }
; __device__ __forceinline__ void fx_add(float* p, size_t idx, float s) { atomicAdd((unsigned long long*)p + idx, (unsigned long long)(long long)(s * 4294967296.0f)); }
;     __device__ __forceinline__ void operator()(const f32x4 (&acc)[2][2][4][2], const Unit& u, int wr, int wc, int fr, int fq) const {
;     ...
;             for (int m = 0; m < 4; ++m) { const int row = row0 + ai * HALF + m * 16; const size_t off = (size_t)row * 1024 + col0; float s = 0.f;
; #pragma unroll
;                 for (int bj = 0; bj < 2; ++bj) { f32x4 a0, a1;
;                     if (xin32) { const float* p = xin32 + off + bj * HALF; a0 = *(const f32x4*)p; a1 = *(const f32x4*)(p + 4); }
;                     else { const u32x4 w = *(const u32x4*)(xb + off + bj * HALF);
;                         a0 = (f32x4){__uint_as_float(w.x << 16), __uint_as_float(w.x & 0xffff0000u), __uint_as_float(w.y << 16), __uint_as_float(w.y & 0xffff0000u)};
;                         a1 = (f32x4){__uint_as_float(w.z << 16), __uint_as_float(w.z & 0xffff0000u), __uint_as_float(w.w << 16), __uint_as_float(w.w & 0xffff0000u)}; }
;                     const f32x4 v0 = a0 + acc[ai][bj][m][0] * alpha, v1 = a1 + acc[ai][bj][m][1] * alpha;
;                     u32x4 w; w.x = cvtpk(v0[0], v0[1]); w.y = cvtpk(v0[2], v0[3]); w.z = cvtpk(v1[0], v1[1]); w.w = cvtpk(v1[2], v1[3]);
;                     *(u32x4*)(xb + off + bj * HALF) = w;
;                     s += (v0[0] * v0[0] + v0[1] * v0[1]) + (v0[2] * v0[2] + v0[3] * v0[3]) + (v1[0] * v1[0] + v1[1] * v1[1]) + (v1[2] * v1[2] + v1[3] * v1[3]); }
;                 s += __shfl_xor(s, 16); s += __shfl_xor(s, 32);
;                 if (fq == 0) fx_add(ssout, row, s); }
.LBB0_1212:
	s_or_b64 exec, exec, s[50:51]
	v_add_u32_e32 v32, 0xa0, v146
	s_waitcnt lgkmcnt(0)
	v_ashrrev_i32_e32 v33, 31, v32
	v_lshlrev_b64 v[34:35], 11, v[32:33]
	v_lshl_add_u64 v[34:35], s[22:23], 0, v[34:35]
	v_lshl_add_u64 v[42:43], v[144:145], 1, v[34:35]
	global_load_dwordx4 v[34:37], v[42:43], off
	global_load_dwordx4 v[38:41], v[42:43], off offset:256
	s_waitcnt vmcnt(1)
	v_lshlrev_b32_e32 v44, 16, v34
	v_and_b32_e32 v45, 0xffff0000, v34
	v_lshlrev_b32_e32 v34, 16, v35
	v_and_b32_e32 v35, 0xffff0000, v35
	s_waitcnt vmcnt(0)
	v_lshlrev_b32_e32 v48, 16, v38
	v_and_b32_e32 v49, 0xffff0000, v38
	v_lshlrev_b32_e32 v38, 16, v39
	v_and_b32_e32 v39, 0xffff0000, v39
	v_lshlrev_b32_e32 v46, 16, v36
	v_and_b32_e32 v47, 0xffff0000, v36
	v_lshlrev_b32_e32 v36, 16, v37
	v_and_b32_e32 v37, 0xffff0000, v37
	v_lshlrev_b32_e32 v50, 16, v40
	v_and_b32_e32 v51, 0xffff0000, v40
	v_lshlrev_b32_e32 v40, 16, v41
	v_and_b32_e32 v41, 0xffff0000, v41
	v_pk_fma_f32 v[30:31], v[30:31], 0.5, v[34:35] op_sel_hi:[1,0,1]
	v_pk_fma_f32 v[28:29], v[28:29], 0.5, v[44:45] op_sel_hi:[1,0,1]
	v_pk_fma_f32 v[22:23], v[22:23], 0.5, v[38:39] op_sel_hi:[1,0,1]
	v_pk_fma_f32 v[20:21], v[20:21], 0.5, v[48:49] op_sel_hi:[1,0,1]
	v_pk_fma_f32 v[26:27], v[26:27], 0.5, v[36:37] op_sel_hi:[1,0,1]
	v_pk_fma_f32 v[24:25], v[24:25], 0.5, v[46:47] op_sel_hi:[1,0,1]
	v_pk_fma_f32 v[34:35], v[18:19], 0.5, v[40:41] op_sel_hi:[1,0,1]
	v_pk_fma_f32 v[36:37], v[16:17], 0.5, v[50:51] op_sel_hi:[1,0,1]
	v_mul_f32_e32 v18, v29, v29
	v_mul_f32_e32 v19, v31, v31
	v_mul_f32_e32 v38, v21, v21
	v_mul_f32_e32 v39, v23, v23
	v_cvt_pk_bf16_f32 v16, v28, v29
	v_mul_f32_e32 v29, v25, v25
	v_mul_f32_e32 v40, v37, v37
	v_fmac_f32_e32 v18, v28, v28
	v_fmac_f32_e32 v19, v30, v30
	v_fmac_f32_e32 v38, v20, v20
	v_fmac_f32_e32 v39, v22, v22
	v_cvt_pk_bf16_f32 v17, v30, v31
	v_mul_f32_e32 v31, v27, v27
	v_mul_f32_e32 v41, v35, v35
	v_fmac_f32_e32 v29, v24, v24
	v_fmac_f32_e32 v40, v36, v36
	v_add_f32_e32 v18, v18, v19
	v_add_f32_e32 v19, v38, v39
	v_fmac_f32_e32 v31, v26, v26
	v_fmac_f32_e32 v41, v34, v34
	v_add_f32_e32 v18, v29, v18
	v_add_f32_e32 v19, v40, v19
	v_add_f32_e32 v18, v31, v18
	v_add_f32_e32 v19, v41, v19
	v_add_f32_e32 v28, v18, v19
	v_mov_b32_e32 v29, v28
	s_nop 1
	v_permlane16_swap_b32_e32 v29, v28
	v_cvt_pk_bf16_f32 v18, v24, v25
	v_cvt_pk_bf16_f32 v19, v26, v27
	global_store_dwordx4 v[42:43], v[16:19], off
	s_waitcnt lgkmcnt(0)
	s_nop 0
	v_add_f32_e32 v16, v28, v29
	v_mov_b32_e32 v17, v16
	s_nop 1
	v_permlane32_swap_b32_e32 v17, v16
	v_cvt_pk_bf16_f32 v18, v20, v21
	v_cvt_pk_bf16_f32 v19, v22, v23
	v_cvt_pk_bf16_f32 v20, v36, v37
	v_cvt_pk_bf16_f32 v21, v34, v35
	global_store_dwordx4 v[42:43], v[18:21], off offset:256
	s_and_saveexec_b64 s[50:51], s[10:11]
	s_cbranch_execz .LBB0_1214
	s_waitcnt lgkmcnt(0)
	v_add_f32_e32 v16, v16, v17
	v_mul_f32_e32 v16, 0x4f800000, v16
	v_trunc_f32_e32 v16, v16
	v_mul_f32_e64 v17, |v16|, s66
	v_floor_f32_e32 v17, v17
	v_fma_f32 v18, v17, s67, |v16|
	v_cvt_u32_f32_e32 v16, v18
	v_cvt_u32_f32_e32 v17, v17
	v_lshl_add_u64 v[18:19], v[32:33], 3, s[36:37]
	global_atomic_add_x2 v[18:19], v[16:17], off
.LBB0_1214:
	s_or_b64 exec, exec, s[50:51]
	v_add_u32_e32 v16, 0xb0, v146
	s_waitcnt lgkmcnt(0)
	v_ashrrev_i32_e32 v17, 31, v16
	v_lshlrev_b64 v[18:19], 11, v[16:17]
	v_lshl_add_u64 v[18:19], s[22:23], 0, v[18:19]
	v_lshl_add_u64 v[26:27], v[144:145], 1, v[18:19]
	global_load_dwordx4 v[18:21], v[26:27], off
	global_load_dwordx4 v[22:25], v[26:27], off offset:256
	s_waitcnt vmcnt(1)
	v_lshlrev_b32_e32 v28, 16, v18
	v_and_b32_e32 v29, 0xffff0000, v18
	v_lshlrev_b32_e32 v18, 16, v19
	v_and_b32_e32 v19, 0xffff0000, v19
	s_waitcnt vmcnt(0)
	v_lshlrev_b32_e32 v32, 16, v22
	v_and_b32_e32 v33, 0xffff0000, v22
	v_lshlrev_b32_e32 v22, 16, v23
	v_and_b32_e32 v23, 0xffff0000, v23
	v_lshlrev_b32_e32 v30, 16, v20
	v_and_b32_e32 v31, 0xffff0000, v20
	v_lshlrev_b32_e32 v20, 16, v21
	v_and_b32_e32 v21, 0xffff0000, v21
	v_lshlrev_b32_e32 v34, 16, v24
	v_and_b32_e32 v35, 0xffff0000, v24
	v_lshlrev_b32_e32 v24, 16, v25
	v_and_b32_e32 v25, 0xffff0000, v25
	v_pk_fma_f32 v[14:15], v[14:15], 0.5, v[18:19] op_sel_hi:[1,0,1]
	v_pk_fma_f32 v[12:13], v[12:13], 0.5, v[28:29] op_sel_hi:[1,0,1]
	v_pk_fma_f32 v[6:7], v[6:7], 0.5, v[22:23] op_sel_hi:[1,0,1]
	v_pk_fma_f32 v[4:5], v[4:5], 0.5, v[32:33] op_sel_hi:[1,0,1]
	v_pk_fma_f32 v[10:11], v[10:11], 0.5, v[20:21] op_sel_hi:[1,0,1]
	v_pk_fma_f32 v[8:9], v[8:9], 0.5, v[30:31] op_sel_hi:[1,0,1]
	v_pk_fma_f32 v[18:19], v[2:3], 0.5, v[24:25] op_sel_hi:[1,0,1]
	v_pk_fma_f32 v[20:21], v[0:1], 0.5, v[34:35] op_sel_hi:[1,0,1]
	v_mul_f32_e32 v2, v13, v13
	v_mul_f32_e32 v3, v15, v15
	v_mul_f32_e32 v22, v5, v5
	v_mul_f32_e32 v23, v7, v7
	v_cvt_pk_bf16_f32 v0, v12, v13
	v_mul_f32_e32 v13, v9, v9
	v_mul_f32_e32 v24, v21, v21
	v_fmac_f32_e32 v2, v12, v12
	v_fmac_f32_e32 v3, v14, v14
	v_fmac_f32_e32 v22, v4, v4
	v_fmac_f32_e32 v23, v6, v6
	v_cvt_pk_bf16_f32 v1, v14, v15
	v_mul_f32_e32 v15, v11, v11
	v_mul_f32_e32 v25, v19, v19
	v_fmac_f32_e32 v13, v8, v8
	v_fmac_f32_e32 v24, v20, v20
	v_add_f32_e32 v2, v2, v3
	v_add_f32_e32 v3, v22, v23
	v_fmac_f32_e32 v15, v10, v10
	v_fmac_f32_e32 v25, v18, v18
	v_add_f32_e32 v2, v13, v2
	v_add_f32_e32 v3, v24, v3
	v_add_f32_e32 v2, v15, v2
	v_add_f32_e32 v3, v25, v3
	v_add_f32_e32 v12, v2, v3
	v_mov_b32_e32 v13, v12
	s_nop 1
	v_permlane16_swap_b32_e32 v13, v12
	v_cvt_pk_bf16_f32 v2, v8, v9
	v_cvt_pk_bf16_f32 v3, v10, v11
	global_store_dwordx4 v[26:27], v[0:3], off
	s_waitcnt lgkmcnt(0)
	s_nop 0
	v_add_f32_e32 v0, v12, v13
	v_mov_b32_e32 v1, v0
	s_nop 1
	v_permlane32_swap_b32_e32 v1, v0
	v_cvt_pk_bf16_f32 v2, v4, v5
	v_cvt_pk_bf16_f32 v3, v6, v7
	v_cvt_pk_bf16_f32 v4, v20, v21
	v_cvt_pk_bf16_f32 v5, v18, v19
	global_store_dwordx4 v[26:27], v[2:5], off offset:256
	s_and_saveexec_b64 s[50:51], s[10:11]
	s_cbranch_execz .LBB0_1216
	s_waitcnt lgkmcnt(0)
	v_add_f32_e32 v0, v0, v1
	v_mul_f32_e32 v0, 0x4f800000, v0
	v_trunc_f32_e32 v0, v0
	v_mul_f32_e64 v1, |v0|, s66
	v_floor_f32_e32 v1, v1
	v_fma_f32 v2, v1, s67, |v0|
	v_cvt_u32_f32_e32 v0, v2
	v_cvt_u32_f32_e32 v1, v1
	v_lshl_add_u64 v[2:3], v[16:17], 3, s[36:37]
	global_atomic_add_x2 v[2:3], v[0:1], off

; __device__ __forceinline__ unsigned cvtpk(float lo, float hi) { f32x2v_ v = {lo, hi}; bf16x2v_ b = __builtin_convertvector(v, bf16x2v_); return __builtin_bit_cast(unsigned, b); }
; __device__ __forceinline__ void fx_add(float* p, size_t idx, float s) { atomicAdd((unsigned long long*)p + idx, (unsigned long long)(long long)(s * 4294967296.0f)); }
;     __device__ __forceinline__ void operator()(const f32x4 (&acc)[2][2][4][2], const Unit& u, int wr, int wc, int fr, int fq) const {
;         const int row0 = u.pm * BM + wr * 64 + fr, col0 = u.pn * BM + wc * 32 + 8 * fq;
; #pragma unroll
;         for (int ai = 0; ai < 2; ++ai)
; #pragma unroll
;             for (int m = 0; m < 4; ++m) { const int row = row0 + ai * HALF + m * 16; const size_t off = (size_t)row * 1024 + col0; float s = 0.f;
; #pragma unroll
;                 for (int bj = 0; bj < 2; ++bj) { f32x4 a0, a1;
;                     if (xin32) { const float* p = xin32 + off + bj * HALF; a0 = *(const f32x4*)p; a1 = *(const f32x4*)(p + 4); }
;                     else { const u32x4 w = *(const u32x4*)(xb + off + bj * HALF);
;                         a0 = (f32x4){__uint_as_float(w.x << 16), __uint_as_float(w.x & 0xffff0000u), __uint_as_float(w.y << 16), __uint_as_float(w.y & 0xffff0000u)};
;                         a1 = (f32x4){__uint_as_float(w.z << 16), __uint_as_float(w.z & 0xffff0000u), __uint_as_float(w.w << 16), __uint_as_float(w.w & 0xffff0000u)}; }
;                     const f32x4 v0 = a0 + acc[ai][bj][m][0] * alpha, v1 = a1 + acc[ai][bj][m][1] * alpha;
;                     u32x4 w; w.x = cvtpk(v0[0], v0[1]); w.y = cvtpk(v0[2], v0[3]); w.z = cvtpk(v1[0], v1[1]); w.w = cvtpk(v1[2], v1[3]);
;                     *(u32x4*)(xb + off + bj * HALF) = w;
;                     s += (v0[0] * v0[0] + v0[1] * v0[1]) + (v0[2] * v0[2] + v0[3] * v0[3]) + (v1[0] * v1[0] + v1[1] * v1[1]) + (v1[2] * v1[2] + v1[3] * v1[3]); }
;                 s += __shfl_xor(s, 16); s += __shfl_xor(s, 32);
;                 if (fq == 0) fx_add(ssout, row, s); }
.LBB0_1596:
	v_lshl_add_u32 v148, s48, 8, v145
	v_ashrrev_i32_e32 v149, 31, v148
	v_lshl_or_b32 v146, s46, 8, v151
	v_lshlrev_b64 v[156:157], 11, v[148:149]
	v_ashrrev_i32_e32 v147, 31, v146
	v_lshl_add_u64 v[156:157], s[22:23], 0, v[156:157]
	v_lshl_add_u64 v[166:167], v[146:147], 1, v[156:157]
	global_load_dwordx4 v[158:161], v[166:167], off
	global_load_dwordx4 v[162:165], v[166:167], off offset:256
	v_and_b32_e32 v157, 64, v155
	v_xor_b32_e32 v156, 16, v155
	v_add_u32_e32 v157, 64, v157
	v_xor_b32_e32 v168, 32, v155
	v_cmp_lt_i32_e32 vcc, v156, v157
	s_waitcnt vmcnt(0)
	v_and_b32_e32 v169, 0xffff0000, v158
	v_cndmask_b32_e32 v156, v155, v156, vcc
	v_cmp_lt_i32_e32 vcc, v168, v157
	v_lshlrev_b32_e32 v157, 2, v156
	v_lshlrev_b32_e32 v172, 16, v162
	v_cndmask_b32_e32 v168, v155, v168, vcc
	v_lshlrev_b32_e32 v156, 2, v168
	v_lshlrev_b32_e32 v168, 16, v158
	v_lshlrev_b32_e32 v158, 16, v159
	v_and_b32_e32 v159, 0xffff0000, v159
	v_and_b32_e32 v173, 0xffff0000, v162
	v_lshlrev_b32_e32 v162, 16, v163
	v_and_b32_e32 v163, 0xffff0000, v163
	v_lshlrev_b32_e32 v170, 16, v160
	v_and_b32_e32 v171, 0xffff0000, v160
	v_lshlrev_b32_e32 v160, 16, v161
	v_and_b32_e32 v161, 0xffff0000, v161
	v_lshlrev_b32_e32 v174, 16, v164
	v_and_b32_e32 v175, 0xffff0000, v164
	v_lshlrev_b32_e32 v164, 16, v165
	v_and_b32_e32 v165, 0xffff0000, v165
	v_pk_add_f32 v[126:127], v[126:127], v[158:159]
	v_pk_add_f32 v[124:125], v[124:125], v[168:169]
	v_pk_add_f32 v[118:119], v[118:119], v[162:163]
	v_pk_add_f32 v[116:117], v[116:117], v[172:173]
	v_pk_add_f32 v[122:123], v[122:123], v[160:161]
	v_pk_add_f32 v[120:121], v[120:121], v[170:171]
	v_pk_add_f32 v[158:159], v[114:115], v[164:165]
	v_pk_add_f32 v[160:161], v[112:113], v[174:175]
	v_mul_f32_e32 v114, v125, v125
	v_mul_f32_e32 v115, v127, v127
	v_mul_f32_e32 v162, v117, v117
	v_mul_f32_e32 v163, v119, v119
	v_cvt_pk_bf16_f32 v112, v124, v125
	v_mul_f32_e32 v125, v121, v121
	v_mul_f32_e32 v164, v161, v161
	v_fmac_f32_e32 v114, v124, v124
	v_fmac_f32_e32 v115, v126, v126
	v_fmac_f32_e32 v162, v116, v116
	v_fmac_f32_e32 v163, v118, v118
	v_cvt_pk_bf16_f32 v113, v126, v127
	v_mul_f32_e32 v127, v123, v123
	v_mul_f32_e32 v165, v159, v159
	v_fmac_f32_e32 v125, v120, v120
	v_fmac_f32_e32 v164, v160, v160
	v_add_f32_e32 v114, v114, v115
	v_add_f32_e32 v115, v162, v163
	v_fmac_f32_e32 v127, v122, v122
	v_fmac_f32_e32 v165, v158, v158
	v_add_f32_e32 v114, v125, v114
	v_add_f32_e32 v115, v164, v115
	v_add_f32_e32 v114, v127, v114
	v_add_f32_e32 v115, v165, v115
	v_add_f32_e32 v124, v114, v115
	v_mov_b32_e32 v125, v124
	s_nop 1
	v_permlane16_swap_b32_e32 v125, v124
	v_cvt_pk_bf16_f32 v114, v120, v121
	v_cvt_pk_bf16_f32 v115, v122, v123
	global_store_dwordx4 v[166:167], v[112:115], off
	s_waitcnt lgkmcnt(0)
	s_nop 0
	v_add_f32_e32 v112, v124, v125
	v_mov_b32_e32 v113, v112
	s_nop 1
	v_permlane32_swap_b32_e32 v113, v112
	v_cvt_pk_bf16_f32 v114, v116, v117
	v_cvt_pk_bf16_f32 v115, v118, v119
	v_cvt_pk_bf16_f32 v116, v160, v161
	v_cvt_pk_bf16_f32 v117, v158, v159
	global_store_dwordx4 v[166:167], v[114:117], off offset:256
	s_and_saveexec_b64 s[46:47], s[4:5]
	s_cbranch_execz .LBB0_1598
	s_waitcnt lgkmcnt(0)
	v_add_f32_e32 v112, v112, v113
	v_mul_f32_e32 v112, 0x4f800000, v112
	v_trunc_f32_e32 v112, v112
	v_mul_f32_e64 v113, |v112|, s62
	v_floor_f32_e32 v113, v113
	v_fma_f32 v114, v113, s63, |v112|
	v_cvt_u32_f32_e32 v112, v114
	v_cvt_u32_f32_e32 v113, v113
	v_lshl_add_u64 v[114:115], v[148:149], 3, s[12:13]
	global_atomic_add_x2 v[114:115], v[112:113], off
.LBB0_1598:
	s_or_b64 exec, exec, s[46:47]
	v_or_b32_e32 v112, 16, v148
	s_waitcnt lgkmcnt(0)
	v_ashrrev_i32_e32 v113, 31, v112
	v_lshlrev_b64 v[114:115], 11, v[112:113]
	v_lshl_add_u64 v[114:115], s[22:23], 0, v[114:115]
	v_lshl_add_u64 v[122:123], v[146:147], 1, v[114:115]
	global_load_dwordx4 v[114:117], v[122:123], off
	global_load_dwordx4 v[118:121], v[122:123], off offset:256
	s_waitcnt vmcnt(1)
	v_lshlrev_b32_e32 v124, 16, v114
	v_and_b32_e32 v125, 0xffff0000, v114
	v_lshlrev_b32_e32 v114, 16, v115
	v_and_b32_e32 v115, 0xffff0000, v115
	s_waitcnt vmcnt(0)
	v_lshlrev_b32_e32 v158, 16, v118
	v_and_b32_e32 v159, 0xffff0000, v118
	v_lshlrev_b32_e32 v118, 16, v119
	v_and_b32_e32 v119, 0xffff0000, v119
	v_lshlrev_b32_e32 v126, 16, v116
	v_and_b32_e32 v127, 0xffff0000, v116
	v_lshlrev_b32_e32 v116, 16, v117
	v_and_b32_e32 v117, 0xffff0000, v117
	v_lshlrev_b32_e32 v160, 16, v120
	v_and_b32_e32 v161, 0xffff0000, v120
	v_lshlrev_b32_e32 v120, 16, v121
	v_and_b32_e32 v121, 0xffff0000, v121
	v_pk_add_f32 v[110:111], v[110:111], v[114:115]
	v_pk_add_f32 v[108:109], v[108:109], v[124:125]
	v_pk_add_f32 v[102:103], v[102:103], v[118:119]
	v_pk_add_f32 v[100:101], v[100:101], v[158:159]
	v_pk_add_f32 v[106:107], v[106:107], v[116:117]
	v_pk_add_f32 v[104:105], v[104:105], v[126:127]
	v_pk_add_f32 v[114:115], v[98:99], v[120:121]
	v_pk_add_f32 v[116:117], v[96:97], v[160:161]
	v_mul_f32_e32 v98, v109, v109
	v_mul_f32_e32 v99, v111, v111
	v_mul_f32_e32 v118, v101, v101
	v_mul_f32_e32 v119, v103, v103
	v_cvt_pk_bf16_f32 v96, v108, v109
	v_mul_f32_e32 v109, v105, v105
	v_mul_f32_e32 v120, v117, v117
	v_fmac_f32_e32 v98, v108, v108
	v_fmac_f32_e32 v99, v110, v110
	v_fmac_f32_e32 v118, v100, v100
	v_fmac_f32_e32 v119, v102, v102
	v_cvt_pk_bf16_f32 v97, v110, v111
	v_mul_f32_e32 v111, v107, v107
	v_mul_f32_e32 v121, v115, v115
	v_fmac_f32_e32 v109, v104, v104
	v_fmac_f32_e32 v120, v116, v116
	v_add_f32_e32 v98, v98, v99
	v_add_f32_e32 v99, v118, v119
	v_fmac_f32_e32 v111, v106, v106
	v_fmac_f32_e32 v121, v114, v114
	v_add_f32_e32 v98, v109, v98
	v_add_f32_e32 v99, v120, v99
	v_add_f32_e32 v98, v111, v98
	v_add_f32_e32 v99, v121, v99
	v_add_f32_e32 v108, v98, v99
	v_mov_b32_e32 v109, v108
	s_nop 1
	v_permlane16_swap_b32_e32 v109, v108
	v_cvt_pk_bf16_f32 v98, v104, v105
	v_cvt_pk_bf16_f32 v99, v106, v107
	global_store_dwordx4 v[122:123], v[96:99], off
	s_waitcnt lgkmcnt(0)
	s_nop 0
	v_add_f32_e32 v96, v108, v109
	v_mov_b32_e32 v97, v96
	s_nop 1
	v_permlane32_swap_b32_e32 v97, v96
	v_cvt_pk_bf16_f32 v98, v100, v101
	v_cvt_pk_bf16_f32 v99, v102, v103
	v_cvt_pk_bf16_f32 v100, v116, v117
	v_cvt_pk_bf16_f32 v101, v114, v115
	global_store_dwordx4 v[122:123], v[98:101], off offset:256
	s_and_saveexec_b64 s[46:47], s[4:5]
	s_cbranch_execz .LBB0_1600
	s_waitcnt lgkmcnt(0)
	v_add_f32_e32 v96, v96, v97
	v_mul_f32_e32 v96, 0x4f800000, v96
	v_trunc_f32_e32 v96, v96
	v_mul_f32_e64 v97, |v96|, s62
	v_floor_f32_e32 v97, v97
	v_fma_f32 v98, v97, s63, |v96|
	v_cvt_u32_f32_e32 v96, v98
	v_cvt_u32_f32_e32 v97, v97
	v_lshl_add_u64 v[98:99], v[112:113], 3, s[12:13]
	global_atomic_add_x2 v[98:99], v[96:97], off
; __device__ __forceinline__ unsigned cvtpk(float lo, float hi) { f32x2v_ v = {lo, hi}; bf16x2v_ b = __builtin_convertvector(v, bf16x2v_); return __builtin_bit_cast(unsigned, b); }
; __device__ __forceinline__ void fx_add(float* p, size_t idx, float s) { atomicAdd((unsigned long long*)p + idx, (unsigned long long)(long long)(s * 4294967296.0f)); }
;     __device__ __forceinline__ void operator()(const f32x4 (&acc)[2][2][4][2], const Unit& u, int wr, int wc, int fr, int fq) const {
;     ...
;             for (int m = 0; m < 4; ++m) { const int row = row0 + ai * HALF + m * 16; const size_t off = (size_t)row * 1024 + col0; float s = 0.f;
; #pragma unroll
;                 for (int bj = 0; bj < 2; ++bj) { f32x4 a0, a1;
;                     if (xin32) { const float* p = xin32 + off + bj * HALF; a0 = *(const f32x4*)p; a1 = *(const f32x4*)(p + 4); }
;                     else { const u32x4 w = *(const u32x4*)(xb + off + bj * HALF);
;                         a0 = (f32x4){__uint_as_float(w.x << 16), __uint_as_float(w.x & 0xffff0000u), __uint_as_float(w.y << 16), __uint_as_float(w.y & 0xffff0000u)};
;                         a1 = (f32x4){__uint_as_float(w.z << 16), __uint_as_float(w.z & 0xffff0000u), __uint_as_float(w.w << 16), __uint_as_float(w.w & 0xffff0000u)}; }
;                     const f32x4 v0 = a0 + acc[ai][bj][m][0] * alpha, v1 = a1 + acc[ai][bj][m][1] * alpha;
;                     u32x4 w; w.x = cvtpk(v0[0], v0[1]); w.y = cvtpk(v0[2], v0[3]); w.z = cvtpk(v1[0], v1[1]); w.w = cvtpk(v1[2], v1[3]);
;                     *(u32x4*)(xb + off + bj * HALF) = w;
;                     s += (v0[0] * v0[0] + v0[1] * v0[1]) + (v0[2] * v0[2] + v0[3] * v0[3]) + (v1[0] * v1[0] + v1[1] * v1[1]) + (v1[2] * v1[2] + v1[3] * v1[3]); }
;                 s += __shfl_xor(s, 16); s += __shfl_xor(s, 32);
;                 if (fq == 0) fx_add(ssout, row, s); }
.LBB0_1600:
	s_or_b64 exec, exec, s[46:47]
	v_or_b32_e32 v96, 32, v148
	s_waitcnt lgkmcnt(0)
	v_ashrrev_i32_e32 v97, 31, v96
	v_lshlrev_b64 v[98:99], 11, v[96:97]
	v_lshl_add_u64 v[98:99], s[22:23], 0, v[98:99]
	v_lshl_add_u64 v[106:107], v[146:147], 1, v[98:99]
	global_load_dwordx4 v[98:101], v[106:107], off
	global_load_dwordx4 v[102:105], v[106:107], off offset:256
	s_waitcnt vmcnt(1)
	v_lshlrev_b32_e32 v108, 16, v98
	v_and_b32_e32 v109, 0xffff0000, v98
	v_lshlrev_b32_e32 v98, 16, v99
	v_and_b32_e32 v99, 0xffff0000, v99
	s_waitcnt vmcnt(0)
	v_lshlrev_b32_e32 v112, 16, v102
	v_and_b32_e32 v113, 0xffff0000, v102
	v_lshlrev_b32_e32 v102, 16, v103
	v_and_b32_e32 v103, 0xffff0000, v103
	v_lshlrev_b32_e32 v110, 16, v100
	v_and_b32_e32 v111, 0xffff0000, v100
	v_lshlrev_b32_e32 v100, 16, v101
	v_and_b32_e32 v101, 0xffff0000, v101
	v_lshlrev_b32_e32 v114, 16, v104
	v_and_b32_e32 v115, 0xffff0000, v104
	v_lshlrev_b32_e32 v104, 16, v105
	v_and_b32_e32 v105, 0xffff0000, v105
	v_pk_add_f32 v[94:95], v[94:95], v[98:99]
	v_pk_add_f32 v[92:93], v[92:93], v[108:109]
	v_pk_add_f32 v[86:87], v[86:87], v[102:103]
	v_pk_add_f32 v[84:85], v[84:85], v[112:113]
	v_pk_add_f32 v[90:91], v[90:91], v[100:101]
	v_pk_add_f32 v[88:89], v[88:89], v[110:111]
	v_pk_add_f32 v[98:99], v[82:83], v[104:105]
	v_pk_add_f32 v[100:101], v[80:81], v[114:115]
	v_mul_f32_e32 v82, v93, v93
	v_mul_f32_e32 v83, v95, v95
	v_mul_f32_e32 v102, v85, v85
	v_mul_f32_e32 v103, v87, v87
	v_cvt_pk_bf16_f32 v80, v92, v93
	v_mul_f32_e32 v93, v89, v89
	v_mul_f32_e32 v104, v101, v101
	v_fmac_f32_e32 v82, v92, v92
	v_fmac_f32_e32 v83, v94, v94
	v_fmac_f32_e32 v102, v84, v84
	v_fmac_f32_e32 v103, v86, v86
	v_cvt_pk_bf16_f32 v81, v94, v95
	v_mul_f32_e32 v95, v91, v91
	v_mul_f32_e32 v105, v99, v99
	v_fmac_f32_e32 v93, v88, v88
	v_fmac_f32_e32 v104, v100, v100
	v_add_f32_e32 v82, v82, v83
	v_add_f32_e32 v83, v102, v103
	v_fmac_f32_e32 v95, v90, v90
	v_fmac_f32_e32 v105, v98, v98
	v_add_f32_e32 v82, v93, v82
	v_add_f32_e32 v83, v104, v83
	v_add_f32_e32 v82, v95, v82
	v_add_f32_e32 v83, v105, v83
	v_add_f32_e32 v92, v82, v83
	v_mov_b32_e32 v93, v92
	s_nop 1
	v_permlane16_swap_b32_e32 v93, v92
	v_cvt_pk_bf16_f32 v82, v88, v89
	v_cvt_pk_bf16_f32 v83, v90, v91
	global_store_dwordx4 v[106:107], v[80:83], off
	s_waitcnt lgkmcnt(0)
	s_nop 0
	v_add_f32_e32 v80, v92, v93
	v_mov_b32_e32 v81, v80
	s_nop 1
	v_permlane32_swap_b32_e32 v81, v80
	v_cvt_pk_bf16_f32 v82, v84, v85
	v_cvt_pk_bf16_f32 v83, v86, v87
	v_cvt_pk_bf16_f32 v84, v100, v101
	v_cvt_pk_bf16_f32 v85, v98, v99
	global_store_dwordx4 v[106:107], v[82:85], off offset:256
	s_and_saveexec_b64 s[46:47], s[4:5]
	s_cbranch_execz .LBB0_1602
	s_waitcnt lgkmcnt(0)
	v_add_f32_e32 v80, v80, v81
	v_mul_f32_e32 v80, 0x4f800000, v80
	v_trunc_f32_e32 v80, v80
	v_mul_f32_e64 v81, |v80|, s62
	v_floor_f32_e32 v81, v81
	v_fma_f32 v82, v81, s63, |v80|
	v_cvt_u32_f32_e32 v80, v82
	v_cvt_u32_f32_e32 v81, v81
	v_lshl_add_u64 v[82:83], v[96:97], 3, s[12:13]
	global_atomic_add_x2 v[82:83], v[80:81], off
.LBB0_1602:
	s_or_b64 exec, exec, s[46:47]
	v_or_b32_e32 v80, 48, v148
	s_waitcnt lgkmcnt(0)
	v_ashrrev_i32_e32 v81, 31, v80
	v_lshlrev_b64 v[82:83], 11, v[80:81]
	v_lshl_add_u64 v[82:83], s[22:23], 0, v[82:83]
	v_lshl_add_u64 v[90:91], v[146:147], 1, v[82:83]
	global_load_dwordx4 v[82:85], v[90:91], off
	global_load_dwordx4 v[86:89], v[90:91], off offset:256
	s_waitcnt vmcnt(1)
	v_lshlrev_b32_e32 v92, 16, v82
	v_and_b32_e32 v93, 0xffff0000, v82
	v_lshlrev_b32_e32 v82, 16, v83
	v_and_b32_e32 v83, 0xffff0000, v83
	s_waitcnt vmcnt(0)
	v_lshlrev_b32_e32 v96, 16, v86
	v_and_b32_e32 v97, 0xffff0000, v86
	v_lshlrev_b32_e32 v86, 16, v87
	v_and_b32_e32 v87, 0xffff0000, v87
	v_lshlrev_b32_e32 v94, 16, v84
	v_and_b32_e32 v95, 0xffff0000, v84
	v_lshlrev_b32_e32 v84, 16, v85
	v_and_b32_e32 v85, 0xffff0000, v85
	v_lshlrev_b32_e32 v98, 16, v88
	v_and_b32_e32 v99, 0xffff0000, v88
	v_lshlrev_b32_e32 v88, 16, v89
	v_and_b32_e32 v89, 0xffff0000, v89
	v_pk_add_f32 v[78:79], v[78:79], v[82:83]
	v_pk_add_f32 v[76:77], v[76:77], v[92:93]
	v_pk_add_f32 v[70:71], v[70:71], v[86:87]
	v_pk_add_f32 v[68:69], v[68:69], v[96:97]
	v_pk_add_f32 v[74:75], v[74:75], v[84:85]
	v_pk_add_f32 v[72:73], v[72:73], v[94:95]
	v_pk_add_f32 v[82:83], v[66:67], v[88:89]
	v_pk_add_f32 v[84:85], v[64:65], v[98:99]
	v_mul_f32_e32 v66, v77, v77
	v_mul_f32_e32 v67, v79, v79
	v_mul_f32_e32 v86, v69, v69
	v_mul_f32_e32 v87, v71, v71
	v_cvt_pk_bf16_f32 v64, v76, v77
	v_mul_f32_e32 v77, v73, v73
	v_mul_f32_e32 v88, v85, v85
	v_fmac_f32_e32 v66, v76, v76
	v_fmac_f32_e32 v67, v78, v78
	v_fmac_f32_e32 v86, v68, v68
	v_fmac_f32_e32 v87, v70, v70
	v_cvt_pk_bf16_f32 v65, v78, v79
	v_mul_f32_e32 v79, v75, v75
	v_mul_f32_e32 v89, v83, v83
	v_fmac_f32_e32 v77, v72, v72
	v_fmac_f32_e32 v88, v84, v84
	v_add_f32_e32 v66, v66, v67
	v_add_f32_e32 v67, v86, v87
	v_fmac_f32_e32 v79, v74, v74
	v_fmac_f32_e32 v89, v82, v82
	v_add_f32_e32 v66, v77, v66
	v_add_f32_e32 v67, v88, v67
	v_add_f32_e32 v66, v79, v66
	v_add_f32_e32 v67, v89, v67
	v_add_f32_e32 v76, v66, v67
	v_mov_b32_e32 v77, v76
	s_nop 1
	v_permlane16_swap_b32_e32 v77, v76
	v_cvt_pk_bf16_f32 v66, v72, v73
	v_cvt_pk_bf16_f32 v67, v74, v75
	global_store_dwordx4 v[90:91], v[64:67], off
	s_waitcnt lgkmcnt(0)
	s_nop 0
	v_add_f32_e32 v64, v76, v77
	v_mov_b32_e32 v65, v64
	s_nop 1
	v_permlane32_swap_b32_e32 v65, v64
	v_cvt_pk_bf16_f32 v66, v68, v69
	v_cvt_pk_bf16_f32 v67, v70, v71
	v_cvt_pk_bf16_f32 v68, v84, v85
	v_cvt_pk_bf16_f32 v69, v82, v83
	global_store_dwordx4 v[90:91], v[66:69], off offset:256
	s_and_saveexec_b64 s[46:47], s[4:5]
	s_cbranch_execz .LBB0_1604
	s_waitcnt lgkmcnt(0)
	v_add_f32_e32 v64, v64, v65
	v_mul_f32_e32 v64, 0x4f800000, v64
	v_trunc_f32_e32 v64, v64
	v_mul_f32_e64 v65, |v64|, s62
	v_floor_f32_e32 v65, v65
	v_fma_f32 v66, v65, s63, |v64|
	v_cvt_u32_f32_e32 v64, v66
	v_cvt_u32_f32_e32 v65, v65
	v_lshl_add_u64 v[66:67], v[80:81], 3, s[12:13]
	global_atomic_add_x2 v[66:67], v[64:65], off
; __device__ __forceinline__ unsigned cvtpk(float lo, float hi) { f32x2v_ v = {lo, hi}; bf16x2v_ b = __builtin_convertvector(v, bf16x2v_); return __builtin_bit_cast(unsigned, b); }
; __device__ __forceinline__ void fx_add(float* p, size_t idx, float s) { atomicAdd((unsigned long long*)p + idx, (unsigned long long)(long long)(s * 4294967296.0f)); }
;     __device__ __forceinline__ void operator()(const f32x4 (&acc)[2][2][4][2], const Unit& u, int wr, int wc, int fr, int fq) const {
;     ...
;             for (int m = 0; m < 4; ++m) { const int row = row0 + ai * HALF + m * 16; const size_t off = (size_t)row * 1024 + col0; float s = 0.f;
; #pragma unroll
;                 for (int bj = 0; bj < 2; ++bj) { f32x4 a0, a1;
;                     if (xin32) { const float* p = xin32 + off + bj * HALF; a0 = *(const f32x4*)p; a1 = *(const f32x4*)(p + 4); }
;                     else { const u32x4 w = *(const u32x4*)(xb + off + bj * HALF);
;                         a0 = (f32x4){__uint_as_float(w.x << 16), __uint_as_float(w.x & 0xffff0000u), __uint_as_float(w.y << 16), __uint_as_float(w.y & 0xffff0000u)};
;                         a1 = (f32x4){__uint_as_float(w.z << 16), __uint_as_float(w.z & 0xffff0000u), __uint_as_float(w.w << 16), __uint_as_float(w.w & 0xffff0000u)}; }
;                     const f32x4 v0 = a0 + acc[ai][bj][m][0] * alpha, v1 = a1 + acc[ai][bj][m][1] * alpha;
;                     u32x4 w; w.x = cvtpk(v0[0], v0[1]); w.y = cvtpk(v0[2], v0[3]); w.z = cvtpk(v1[0], v1[1]); w.w = cvtpk(v1[2], v1[3]);
;                     *(u32x4*)(xb + off + bj * HALF) = w;
;                     s += (v0[0] * v0[0] + v0[1] * v0[1]) + (v0[2] * v0[2] + v0[3] * v0[3]) + (v1[0] * v1[0] + v1[1] * v1[1]) + (v1[2] * v1[2] + v1[3] * v1[3]); }
;                 s += __shfl_xor(s, 16); s += __shfl_xor(s, 32);
;                 if (fq == 0) fx_add(ssout, row, s); }
.LBB0_1604:
	s_or_b64 exec, exec, s[46:47]
	v_add_u32_e32 v64, 0x80, v148
	s_waitcnt lgkmcnt(0)
	v_ashrrev_i32_e32 v65, 31, v64
	v_lshlrev_b64 v[66:67], 11, v[64:65]
	v_lshl_add_u64 v[66:67], s[22:23], 0, v[66:67]
	v_lshl_add_u64 v[74:75], v[146:147], 1, v[66:67]
	global_load_dwordx4 v[66:69], v[74:75], off
	global_load_dwordx4 v[70:73], v[74:75], off offset:256
	s_waitcnt vmcnt(1)
	v_lshlrev_b32_e32 v76, 16, v66
	v_and_b32_e32 v77, 0xffff0000, v66
	v_lshlrev_b32_e32 v66, 16, v67
	v_and_b32_e32 v67, 0xffff0000, v67
	s_waitcnt vmcnt(0)
	v_lshlrev_b32_e32 v80, 16, v70
	v_and_b32_e32 v81, 0xffff0000, v70
	v_lshlrev_b32_e32 v70, 16, v71
	v_and_b32_e32 v71, 0xffff0000, v71
	v_lshlrev_b32_e32 v78, 16, v68
	v_and_b32_e32 v79, 0xffff0000, v68
	v_lshlrev_b32_e32 v68, 16, v69
	v_and_b32_e32 v69, 0xffff0000, v69
	v_lshlrev_b32_e32 v82, 16, v72
	v_and_b32_e32 v83, 0xffff0000, v72
	v_lshlrev_b32_e32 v72, 16, v73
	v_and_b32_e32 v73, 0xffff0000, v73
	v_pk_add_f32 v[62:63], v[62:63], v[66:67]
	v_pk_add_f32 v[60:61], v[60:61], v[76:77]
	v_pk_add_f32 v[54:55], v[54:55], v[70:71]
	v_pk_add_f32 v[52:53], v[52:53], v[80:81]
	v_pk_add_f32 v[58:59], v[58:59], v[68:69]
	v_pk_add_f32 v[56:57], v[56:57], v[78:79]
	v_pk_add_f32 v[66:67], v[50:51], v[72:73]
	v_pk_add_f32 v[68:69], v[48:49], v[82:83]
	v_mul_f32_e32 v50, v61, v61
	v_mul_f32_e32 v51, v63, v63
	v_mul_f32_e32 v70, v53, v53
	v_mul_f32_e32 v71, v55, v55
	v_cvt_pk_bf16_f32 v48, v60, v61
	v_mul_f32_e32 v61, v57, v57
	v_mul_f32_e32 v72, v69, v69
	v_fmac_f32_e32 v50, v60, v60
	v_fmac_f32_e32 v51, v62, v62
	v_fmac_f32_e32 v70, v52, v52
	v_fmac_f32_e32 v71, v54, v54
	v_cvt_pk_bf16_f32 v49, v62, v63
	v_mul_f32_e32 v63, v59, v59
	v_mul_f32_e32 v73, v67, v67
	v_fmac_f32_e32 v61, v56, v56
	v_fmac_f32_e32 v72, v68, v68
	v_add_f32_e32 v50, v50, v51
	v_add_f32_e32 v51, v70, v71
	v_fmac_f32_e32 v63, v58, v58
	v_fmac_f32_e32 v73, v66, v66
	v_add_f32_e32 v50, v61, v50
	v_add_f32_e32 v51, v72, v51
	v_add_f32_e32 v50, v63, v50
	v_add_f32_e32 v51, v73, v51
	v_add_f32_e32 v60, v50, v51
	v_mov_b32_e32 v61, v60
	s_nop 1
	v_permlane16_swap_b32_e32 v61, v60
	v_cvt_pk_bf16_f32 v50, v56, v57
	v_cvt_pk_bf16_f32 v51, v58, v59
	global_store_dwordx4 v[74:75], v[48:51], off
	s_waitcnt lgkmcnt(0)
	s_nop 0
	v_add_f32_e32 v48, v60, v61
	v_mov_b32_e32 v49, v48
	s_nop 1
	v_permlane32_swap_b32_e32 v49, v48
	v_cvt_pk_bf16_f32 v50, v52, v53
	v_cvt_pk_bf16_f32 v51, v54, v55
	v_cvt_pk_bf16_f32 v52, v68, v69
	v_cvt_pk_bf16_f32 v53, v66, v67
	global_store_dwordx4 v[74:75], v[50:53], off offset:256
	s_and_saveexec_b64 s[46:47], s[4:5]
	s_cbranch_execz .LBB0_1606
	s_waitcnt lgkmcnt(0)
	v_add_f32_e32 v48, v48, v49
	v_mul_f32_e32 v48, 0x4f800000, v48
	v_trunc_f32_e32 v48, v48
	v_mul_f32_e64 v49, |v48|, s62
	v_floor_f32_e32 v49, v49
	v_fma_f32 v50, v49, s63, |v48|
	v_cvt_u32_f32_e32 v48, v50
	v_cvt_u32_f32_e32 v49, v49
	v_lshl_add_u64 v[50:51], v[64:65], 3, s[12:13]
	global_atomic_add_x2 v[50:51], v[48:49], off
.LBB0_1606:
	s_or_b64 exec, exec, s[46:47]
	v_add_u32_e32 v48, 0x90, v148
	s_waitcnt lgkmcnt(0)
	v_ashrrev_i32_e32 v49, 31, v48
	v_lshlrev_b64 v[50:51], 11, v[48:49]
	v_lshl_add_u64 v[50:51], s[22:23], 0, v[50:51]
	v_lshl_add_u64 v[58:59], v[146:147], 1, v[50:51]
	global_load_dwordx4 v[50:53], v[58:59], off
	global_load_dwordx4 v[54:57], v[58:59], off offset:256
	s_waitcnt vmcnt(1)
	v_lshlrev_b32_e32 v60, 16, v50
	v_and_b32_e32 v61, 0xffff0000, v50
	v_lshlrev_b32_e32 v50, 16, v51
	v_and_b32_e32 v51, 0xffff0000, v51
	s_waitcnt vmcnt(0)
	v_lshlrev_b32_e32 v64, 16, v54
	v_and_b32_e32 v65, 0xffff0000, v54
	v_lshlrev_b32_e32 v54, 16, v55
	v_and_b32_e32 v55, 0xffff0000, v55
	v_lshlrev_b32_e32 v62, 16, v52
	v_and_b32_e32 v63, 0xffff0000, v52
	v_lshlrev_b32_e32 v52, 16, v53
	v_and_b32_e32 v53, 0xffff0000, v53
	v_lshlrev_b32_e32 v66, 16, v56
	v_and_b32_e32 v67, 0xffff0000, v56
	v_lshlrev_b32_e32 v56, 16, v57
	v_and_b32_e32 v57, 0xffff0000, v57
	v_pk_add_f32 v[46:47], v[46:47], v[50:51]
	v_pk_add_f32 v[44:45], v[44:45], v[60:61]
	v_pk_add_f32 v[38:39], v[38:39], v[54:55]
	v_pk_add_f32 v[36:37], v[36:37], v[64:65]
	v_pk_add_f32 v[42:43], v[42:43], v[52:53]
	v_pk_add_f32 v[40:41], v[40:41], v[62:63]
	v_pk_add_f32 v[50:51], v[34:35], v[56:57]
	v_pk_add_f32 v[52:53], v[32:33], v[66:67]
	v_mul_f32_e32 v34, v45, v45
	v_mul_f32_e32 v35, v47, v47
	v_mul_f32_e32 v54, v37, v37
	v_mul_f32_e32 v55, v39, v39
	v_cvt_pk_bf16_f32 v32, v44, v45
	v_mul_f32_e32 v45, v41, v41
	v_mul_f32_e32 v56, v53, v53
	v_fmac_f32_e32 v34, v44, v44
	v_fmac_f32_e32 v35, v46, v46
	v_fmac_f32_e32 v54, v36, v36
	v_fmac_f32_e32 v55, v38, v38
	v_cvt_pk_bf16_f32 v33, v46, v47
	v_mul_f32_e32 v47, v43, v43
	v_mul_f32_e32 v57, v51, v51
	v_fmac_f32_e32 v45, v40, v40
	v_fmac_f32_e32 v56, v52, v52
	v_add_f32_e32 v34, v34, v35
	v_add_f32_e32 v35, v54, v55
	v_fmac_f32_e32 v47, v42, v42
	v_fmac_f32_e32 v57, v50, v50
	v_add_f32_e32 v34, v45, v34
	v_add_f32_e32 v35, v56, v35
	v_add_f32_e32 v34, v47, v34
	v_add_f32_e32 v35, v57, v35
	v_add_f32_e32 v44, v34, v35
	v_mov_b32_e32 v45, v44
	s_nop 1
	v_permlane16_swap_b32_e32 v45, v44
	v_cvt_pk_bf16_f32 v34, v40, v41
	v_cvt_pk_bf16_f32 v35, v42, v43
	global_store_dwordx4 v[58:59], v[32:35], off
	s_waitcnt lgkmcnt(0)
	s_nop 0
	v_add_f32_e32 v32, v44, v45
	v_mov_b32_e32 v33, v32
	s_nop 1
	v_permlane32_swap_b32_e32 v33, v32
	v_cvt_pk_bf16_f32 v34, v36, v37
	v_cvt_pk_bf16_f32 v35, v38, v39
	v_cvt_pk_bf16_f32 v36, v52, v53
	v_cvt_pk_bf16_f32 v37, v50, v51
	global_store_dwordx4 v[58:59], v[34:37], off offset:256
	s_and_saveexec_b64 s[46:47], s[4:5]
	s_cbranch_execz .LBB0_1608
	s_waitcnt lgkmcnt(0)
	v_add_f32_e32 v32, v32, v33
	v_mul_f32_e32 v32, 0x4f800000, v32
	v_trunc_f32_e32 v32, v32
	v_mul_f32_e64 v33, |v32|, s62
	v_floor_f32_e32 v33, v33
	v_fma_f32 v34, v33, s63, |v32|
	v_cvt_u32_f32_e32 v32, v34
	v_cvt_u32_f32_e32 v33, v33
	v_lshl_add_u64 v[34:35], v[48:49], 3, s[12:13]
	global_atomic_add_x2 v[34:35], v[32:33], off
; __device__ __forceinline__ unsigned cvtpk(float lo, float hi) { f32x2v_ v = {lo, hi}; bf16x2v_ b = __builtin_convertvector(v, bf16x2v_); return __builtin_bit_cast(unsigned, b); }
; __device__ __forceinline__ void fx_add(float* p, size_t idx, float s) { atomicAdd((unsigned long long*)p + idx, (unsigned long long)(long long)(s * 4294967296.0f)); }
;     __device__ __forceinline__ void operator()(const f32x4 (&acc)[2][2][4][2], const Unit& u, int wr, int wc, int fr, int fq) const {
;     ...
;             for (int m = 0; m < 4; ++m) { const int row = row0 + ai * HALF + m * 16; const size_t off = (size_t)row * 1024 + col0; float s = 0.f;
; #pragma unroll
;                 for (int bj = 0; bj < 2; ++bj) { f32x4 a0, a1;
;                     if (xin32) { const float* p = xin32 + off + bj * HALF; a0 = *(const f32x4*)p; a1 = *(const f32x4*)(p + 4); }
;                     else { const u32x4 w = *(const u32x4*)(xb + off + bj * HALF);
;                         a0 = (f32x4){__uint_as_float(w.x << 16), __uint_as_float(w.x & 0xffff0000u), __uint_as_float(w.y << 16), __uint_as_float(w.y & 0xffff0000u)};
;                         a1 = (f32x4){__uint_as_float(w.z << 16), __uint_as_float(w.z & 0xffff0000u), __uint_as_float(w.w << 16), __uint_as_float(w.w & 0xffff0000u)}; }
;                     const f32x4 v0 = a0 + acc[ai][bj][m][0] * alpha, v1 = a1 + acc[ai][bj][m][1] * alpha;
;                     u32x4 w; w.x = cvtpk(v0[0], v0[1]); w.y = cvtpk(v0[2], v0[3]); w.z = cvtpk(v1[0], v1[1]); w.w = cvtpk(v1[2], v1[3]);
;                     *(u32x4*)(xb + off + bj * HALF) = w;
;                     s += (v0[0] * v0[0] + v0[1] * v0[1]) + (v0[2] * v0[2] + v0[3] * v0[3]) + (v1[0] * v1[0] + v1[1] * v1[1]) + (v1[2] * v1[2] + v1[3] * v1[3]); }
;                 s += __shfl_xor(s, 16); s += __shfl_xor(s, 32);
;                 if (fq == 0) fx_add(ssout, row, s); }
.LBB0_1608:
	s_or_b64 exec, exec, s[46:47]
	v_add_u32_e32 v32, 0xa0, v148
	s_waitcnt lgkmcnt(0)
	v_ashrrev_i32_e32 v33, 31, v32
	v_lshlrev_b64 v[34:35], 11, v[32:33]
	v_lshl_add_u64 v[34:35], s[22:23], 0, v[34:35]
	v_lshl_add_u64 v[42:43], v[146:147], 1, v[34:35]
	global_load_dwordx4 v[34:37], v[42:43], off
	global_load_dwordx4 v[38:41], v[42:43], off offset:256
	s_waitcnt vmcnt(1)
	v_lshlrev_b32_e32 v44, 16, v34
	v_and_b32_e32 v45, 0xffff0000, v34
	v_lshlrev_b32_e32 v34, 16, v35
	v_and_b32_e32 v35, 0xffff0000, v35
	s_waitcnt vmcnt(0)
	v_lshlrev_b32_e32 v48, 16, v38
	v_and_b32_e32 v49, 0xffff0000, v38
	v_lshlrev_b32_e32 v38, 16, v39
	v_and_b32_e32 v39, 0xffff0000, v39
	v_lshlrev_b32_e32 v46, 16, v36
	v_and_b32_e32 v47, 0xffff0000, v36
	v_lshlrev_b32_e32 v36, 16, v37
	v_and_b32_e32 v37, 0xffff0000, v37
	v_lshlrev_b32_e32 v50, 16, v40
	v_and_b32_e32 v51, 0xffff0000, v40
	v_lshlrev_b32_e32 v40, 16, v41
	v_and_b32_e32 v41, 0xffff0000, v41
	v_pk_add_f32 v[30:31], v[30:31], v[34:35]
	v_pk_add_f32 v[28:29], v[28:29], v[44:45]
	v_pk_add_f32 v[22:23], v[22:23], v[38:39]
	v_pk_add_f32 v[20:21], v[20:21], v[48:49]
	v_pk_add_f32 v[26:27], v[26:27], v[36:37]
	v_pk_add_f32 v[24:25], v[24:25], v[46:47]
	v_pk_add_f32 v[34:35], v[18:19], v[40:41]
	v_pk_add_f32 v[36:37], v[16:17], v[50:51]
	v_mul_f32_e32 v18, v29, v29
	v_mul_f32_e32 v19, v31, v31
	v_mul_f32_e32 v38, v21, v21
	v_mul_f32_e32 v39, v23, v23
	v_cvt_pk_bf16_f32 v16, v28, v29
	v_mul_f32_e32 v29, v25, v25
	v_mul_f32_e32 v40, v37, v37
	v_fmac_f32_e32 v18, v28, v28
	v_fmac_f32_e32 v19, v30, v30
	v_fmac_f32_e32 v38, v20, v20
	v_fmac_f32_e32 v39, v22, v22
	v_cvt_pk_bf16_f32 v17, v30, v31
	v_mul_f32_e32 v31, v27, v27
	v_mul_f32_e32 v41, v35, v35
	v_fmac_f32_e32 v29, v24, v24
	v_fmac_f32_e32 v40, v36, v36
	v_add_f32_e32 v18, v18, v19
	v_add_f32_e32 v19, v38, v39
	v_fmac_f32_e32 v31, v26, v26
	v_fmac_f32_e32 v41, v34, v34
	v_add_f32_e32 v18, v29, v18
	v_add_f32_e32 v19, v40, v19
	v_add_f32_e32 v18, v31, v18
	v_add_f32_e32 v19, v41, v19
	v_add_f32_e32 v28, v18, v19
	v_mov_b32_e32 v29, v28
	s_nop 1
	v_permlane16_swap_b32_e32 v29, v28
	v_cvt_pk_bf16_f32 v18, v24, v25
	v_cvt_pk_bf16_f32 v19, v26, v27
	global_store_dwordx4 v[42:43], v[16:19], off
	s_waitcnt lgkmcnt(0)
	s_nop 0
	v_add_f32_e32 v16, v28, v29
	v_mov_b32_e32 v17, v16
	s_nop 1
	v_permlane32_swap_b32_e32 v17, v16
	v_cvt_pk_bf16_f32 v18, v20, v21
	v_cvt_pk_bf16_f32 v19, v22, v23
	v_cvt_pk_bf16_f32 v20, v36, v37
	v_cvt_pk_bf16_f32 v21, v34, v35
	global_store_dwordx4 v[42:43], v[18:21], off offset:256
	s_and_saveexec_b64 s[46:47], s[4:5]
	s_cbranch_execz .LBB0_1610
	s_waitcnt lgkmcnt(0)
	v_add_f32_e32 v16, v16, v17
	v_mul_f32_e32 v16, 0x4f800000, v16
	v_trunc_f32_e32 v16, v16
	v_mul_f32_e64 v17, |v16|, s62
	v_floor_f32_e32 v17, v17
	v_fma_f32 v18, v17, s63, |v16|
	v_cvt_u32_f32_e32 v16, v18
	v_cvt_u32_f32_e32 v17, v17
	v_lshl_add_u64 v[18:19], v[32:33], 3, s[12:13]
	global_atomic_add_x2 v[18:19], v[16:17], off
.LBB0_1610:
	s_or_b64 exec, exec, s[46:47]
	v_add_u32_e32 v16, 0xb0, v148
	s_waitcnt lgkmcnt(0)
	v_ashrrev_i32_e32 v17, 31, v16
	v_lshlrev_b64 v[18:19], 11, v[16:17]
	v_lshl_add_u64 v[18:19], s[22:23], 0, v[18:19]
	v_lshl_add_u64 v[26:27], v[146:147], 1, v[18:19]
	global_load_dwordx4 v[18:21], v[26:27], off
	global_load_dwordx4 v[22:25], v[26:27], off offset:256
	s_waitcnt vmcnt(1)
	v_lshlrev_b32_e32 v28, 16, v18
	v_and_b32_e32 v29, 0xffff0000, v18
	v_lshlrev_b32_e32 v18, 16, v19
	v_and_b32_e32 v19, 0xffff0000, v19
	s_waitcnt vmcnt(0)
	v_lshlrev_b32_e32 v32, 16, v22
	v_and_b32_e32 v33, 0xffff0000, v22
	v_lshlrev_b32_e32 v22, 16, v23
	v_and_b32_e32 v23, 0xffff0000, v23
	v_lshlrev_b32_e32 v30, 16, v20
	v_and_b32_e32 v31, 0xffff0000, v20
	v_lshlrev_b32_e32 v20, 16, v21
	v_and_b32_e32 v21, 0xffff0000, v21
	v_lshlrev_b32_e32 v34, 16, v24
	v_and_b32_e32 v35, 0xffff0000, v24
	v_lshlrev_b32_e32 v24, 16, v25
	v_and_b32_e32 v25, 0xffff0000, v25
	v_pk_add_f32 v[14:15], v[14:15], v[18:19]
	v_pk_add_f32 v[12:13], v[12:13], v[28:29]
	v_pk_add_f32 v[6:7], v[6:7], v[22:23]
	v_pk_add_f32 v[4:5], v[4:5], v[32:33]
	v_pk_add_f32 v[10:11], v[10:11], v[20:21]
	v_pk_add_f32 v[8:9], v[8:9], v[30:31]
	v_pk_add_f32 v[18:19], v[2:3], v[24:25]
	v_pk_add_f32 v[20:21], v[0:1], v[34:35]
	v_mul_f32_e32 v2, v13, v13
	v_mul_f32_e32 v3, v15, v15
	v_mul_f32_e32 v22, v5, v5
	v_mul_f32_e32 v23, v7, v7
	v_cvt_pk_bf16_f32 v0, v12, v13
	v_mul_f32_e32 v13, v9, v9
	v_mul_f32_e32 v24, v21, v21
	v_fmac_f32_e32 v2, v12, v12
	v_fmac_f32_e32 v3, v14, v14
	v_fmac_f32_e32 v22, v4, v4
	v_fmac_f32_e32 v23, v6, v6
	v_cvt_pk_bf16_f32 v1, v14, v15
	v_mul_f32_e32 v15, v11, v11
	v_mul_f32_e32 v25, v19, v19
	v_fmac_f32_e32 v13, v8, v8
	v_fmac_f32_e32 v24, v20, v20
	v_add_f32_e32 v2, v2, v3
	v_add_f32_e32 v3, v22, v23
	v_fmac_f32_e32 v15, v10, v10
	v_fmac_f32_e32 v25, v18, v18
	v_add_f32_e32 v2, v13, v2
	v_add_f32_e32 v3, v24, v3
	v_add_f32_e32 v2, v15, v2
	v_add_f32_e32 v3, v25, v3
	v_add_f32_e32 v12, v2, v3
	v_mov_b32_e32 v13, v12
	s_nop 1
	v_permlane16_swap_b32_e32 v13, v12
	v_cvt_pk_bf16_f32 v2, v8, v9
	v_cvt_pk_bf16_f32 v3, v10, v11
	global_store_dwordx4 v[26:27], v[0:3], off
	s_waitcnt lgkmcnt(0)
	s_nop 0
	v_add_f32_e32 v0, v12, v13
	v_mov_b32_e32 v1, v0
	s_nop 1
	v_permlane32_swap_b32_e32 v1, v0
	v_cvt_pk_bf16_f32 v2, v4, v5
	v_cvt_pk_bf16_f32 v3, v6, v7
	v_cvt_pk_bf16_f32 v4, v20, v21
	v_cvt_pk_bf16_f32 v5, v18, v19
	global_store_dwordx4 v[26:27], v[2:5], off offset:256
	s_and_saveexec_b64 s[46:47], s[4:5]
	s_cbranch_execz .LBB0_1612
	s_waitcnt lgkmcnt(0)
	v_add_f32_e32 v0, v0, v1
	v_mul_f32_e32 v0, 0x4f800000, v0
	v_trunc_f32_e32 v0, v0
	v_mul_f32_e64 v1, |v0|, s62
	v_floor_f32_e32 v1, v1
	v_fma_f32 v2, v1, s63, |v0|
	v_cvt_u32_f32_e32 v0, v2
	v_cvt_u32_f32_e32 v1, v1
	v_lshl_add_u64 v[2:3], v[16:17], 3, s[12:13]
	global_atomic_add_x2 v[2:3], v[0:1], off

; __device__ __forceinline__ unsigned cvtpk(float lo, float hi) { f32x2v_ v = {lo, hi}; bf16x2v_ b = __builtin_convertvector(v, bf16x2v_); return __builtin_bit_cast(unsigned, b); }
; __device__ __forceinline__ void fx_add(float* p, size_t idx, float s) { atomicAdd((unsigned long long*)p + idx, (unsigned long long)(long long)(s * 4294967296.0f)); }
;     __device__ __forceinline__ void operator()(const f32x4 (&acc)[2][2][4][2], const Unit& u, int wr, int wc, int fr, int fq) const {
;         const int row0 = u.pm * BM + wr * 64 + fr, col0 = u.pn * BM + wc * 32 + 8 * fq;
; #pragma unroll
;         for (int ai = 0; ai < 2; ++ai)
; #pragma unroll
;             for (int m = 0; m < 4; ++m) { const int row = row0 + ai * HALF + m * 16; const size_t off = (size_t)row * 1024 + col0; float s = 0.f;
; #pragma unroll
;                 for (int bj = 0; bj < 2; ++bj) { f32x4 a0, a1;
;                     if (xin32) { const float* p = xin32 + off + bj * HALF; a0 = *(const f32x4*)p; a1 = *(const f32x4*)(p + 4); }
;                     else { const u32x4 w = *(const u32x4*)(xb + off + bj * HALF);
;                         a0 = (f32x4){__uint_as_float(w.x << 16), __uint_as_float(w.x & 0xffff0000u), __uint_as_float(w.y << 16), __uint_as_float(w.y & 0xffff0000u)};
;                         a1 = (f32x4){__uint_as_float(w.z << 16), __uint_as_float(w.z & 0xffff0000u), __uint_as_float(w.w << 16), __uint_as_float(w.w & 0xffff0000u)}; }
;                     const f32x4 v0 = a0 + acc[ai][bj][m][0] * alpha, v1 = a1 + acc[ai][bj][m][1] * alpha;
;                     u32x4 w; w.x = cvtpk(v0[0], v0[1]); w.y = cvtpk(v0[2], v0[3]); w.z = cvtpk(v1[0], v1[1]); w.w = cvtpk(v1[2], v1[3]);
;                     *(u32x4*)(xb + off + bj * HALF) = w;
;                     s += (v0[0] * v0[0] + v0[1] * v0[1]) + (v0[2] * v0[2] + v0[3] * v0[3]) + (v1[0] * v1[0] + v1[1] * v1[1]) + (v1[2] * v1[2] + v1[3] * v1[3]); }
;                 s += __shfl_xor(s, 16); s += __shfl_xor(s, 32);
;                 if (fq == 0) fx_add(ssout, row, s); }
.LBB0_1819:
	v_lshl_add_u32 v146, s42, 8, v148
	v_ashrrev_i32_e32 v147, 31, v146
	v_lshl_or_b32 v144, s40, 8, v150
	v_lshlrev_b64 v[156:157], 11, v[146:147]
	v_ashrrev_i32_e32 v145, 31, v144
	v_lshl_add_u64 v[156:157], s[22:23], 0, v[156:157]
	v_lshl_add_u64 v[166:167], v[144:145], 1, v[156:157]
	global_load_dwordx4 v[158:161], v[166:167], off
	global_load_dwordx4 v[162:165], v[166:167], off offset:256
	v_and_b32_e32 v156, 64, v154
	v_xor_b32_e32 v155, 16, v154
	v_add_u32_e32 v156, 64, v156
	v_xor_b32_e32 v157, 32, v154
	v_cmp_lt_i32_e32 vcc, v155, v156
	s_waitcnt vmcnt(0)
	v_lshlrev_b32_e32 v168, 16, v158
	v_cndmask_b32_e32 v155, v154, v155, vcc
	v_cmp_lt_i32_e32 vcc, v157, v156
	v_and_b32_e32 v169, 0xffff0000, v158
	v_lshlrev_b32_e32 v158, 16, v159
	v_and_b32_e32 v159, 0xffff0000, v159
	v_lshlrev_b32_e32 v172, 16, v162
	v_and_b32_e32 v173, 0xffff0000, v162
	v_lshlrev_b32_e32 v162, 16, v163
	v_and_b32_e32 v163, 0xffff0000, v163
	v_cndmask_b32_e32 v157, v154, v157, vcc
	v_lshlrev_b32_e32 v170, 16, v160
	v_and_b32_e32 v171, 0xffff0000, v160
	v_lshlrev_b32_e32 v160, 16, v161
	v_and_b32_e32 v161, 0xffff0000, v161
	v_lshlrev_b32_e32 v174, 16, v164
	v_and_b32_e32 v175, 0xffff0000, v164
	v_lshlrev_b32_e32 v164, 16, v165
	v_and_b32_e32 v165, 0xffff0000, v165
	v_pk_add_f32 v[126:127], v[126:127], v[158:159]
	v_pk_add_f32 v[124:125], v[124:125], v[168:169]
	v_pk_add_f32 v[118:119], v[118:119], v[162:163]
	v_pk_add_f32 v[116:117], v[116:117], v[172:173]
	v_lshlrev_b32_e32 v156, 2, v155
	v_lshlrev_b32_e32 v155, 2, v157
	v_pk_add_f32 v[122:123], v[122:123], v[160:161]
	v_pk_add_f32 v[120:121], v[120:121], v[170:171]
	v_pk_add_f32 v[158:159], v[114:115], v[164:165]
	v_pk_add_f32 v[160:161], v[112:113], v[174:175]
	v_mul_f32_e32 v114, v125, v125
	v_mul_f32_e32 v115, v127, v127
	v_mul_f32_e32 v157, v117, v117
	v_mul_f32_e32 v162, v119, v119
	v_cvt_pk_bf16_f32 v112, v124, v125
	v_mul_f32_e32 v125, v121, v121
	v_mul_f32_e32 v163, v161, v161
	v_fmac_f32_e32 v114, v124, v124
	v_fmac_f32_e32 v115, v126, v126
	v_fmac_f32_e32 v157, v116, v116
	v_fmac_f32_e32 v162, v118, v118
	v_cvt_pk_bf16_f32 v113, v126, v127
	v_mul_f32_e32 v127, v123, v123
	v_mul_f32_e32 v164, v159, v159
	v_fmac_f32_e32 v125, v120, v120
	v_fmac_f32_e32 v163, v160, v160
	v_add_f32_e32 v114, v114, v115
	v_add_f32_e32 v115, v157, v162
	v_fmac_f32_e32 v127, v122, v122
	v_fmac_f32_e32 v164, v158, v158
	v_add_f32_e32 v114, v125, v114
	v_add_f32_e32 v115, v163, v115
	v_add_f32_e32 v114, v127, v114
	v_add_f32_e32 v115, v164, v115
	v_add_f32_e32 v124, v114, v115
	v_mov_b32_e32 v125, v124
	s_nop 1
	v_permlane16_swap_b32_e32 v125, v124
	v_cvt_pk_bf16_f32 v114, v120, v121
	v_cvt_pk_bf16_f32 v115, v122, v123
	global_store_dwordx4 v[166:167], v[112:115], off
	s_waitcnt lgkmcnt(0)
	s_nop 0
	v_add_f32_e32 v112, v124, v125
	v_mov_b32_e32 v113, v112
	s_nop 1
	v_permlane32_swap_b32_e32 v113, v112
	v_cvt_pk_bf16_f32 v114, v116, v117
	v_cvt_pk_bf16_f32 v115, v118, v119
	v_cvt_pk_bf16_f32 v116, v160, v161
	v_cvt_pk_bf16_f32 v117, v158, v159
	global_store_dwordx4 v[166:167], v[114:117], off offset:256
	s_and_saveexec_b64 s[40:41], s[4:5]
	s_cbranch_execz .LBB0_1821
	s_waitcnt lgkmcnt(0)
	v_add_f32_e32 v112, v112, v113
	v_mul_f32_e32 v112, 0x4f800000, v112
	v_trunc_f32_e32 v112, v112
	v_mul_f32_e64 v113, |v112|, s56
	v_floor_f32_e32 v113, v113
	v_fma_f32 v114, v113, s57, |v112|
	v_cvt_u32_f32_e32 v112, v114
	v_cvt_u32_f32_e32 v113, v113
	v_lshl_add_u64 v[114:115], v[146:147], 3, s[0:1]
	global_atomic_add_x2 v[114:115], v[112:113], off
.LBB0_1821:
	s_or_b64 exec, exec, s[40:41]
	v_or_b32_e32 v112, 16, v146
	s_waitcnt lgkmcnt(0)
	v_ashrrev_i32_e32 v113, 31, v112
	v_lshlrev_b64 v[114:115], 11, v[112:113]
	v_lshl_add_u64 v[114:115], s[22:23], 0, v[114:115]
	v_lshl_add_u64 v[122:123], v[144:145], 1, v[114:115]
	global_load_dwordx4 v[114:117], v[122:123], off
	global_load_dwordx4 v[118:121], v[122:123], off offset:256
	s_waitcnt vmcnt(1)
	v_lshlrev_b32_e32 v124, 16, v114
	v_and_b32_e32 v125, 0xffff0000, v114
	v_lshlrev_b32_e32 v114, 16, v115
	v_and_b32_e32 v115, 0xffff0000, v115
	s_waitcnt vmcnt(0)
	v_lshlrev_b32_e32 v158, 16, v118
	v_and_b32_e32 v159, 0xffff0000, v118
	v_lshlrev_b32_e32 v118, 16, v119
	v_and_b32_e32 v119, 0xffff0000, v119
	v_lshlrev_b32_e32 v126, 16, v116
	v_and_b32_e32 v127, 0xffff0000, v116
	v_lshlrev_b32_e32 v116, 16, v117
	v_and_b32_e32 v117, 0xffff0000, v117
	v_lshlrev_b32_e32 v160, 16, v120
	v_and_b32_e32 v161, 0xffff0000, v120
	v_lshlrev_b32_e32 v120, 16, v121
	v_and_b32_e32 v121, 0xffff0000, v121
	v_pk_add_f32 v[110:111], v[110:111], v[114:115]
	v_pk_add_f32 v[108:109], v[108:109], v[124:125]
	v_pk_add_f32 v[102:103], v[102:103], v[118:119]
	v_pk_add_f32 v[100:101], v[100:101], v[158:159]
	v_pk_add_f32 v[106:107], v[106:107], v[116:117]
	v_pk_add_f32 v[104:105], v[104:105], v[126:127]
	v_pk_add_f32 v[114:115], v[98:99], v[120:121]
	v_pk_add_f32 v[116:117], v[96:97], v[160:161]
	v_mul_f32_e32 v98, v109, v109
	v_mul_f32_e32 v99, v111, v111
	v_mul_f32_e32 v118, v101, v101
	v_mul_f32_e32 v119, v103, v103
	v_cvt_pk_bf16_f32 v96, v108, v109
	v_mul_f32_e32 v109, v105, v105
	v_mul_f32_e32 v120, v117, v117
	v_fmac_f32_e32 v98, v108, v108
	v_fmac_f32_e32 v99, v110, v110
	v_fmac_f32_e32 v118, v100, v100
	v_fmac_f32_e32 v119, v102, v102
	v_cvt_pk_bf16_f32 v97, v110, v111
	v_mul_f32_e32 v111, v107, v107
	v_mul_f32_e32 v121, v115, v115
	v_fmac_f32_e32 v109, v104, v104
	v_fmac_f32_e32 v120, v116, v116
	v_add_f32_e32 v98, v98, v99
	v_add_f32_e32 v99, v118, v119
	v_fmac_f32_e32 v111, v106, v106
	v_fmac_f32_e32 v121, v114, v114
	v_add_f32_e32 v98, v109, v98
	v_add_f32_e32 v99, v120, v99
	v_add_f32_e32 v98, v111, v98
	v_add_f32_e32 v99, v121, v99
	v_add_f32_e32 v108, v98, v99
	v_mov_b32_e32 v109, v108
	s_nop 1
	v_permlane16_swap_b32_e32 v109, v108
	v_cvt_pk_bf16_f32 v98, v104, v105
	v_cvt_pk_bf16_f32 v99, v106, v107
	global_store_dwordx4 v[122:123], v[96:99], off
	s_waitcnt lgkmcnt(0)
	s_nop 0
	v_add_f32_e32 v96, v108, v109
	v_mov_b32_e32 v97, v96
	s_nop 1
	v_permlane32_swap_b32_e32 v97, v96
	v_cvt_pk_bf16_f32 v98, v100, v101
	v_cvt_pk_bf16_f32 v99, v102, v103
	v_cvt_pk_bf16_f32 v100, v116, v117
	v_cvt_pk_bf16_f32 v101, v114, v115
	global_store_dwordx4 v[122:123], v[98:101], off offset:256
	s_and_saveexec_b64 s[40:41], s[4:5]
	s_cbranch_execz .LBB0_1823
	s_waitcnt lgkmcnt(0)
	v_add_f32_e32 v96, v96, v97
	v_mul_f32_e32 v96, 0x4f800000, v96
	v_trunc_f32_e32 v96, v96
	v_mul_f32_e64 v97, |v96|, s56
	v_floor_f32_e32 v97, v97
	v_fma_f32 v98, v97, s57, |v96|
	v_cvt_u32_f32_e32 v96, v98
	v_cvt_u32_f32_e32 v97, v97
	v_lshl_add_u64 v[98:99], v[112:113], 3, s[0:1]
	global_atomic_add_x2 v[98:99], v[96:97], off
; __device__ __forceinline__ unsigned cvtpk(float lo, float hi) { f32x2v_ v = {lo, hi}; bf16x2v_ b = __builtin_convertvector(v, bf16x2v_); return __builtin_bit_cast(unsigned, b); }
; __device__ __forceinline__ void fx_add(float* p, size_t idx, float s) { atomicAdd((unsigned long long*)p + idx, (unsigned long long)(long long)(s * 4294967296.0f)); }
;     __device__ __forceinline__ void operator()(const f32x4 (&acc)[2][2][4][2], const Unit& u, int wr, int wc, int fr, int fq) const {
;     ...
;             for (int m = 0; m < 4; ++m) { const int row = row0 + ai * HALF + m * 16; const size_t off = (size_t)row * 1024 + col0; float s = 0.f;
; #pragma unroll
;                 for (int bj = 0; bj < 2; ++bj) { f32x4 a0, a1;
;                     if (xin32) { const float* p = xin32 + off + bj * HALF; a0 = *(const f32x4*)p; a1 = *(const f32x4*)(p + 4); }
;                     else { const u32x4 w = *(const u32x4*)(xb + off + bj * HALF);
;                         a0 = (f32x4){__uint_as_float(w.x << 16), __uint_as_float(w.x & 0xffff0000u), __uint_as_float(w.y << 16), __uint_as_float(w.y & 0xffff0000u)};
;                         a1 = (f32x4){__uint_as_float(w.z << 16), __uint_as_float(w.z & 0xffff0000u), __uint_as_float(w.w << 16), __uint_as_float(w.w & 0xffff0000u)}; }
;                     const f32x4 v0 = a0 + acc[ai][bj][m][0] * alpha, v1 = a1 + acc[ai][bj][m][1] * alpha;
;                     u32x4 w; w.x = cvtpk(v0[0], v0[1]); w.y = cvtpk(v0[2], v0[3]); w.z = cvtpk(v1[0], v1[1]); w.w = cvtpk(v1[2], v1[3]);
;                     *(u32x4*)(xb + off + bj * HALF) = w;
;                     s += (v0[0] * v0[0] + v0[1] * v0[1]) + (v0[2] * v0[2] + v0[3] * v0[3]) + (v1[0] * v1[0] + v1[1] * v1[1]) + (v1[2] * v1[2] + v1[3] * v1[3]); }
;                 s += __shfl_xor(s, 16); s += __shfl_xor(s, 32);
;                 if (fq == 0) fx_add(ssout, row, s); }
.LBB0_1823:
	s_or_b64 exec, exec, s[40:41]
	v_or_b32_e32 v96, 32, v146
	s_waitcnt lgkmcnt(0)
	v_ashrrev_i32_e32 v97, 31, v96
	v_lshlrev_b64 v[98:99], 11, v[96:97]
	v_lshl_add_u64 v[98:99], s[22:23], 0, v[98:99]
	v_lshl_add_u64 v[106:107], v[144:145], 1, v[98:99]
	global_load_dwordx4 v[98:101], v[106:107], off
	global_load_dwordx4 v[102:105], v[106:107], off offset:256
	s_waitcnt vmcnt(1)
	v_lshlrev_b32_e32 v108, 16, v98
	v_and_b32_e32 v109, 0xffff0000, v98
	v_lshlrev_b32_e32 v98, 16, v99
	v_and_b32_e32 v99, 0xffff0000, v99
	s_waitcnt vmcnt(0)
	v_lshlrev_b32_e32 v112, 16, v102
	v_and_b32_e32 v113, 0xffff0000, v102
	v_lshlrev_b32_e32 v102, 16, v103
	v_and_b32_e32 v103, 0xffff0000, v103
	v_lshlrev_b32_e32 v110, 16, v100
	v_and_b32_e32 v111, 0xffff0000, v100
	v_lshlrev_b32_e32 v100, 16, v101
	v_and_b32_e32 v101, 0xffff0000, v101
	v_lshlrev_b32_e32 v114, 16, v104
	v_and_b32_e32 v115, 0xffff0000, v104
	v_lshlrev_b32_e32 v104, 16, v105
	v_and_b32_e32 v105, 0xffff0000, v105
	v_pk_add_f32 v[94:95], v[94:95], v[98:99]
	v_pk_add_f32 v[92:93], v[92:93], v[108:109]
	v_pk_add_f32 v[86:87], v[86:87], v[102:103]
	v_pk_add_f32 v[84:85], v[84:85], v[112:113]
	v_pk_add_f32 v[90:91], v[90:91], v[100:101]
	v_pk_add_f32 v[88:89], v[88:89], v[110:111]
	v_pk_add_f32 v[98:99], v[82:83], v[104:105]
	v_pk_add_f32 v[100:101], v[80:81], v[114:115]
	v_mul_f32_e32 v82, v93, v93
	v_mul_f32_e32 v83, v95, v95
	v_mul_f32_e32 v102, v85, v85
	v_mul_f32_e32 v103, v87, v87
	v_cvt_pk_bf16_f32 v80, v92, v93
	v_mul_f32_e32 v93, v89, v89
	v_mul_f32_e32 v104, v101, v101
	v_fmac_f32_e32 v82, v92, v92
	v_fmac_f32_e32 v83, v94, v94
	v_fmac_f32_e32 v102, v84, v84
	v_fmac_f32_e32 v103, v86, v86
	v_cvt_pk_bf16_f32 v81, v94, v95
	v_mul_f32_e32 v95, v91, v91
	v_mul_f32_e32 v105, v99, v99
	v_fmac_f32_e32 v93, v88, v88
	v_fmac_f32_e32 v104, v100, v100
	v_add_f32_e32 v82, v82, v83
	v_add_f32_e32 v83, v102, v103
	v_fmac_f32_e32 v95, v90, v90
	v_fmac_f32_e32 v105, v98, v98
	v_add_f32_e32 v82, v93, v82
	v_add_f32_e32 v83, v104, v83
	v_add_f32_e32 v82, v95, v82
	v_add_f32_e32 v83, v105, v83
	v_add_f32_e32 v92, v82, v83
	v_mov_b32_e32 v93, v92
	s_nop 1
	v_permlane16_swap_b32_e32 v93, v92
	v_cvt_pk_bf16_f32 v82, v88, v89
	v_cvt_pk_bf16_f32 v83, v90, v91
	global_store_dwordx4 v[106:107], v[80:83], off
	s_waitcnt lgkmcnt(0)
	s_nop 0
	v_add_f32_e32 v80, v92, v93
	v_mov_b32_e32 v81, v80
	s_nop 1
	v_permlane32_swap_b32_e32 v81, v80
	v_cvt_pk_bf16_f32 v82, v84, v85
	v_cvt_pk_bf16_f32 v83, v86, v87
	v_cvt_pk_bf16_f32 v84, v100, v101
	v_cvt_pk_bf16_f32 v85, v98, v99
	global_store_dwordx4 v[106:107], v[82:85], off offset:256
	s_and_saveexec_b64 s[40:41], s[4:5]
	s_cbranch_execz .LBB0_1825
	s_waitcnt lgkmcnt(0)
	v_add_f32_e32 v80, v80, v81
	v_mul_f32_e32 v80, 0x4f800000, v80
	v_trunc_f32_e32 v80, v80
	v_mul_f32_e64 v81, |v80|, s56
	v_floor_f32_e32 v81, v81
	v_fma_f32 v82, v81, s57, |v80|
	v_cvt_u32_f32_e32 v80, v82
	v_cvt_u32_f32_e32 v81, v81
	v_lshl_add_u64 v[82:83], v[96:97], 3, s[0:1]
	global_atomic_add_x2 v[82:83], v[80:81], off
.LBB0_1825:
	s_or_b64 exec, exec, s[40:41]
	v_or_b32_e32 v80, 48, v146
	s_waitcnt lgkmcnt(0)
	v_ashrrev_i32_e32 v81, 31, v80
	v_lshlrev_b64 v[82:83], 11, v[80:81]
	v_lshl_add_u64 v[82:83], s[22:23], 0, v[82:83]
	v_lshl_add_u64 v[90:91], v[144:145], 1, v[82:83]
	global_load_dwordx4 v[82:85], v[90:91], off
	global_load_dwordx4 v[86:89], v[90:91], off offset:256
	s_waitcnt vmcnt(1)
	v_lshlrev_b32_e32 v92, 16, v82
	v_and_b32_e32 v93, 0xffff0000, v82
	v_lshlrev_b32_e32 v82, 16, v83
	v_and_b32_e32 v83, 0xffff0000, v83
	s_waitcnt vmcnt(0)
	v_lshlrev_b32_e32 v96, 16, v86
	v_and_b32_e32 v97, 0xffff0000, v86
	v_lshlrev_b32_e32 v86, 16, v87
	v_and_b32_e32 v87, 0xffff0000, v87
	v_lshlrev_b32_e32 v94, 16, v84
	v_and_b32_e32 v95, 0xffff0000, v84
	v_lshlrev_b32_e32 v84, 16, v85
	v_and_b32_e32 v85, 0xffff0000, v85
	v_lshlrev_b32_e32 v98, 16, v88
	v_and_b32_e32 v99, 0xffff0000, v88
	v_lshlrev_b32_e32 v88, 16, v89
	v_and_b32_e32 v89, 0xffff0000, v89
	v_pk_add_f32 v[78:79], v[78:79], v[82:83]
	v_pk_add_f32 v[76:77], v[76:77], v[92:93]
	v_pk_add_f32 v[70:71], v[70:71], v[86:87]
	v_pk_add_f32 v[68:69], v[68:69], v[96:97]
	v_pk_add_f32 v[74:75], v[74:75], v[84:85]
	v_pk_add_f32 v[72:73], v[72:73], v[94:95]
	v_pk_add_f32 v[82:83], v[66:67], v[88:89]
	v_pk_add_f32 v[84:85], v[64:65], v[98:99]
	v_mul_f32_e32 v66, v77, v77
	v_mul_f32_e32 v67, v79, v79
	v_mul_f32_e32 v86, v69, v69
	v_mul_f32_e32 v87, v71, v71
	v_cvt_pk_bf16_f32 v64, v76, v77
	v_mul_f32_e32 v77, v73, v73
	v_mul_f32_e32 v88, v85, v85
	v_fmac_f32_e32 v66, v76, v76
	v_fmac_f32_e32 v67, v78, v78
	v_fmac_f32_e32 v86, v68, v68
	v_fmac_f32_e32 v87, v70, v70
	v_cvt_pk_bf16_f32 v65, v78, v79
	v_mul_f32_e32 v79, v75, v75
	v_mul_f32_e32 v89, v83, v83
	v_fmac_f32_e32 v77, v72, v72
	v_fmac_f32_e32 v88, v84, v84
	v_add_f32_e32 v66, v66, v67
	v_add_f32_e32 v67, v86, v87
	v_fmac_f32_e32 v79, v74, v74
	v_fmac_f32_e32 v89, v82, v82
	v_add_f32_e32 v66, v77, v66
	v_add_f32_e32 v67, v88, v67
	v_add_f32_e32 v66, v79, v66
	v_add_f32_e32 v67, v89, v67
	v_add_f32_e32 v76, v66, v67
	v_mov_b32_e32 v77, v76
	s_nop 1
	v_permlane16_swap_b32_e32 v77, v76
	v_cvt_pk_bf16_f32 v66, v72, v73
	v_cvt_pk_bf16_f32 v67, v74, v75
	global_store_dwordx4 v[90:91], v[64:67], off
	s_waitcnt lgkmcnt(0)
	s_nop 0
	v_add_f32_e32 v64, v76, v77
	v_mov_b32_e32 v65, v64
	s_nop 1
	v_permlane32_swap_b32_e32 v65, v64
	v_cvt_pk_bf16_f32 v66, v68, v69
	v_cvt_pk_bf16_f32 v67, v70, v71
	v_cvt_pk_bf16_f32 v68, v84, v85
	v_cvt_pk_bf16_f32 v69, v82, v83
	global_store_dwordx4 v[90:91], v[66:69], off offset:256
	s_and_saveexec_b64 s[40:41], s[4:5]
	s_cbranch_execz .LBB0_1827
	s_waitcnt lgkmcnt(0)
	v_add_f32_e32 v64, v64, v65
	v_mul_f32_e32 v64, 0x4f800000, v64
	v_trunc_f32_e32 v64, v64
	v_mul_f32_e64 v65, |v64|, s56
	v_floor_f32_e32 v65, v65
	v_fma_f32 v66, v65, s57, |v64|
	v_cvt_u32_f32_e32 v64, v66
	v_cvt_u32_f32_e32 v65, v65
	v_lshl_add_u64 v[66:67], v[80:81], 3, s[0:1]
	global_atomic_add_x2 v[66:67], v[64:65], off
; __device__ __forceinline__ unsigned cvtpk(float lo, float hi) { f32x2v_ v = {lo, hi}; bf16x2v_ b = __builtin_convertvector(v, bf16x2v_); return __builtin_bit_cast(unsigned, b); }
; __device__ __forceinline__ void fx_add(float* p, size_t idx, float s) { atomicAdd((unsigned long long*)p + idx, (unsigned long long)(long long)(s * 4294967296.0f)); }
;     __device__ __forceinline__ void operator()(const f32x4 (&acc)[2][2][4][2], const Unit& u, int wr, int wc, int fr, int fq) const {
;     ...
;             for (int m = 0; m < 4; ++m) { const int row = row0 + ai * HALF + m * 16; const size_t off = (size_t)row * 1024 + col0; float s = 0.f;
; #pragma unroll
;                 for (int bj = 0; bj < 2; ++bj) { f32x4 a0, a1;
;                     if (xin32) { const float* p = xin32 + off + bj * HALF; a0 = *(const f32x4*)p; a1 = *(const f32x4*)(p + 4); }
;                     else { const u32x4 w = *(const u32x4*)(xb + off + bj * HALF);
;                         a0 = (f32x4){__uint_as_float(w.x << 16), __uint_as_float(w.x & 0xffff0000u), __uint_as_float(w.y << 16), __uint_as_float(w.y & 0xffff0000u)};
;                         a1 = (f32x4){__uint_as_float(w.z << 16), __uint_as_float(w.z & 0xffff0000u), __uint_as_float(w.w << 16), __uint_as_float(w.w & 0xffff0000u)}; }
;                     const f32x4 v0 = a0 + acc[ai][bj][m][0] * alpha, v1 = a1 + acc[ai][bj][m][1] * alpha;
;                     u32x4 w; w.x = cvtpk(v0[0], v0[1]); w.y = cvtpk(v0[2], v0[3]); w.z = cvtpk(v1[0], v1[1]); w.w = cvtpk(v1[2], v1[3]);
;                     *(u32x4*)(xb + off + bj * HALF) = w;
;                     s += (v0[0] * v0[0] + v0[1] * v0[1]) + (v0[2] * v0[2] + v0[3] * v0[3]) + (v1[0] * v1[0] + v1[1] * v1[1]) + (v1[2] * v1[2] + v1[3] * v1[3]); }
;                 s += __shfl_xor(s, 16); s += __shfl_xor(s, 32);
;                 if (fq == 0) fx_add(ssout, row, s); }
.LBB0_1827:
	s_or_b64 exec, exec, s[40:41]
	v_add_u32_e32 v64, 0x80, v146
	s_waitcnt lgkmcnt(0)
	v_ashrrev_i32_e32 v65, 31, v64
	v_lshlrev_b64 v[66:67], 11, v[64:65]
	v_lshl_add_u64 v[66:67], s[22:23], 0, v[66:67]
	v_lshl_add_u64 v[74:75], v[144:145], 1, v[66:67]
	global_load_dwordx4 v[66:69], v[74:75], off
	global_load_dwordx4 v[70:73], v[74:75], off offset:256
	s_waitcnt vmcnt(1)
	v_lshlrev_b32_e32 v76, 16, v66
	v_and_b32_e32 v77, 0xffff0000, v66
	v_lshlrev_b32_e32 v66, 16, v67
	v_and_b32_e32 v67, 0xffff0000, v67
	s_waitcnt vmcnt(0)
	v_lshlrev_b32_e32 v80, 16, v70
	v_and_b32_e32 v81, 0xffff0000, v70
	v_lshlrev_b32_e32 v70, 16, v71
	v_and_b32_e32 v71, 0xffff0000, v71
	v_lshlrev_b32_e32 v78, 16, v68
	v_and_b32_e32 v79, 0xffff0000, v68
	v_lshlrev_b32_e32 v68, 16, v69
	v_and_b32_e32 v69, 0xffff0000, v69
	v_lshlrev_b32_e32 v82, 16, v72
	v_and_b32_e32 v83, 0xffff0000, v72
	v_lshlrev_b32_e32 v72, 16, v73
	v_and_b32_e32 v73, 0xffff0000, v73
	v_pk_add_f32 v[62:63], v[62:63], v[66:67]
	v_pk_add_f32 v[60:61], v[60:61], v[76:77]
	v_pk_add_f32 v[54:55], v[54:55], v[70:71]
	v_pk_add_f32 v[52:53], v[52:53], v[80:81]
	v_pk_add_f32 v[58:59], v[58:59], v[68:69]
	v_pk_add_f32 v[56:57], v[56:57], v[78:79]
	v_pk_add_f32 v[66:67], v[50:51], v[72:73]
	v_pk_add_f32 v[68:69], v[48:49], v[82:83]
	v_mul_f32_e32 v50, v61, v61
	v_mul_f32_e32 v51, v63, v63
	v_mul_f32_e32 v70, v53, v53
	v_mul_f32_e32 v71, v55, v55
	v_cvt_pk_bf16_f32 v48, v60, v61
	v_mul_f32_e32 v61, v57, v57
	v_mul_f32_e32 v72, v69, v69
	v_fmac_f32_e32 v50, v60, v60
	v_fmac_f32_e32 v51, v62, v62
	v_fmac_f32_e32 v70, v52, v52
	v_fmac_f32_e32 v71, v54, v54
	v_cvt_pk_bf16_f32 v49, v62, v63
	v_mul_f32_e32 v63, v59, v59
	v_mul_f32_e32 v73, v67, v67
	v_fmac_f32_e32 v61, v56, v56
	v_fmac_f32_e32 v72, v68, v68
	v_add_f32_e32 v50, v50, v51
	v_add_f32_e32 v51, v70, v71
	v_fmac_f32_e32 v63, v58, v58
	v_fmac_f32_e32 v73, v66, v66
	v_add_f32_e32 v50, v61, v50
	v_add_f32_e32 v51, v72, v51
	v_add_f32_e32 v50, v63, v50
	v_add_f32_e32 v51, v73, v51
	v_add_f32_e32 v60, v50, v51
	v_mov_b32_e32 v61, v60
	s_nop 1
	v_permlane16_swap_b32_e32 v61, v60
	v_cvt_pk_bf16_f32 v50, v56, v57
	v_cvt_pk_bf16_f32 v51, v58, v59
	global_store_dwordx4 v[74:75], v[48:51], off
	s_waitcnt lgkmcnt(0)
	s_nop 0
	v_add_f32_e32 v48, v60, v61
	v_mov_b32_e32 v49, v48
	s_nop 1
	v_permlane32_swap_b32_e32 v49, v48
	v_cvt_pk_bf16_f32 v50, v52, v53
	v_cvt_pk_bf16_f32 v51, v54, v55
	v_cvt_pk_bf16_f32 v52, v68, v69
	v_cvt_pk_bf16_f32 v53, v66, v67
	global_store_dwordx4 v[74:75], v[50:53], off offset:256
	s_and_saveexec_b64 s[40:41], s[4:5]
	s_cbranch_execz .LBB0_1829
	s_waitcnt lgkmcnt(0)
	v_add_f32_e32 v48, v48, v49
	v_mul_f32_e32 v48, 0x4f800000, v48
	v_trunc_f32_e32 v48, v48
	v_mul_f32_e64 v49, |v48|, s56
	v_floor_f32_e32 v49, v49
	v_fma_f32 v50, v49, s57, |v48|
	v_cvt_u32_f32_e32 v48, v50
	v_cvt_u32_f32_e32 v49, v49
	v_lshl_add_u64 v[50:51], v[64:65], 3, s[0:1]
	global_atomic_add_x2 v[50:51], v[48:49], off
.LBB0_1829:
	s_or_b64 exec, exec, s[40:41]
	v_add_u32_e32 v48, 0x90, v146
	s_waitcnt lgkmcnt(0)
	v_ashrrev_i32_e32 v49, 31, v48
	v_lshlrev_b64 v[50:51], 11, v[48:49]
	v_lshl_add_u64 v[50:51], s[22:23], 0, v[50:51]
	v_lshl_add_u64 v[58:59], v[144:145], 1, v[50:51]
	global_load_dwordx4 v[50:53], v[58:59], off
	global_load_dwordx4 v[54:57], v[58:59], off offset:256
	s_waitcnt vmcnt(1)
	v_lshlrev_b32_e32 v60, 16, v50
	v_and_b32_e32 v61, 0xffff0000, v50
	v_lshlrev_b32_e32 v50, 16, v51
	v_and_b32_e32 v51, 0xffff0000, v51
	s_waitcnt vmcnt(0)
	v_lshlrev_b32_e32 v64, 16, v54
	v_and_b32_e32 v65, 0xffff0000, v54
	v_lshlrev_b32_e32 v54, 16, v55
	v_and_b32_e32 v55, 0xffff0000, v55
	v_lshlrev_b32_e32 v62, 16, v52
	v_and_b32_e32 v63, 0xffff0000, v52
	v_lshlrev_b32_e32 v52, 16, v53
	v_and_b32_e32 v53, 0xffff0000, v53
	v_lshlrev_b32_e32 v66, 16, v56
	v_and_b32_e32 v67, 0xffff0000, v56
	v_lshlrev_b32_e32 v56, 16, v57
	v_and_b32_e32 v57, 0xffff0000, v57
	v_pk_add_f32 v[46:47], v[46:47], v[50:51]
	v_pk_add_f32 v[44:45], v[44:45], v[60:61]
	v_pk_add_f32 v[38:39], v[38:39], v[54:55]
	v_pk_add_f32 v[36:37], v[36:37], v[64:65]
	v_pk_add_f32 v[42:43], v[42:43], v[52:53]
	v_pk_add_f32 v[40:41], v[40:41], v[62:63]
	v_pk_add_f32 v[50:51], v[34:35], v[56:57]
	v_pk_add_f32 v[52:53], v[32:33], v[66:67]
	v_mul_f32_e32 v34, v45, v45
	v_mul_f32_e32 v35, v47, v47
	v_mul_f32_e32 v54, v37, v37
	v_mul_f32_e32 v55, v39, v39
	v_cvt_pk_bf16_f32 v32, v44, v45
	v_mul_f32_e32 v45, v41, v41
	v_mul_f32_e32 v56, v53, v53
	v_fmac_f32_e32 v34, v44, v44
	v_fmac_f32_e32 v35, v46, v46
	v_fmac_f32_e32 v54, v36, v36
	v_fmac_f32_e32 v55, v38, v38
	v_cvt_pk_bf16_f32 v33, v46, v47
	v_mul_f32_e32 v47, v43, v43
	v_mul_f32_e32 v57, v51, v51
	v_fmac_f32_e32 v45, v40, v40
	v_fmac_f32_e32 v56, v52, v52
	v_add_f32_e32 v34, v34, v35
	v_add_f32_e32 v35, v54, v55
	v_fmac_f32_e32 v47, v42, v42
	v_fmac_f32_e32 v57, v50, v50
	v_add_f32_e32 v34, v45, v34
	v_add_f32_e32 v35, v56, v35
	v_add_f32_e32 v34, v47, v34
	v_add_f32_e32 v35, v57, v35
	v_add_f32_e32 v44, v34, v35
	v_mov_b32_e32 v45, v44
	s_nop 1
	v_permlane16_swap_b32_e32 v45, v44
	v_cvt_pk_bf16_f32 v34, v40, v41
	v_cvt_pk_bf16_f32 v35, v42, v43
	global_store_dwordx4 v[58:59], v[32:35], off
	s_waitcnt lgkmcnt(0)
	s_nop 0
	v_add_f32_e32 v32, v44, v45
	v_mov_b32_e32 v33, v32
	s_nop 1
	v_permlane32_swap_b32_e32 v33, v32
	v_cvt_pk_bf16_f32 v34, v36, v37
	v_cvt_pk_bf16_f32 v35, v38, v39
	v_cvt_pk_bf16_f32 v36, v52, v53
	v_cvt_pk_bf16_f32 v37, v50, v51
	global_store_dwordx4 v[58:59], v[34:37], off offset:256
	s_and_saveexec_b64 s[40:41], s[4:5]
	s_cbranch_execz .LBB0_1831
	s_waitcnt lgkmcnt(0)
	v_add_f32_e32 v32, v32, v33
	v_mul_f32_e32 v32, 0x4f800000, v32
	v_trunc_f32_e32 v32, v32
	v_mul_f32_e64 v33, |v32|, s56
	v_floor_f32_e32 v33, v33
	v_fma_f32 v34, v33, s57, |v32|
	v_cvt_u32_f32_e32 v32, v34
	v_cvt_u32_f32_e32 v33, v33
	v_lshl_add_u64 v[34:35], v[48:49], 3, s[0:1]
	global_atomic_add_x2 v[34:35], v[32:33], off
; __device__ __forceinline__ unsigned cvtpk(float lo, float hi) { f32x2v_ v = {lo, hi}; bf16x2v_ b = __builtin_convertvector(v, bf16x2v_); return __builtin_bit_cast(unsigned, b); }
; __device__ __forceinline__ void fx_add(float* p, size_t idx, float s) { atomicAdd((unsigned long long*)p + idx, (unsigned long long)(long long)(s * 4294967296.0f)); }
;     __device__ __forceinline__ void operator()(const f32x4 (&acc)[2][2][4][2], const Unit& u, int wr, int wc, int fr, int fq) const {
;     ...
;             for (int m = 0; m < 4; ++m) { const int row = row0 + ai * HALF + m * 16; const size_t off = (size_t)row * 1024 + col0; float s = 0.f;
; #pragma unroll
;                 for (int bj = 0; bj < 2; ++bj) { f32x4 a0, a1;
;                     if (xin32) { const float* p = xin32 + off + bj * HALF; a0 = *(const f32x4*)p; a1 = *(const f32x4*)(p + 4); }
;                     else { const u32x4 w = *(const u32x4*)(xb + off + bj * HALF);
;                         a0 = (f32x4){__uint_as_float(w.x << 16), __uint_as_float(w.x & 0xffff0000u), __uint_as_float(w.y << 16), __uint_as_float(w.y & 0xffff0000u)};
;                         a1 = (f32x4){__uint_as_float(w.z << 16), __uint_as_float(w.z & 0xffff0000u), __uint_as_float(w.w << 16), __uint_as_float(w.w & 0xffff0000u)}; }
;                     const f32x4 v0 = a0 + acc[ai][bj][m][0] * alpha, v1 = a1 + acc[ai][bj][m][1] * alpha;
;                     u32x4 w; w.x = cvtpk(v0[0], v0[1]); w.y = cvtpk(v0[2], v0[3]); w.z = cvtpk(v1[0], v1[1]); w.w = cvtpk(v1[2], v1[3]);
;                     *(u32x4*)(xb + off + bj * HALF) = w;
;                     s += (v0[0] * v0[0] + v0[1] * v0[1]) + (v0[2] * v0[2] + v0[3] * v0[3]) + (v1[0] * v1[0] + v1[1] * v1[1]) + (v1[2] * v1[2] + v1[3] * v1[3]); }
;                 s += __shfl_xor(s, 16); s += __shfl_xor(s, 32);
;                 if (fq == 0) fx_add(ssout, row, s); }
.LBB0_1831:
	s_or_b64 exec, exec, s[40:41]
	v_add_u32_e32 v32, 0xa0, v146
	s_waitcnt lgkmcnt(0)
	v_ashrrev_i32_e32 v33, 31, v32
	v_lshlrev_b64 v[34:35], 11, v[32:33]
	v_lshl_add_u64 v[34:35], s[22:23], 0, v[34:35]
	v_lshl_add_u64 v[42:43], v[144:145], 1, v[34:35]
	global_load_dwordx4 v[34:37], v[42:43], off
	global_load_dwordx4 v[38:41], v[42:43], off offset:256
	s_waitcnt vmcnt(1)
	v_lshlrev_b32_e32 v44, 16, v34
	v_and_b32_e32 v45, 0xffff0000, v34
	v_lshlrev_b32_e32 v34, 16, v35
	v_and_b32_e32 v35, 0xffff0000, v35
	s_waitcnt vmcnt(0)
	v_lshlrev_b32_e32 v48, 16, v38
	v_and_b32_e32 v49, 0xffff0000, v38
	v_lshlrev_b32_e32 v38, 16, v39
	v_and_b32_e32 v39, 0xffff0000, v39
	v_lshlrev_b32_e32 v46, 16, v36
	v_and_b32_e32 v47, 0xffff0000, v36
	v_lshlrev_b32_e32 v36, 16, v37
	v_and_b32_e32 v37, 0xffff0000, v37
	v_lshlrev_b32_e32 v50, 16, v40
	v_and_b32_e32 v51, 0xffff0000, v40
	v_lshlrev_b32_e32 v40, 16, v41
	v_and_b32_e32 v41, 0xffff0000, v41
	v_pk_add_f32 v[30:31], v[30:31], v[34:35]
	v_pk_add_f32 v[28:29], v[28:29], v[44:45]
	v_pk_add_f32 v[22:23], v[22:23], v[38:39]
	v_pk_add_f32 v[20:21], v[20:21], v[48:49]
	v_pk_add_f32 v[26:27], v[26:27], v[36:37]
	v_pk_add_f32 v[24:25], v[24:25], v[46:47]
	v_pk_add_f32 v[34:35], v[18:19], v[40:41]
	v_pk_add_f32 v[36:37], v[16:17], v[50:51]
	v_mul_f32_e32 v18, v29, v29
	v_mul_f32_e32 v19, v31, v31
	v_mul_f32_e32 v38, v21, v21
	v_mul_f32_e32 v39, v23, v23
	v_cvt_pk_bf16_f32 v16, v28, v29
	v_mul_f32_e32 v29, v25, v25
	v_mul_f32_e32 v40, v37, v37
	v_fmac_f32_e32 v18, v28, v28
	v_fmac_f32_e32 v19, v30, v30
	v_fmac_f32_e32 v38, v20, v20
	v_fmac_f32_e32 v39, v22, v22
	v_cvt_pk_bf16_f32 v17, v30, v31
	v_mul_f32_e32 v31, v27, v27
	v_mul_f32_e32 v41, v35, v35
	v_fmac_f32_e32 v29, v24, v24
	v_fmac_f32_e32 v40, v36, v36
	v_add_f32_e32 v18, v18, v19
	v_add_f32_e32 v19, v38, v39
	v_fmac_f32_e32 v31, v26, v26
	v_fmac_f32_e32 v41, v34, v34
	v_add_f32_e32 v18, v29, v18
	v_add_f32_e32 v19, v40, v19
	v_add_f32_e32 v18, v31, v18
	v_add_f32_e32 v19, v41, v19
	v_add_f32_e32 v28, v18, v19
	v_mov_b32_e32 v29, v28
	s_nop 1
	v_permlane16_swap_b32_e32 v29, v28
	v_cvt_pk_bf16_f32 v18, v24, v25
	v_cvt_pk_bf16_f32 v19, v26, v27
	global_store_dwordx4 v[42:43], v[16:19], off
	s_waitcnt lgkmcnt(0)
	s_nop 0
	v_add_f32_e32 v16, v28, v29
	v_mov_b32_e32 v17, v16
	s_nop 1
	v_permlane32_swap_b32_e32 v17, v16
	v_cvt_pk_bf16_f32 v18, v20, v21
	v_cvt_pk_bf16_f32 v19, v22, v23
	v_cvt_pk_bf16_f32 v20, v36, v37
	v_cvt_pk_bf16_f32 v21, v34, v35
	global_store_dwordx4 v[42:43], v[18:21], off offset:256
	s_and_saveexec_b64 s[40:41], s[4:5]
	s_cbranch_execz .LBB0_1833
	s_waitcnt lgkmcnt(0)
	v_add_f32_e32 v16, v16, v17
	v_mul_f32_e32 v16, 0x4f800000, v16
	v_trunc_f32_e32 v16, v16
	v_mul_f32_e64 v17, |v16|, s56
	v_floor_f32_e32 v17, v17
	v_fma_f32 v18, v17, s57, |v16|
	v_cvt_u32_f32_e32 v16, v18
	v_cvt_u32_f32_e32 v17, v17
	v_lshl_add_u64 v[18:19], v[32:33], 3, s[0:1]
	global_atomic_add_x2 v[18:19], v[16:17], off
.LBB0_1833:
	s_or_b64 exec, exec, s[40:41]
	v_add_u32_e32 v16, 0xb0, v146
	s_waitcnt lgkmcnt(0)
	v_ashrrev_i32_e32 v17, 31, v16
	v_lshlrev_b64 v[18:19], 11, v[16:17]
	v_lshl_add_u64 v[18:19], s[22:23], 0, v[18:19]
	v_lshl_add_u64 v[26:27], v[144:145], 1, v[18:19]
	global_load_dwordx4 v[18:21], v[26:27], off
	global_load_dwordx4 v[22:25], v[26:27], off offset:256
	s_waitcnt vmcnt(1)
	v_lshlrev_b32_e32 v28, 16, v18
	v_and_b32_e32 v29, 0xffff0000, v18
	v_lshlrev_b32_e32 v18, 16, v19
	v_and_b32_e32 v19, 0xffff0000, v19
	s_waitcnt vmcnt(0)
	v_lshlrev_b32_e32 v32, 16, v22
	v_and_b32_e32 v33, 0xffff0000, v22
	v_lshlrev_b32_e32 v22, 16, v23
	v_and_b32_e32 v23, 0xffff0000, v23
	v_lshlrev_b32_e32 v30, 16, v20
	v_and_b32_e32 v31, 0xffff0000, v20
	v_lshlrev_b32_e32 v20, 16, v21
	v_and_b32_e32 v21, 0xffff0000, v21
	v_lshlrev_b32_e32 v34, 16, v24
	v_and_b32_e32 v35, 0xffff0000, v24
	v_lshlrev_b32_e32 v24, 16, v25
	v_and_b32_e32 v25, 0xffff0000, v25
	v_pk_add_f32 v[14:15], v[14:15], v[18:19]
	v_pk_add_f32 v[12:13], v[12:13], v[28:29]
	v_pk_add_f32 v[6:7], v[6:7], v[22:23]
	v_pk_add_f32 v[4:5], v[4:5], v[32:33]
	v_pk_add_f32 v[10:11], v[10:11], v[20:21]
	v_pk_add_f32 v[8:9], v[8:9], v[30:31]
	v_pk_add_f32 v[18:19], v[2:3], v[24:25]
	v_pk_add_f32 v[20:21], v[0:1], v[34:35]
	v_mul_f32_e32 v2, v13, v13
	v_mul_f32_e32 v3, v15, v15
	v_mul_f32_e32 v22, v5, v5
	v_mul_f32_e32 v23, v7, v7
	v_cvt_pk_bf16_f32 v0, v12, v13
	v_mul_f32_e32 v13, v9, v9
	v_mul_f32_e32 v24, v21, v21
	v_fmac_f32_e32 v2, v12, v12
	v_fmac_f32_e32 v3, v14, v14
	v_fmac_f32_e32 v22, v4, v4
	v_fmac_f32_e32 v23, v6, v6
	v_cvt_pk_bf16_f32 v1, v14, v15
	v_mul_f32_e32 v15, v11, v11
	v_mul_f32_e32 v25, v19, v19
	v_fmac_f32_e32 v13, v8, v8
	v_fmac_f32_e32 v24, v20, v20
	v_add_f32_e32 v2, v2, v3
	v_add_f32_e32 v3, v22, v23
	v_fmac_f32_e32 v15, v10, v10
	v_fmac_f32_e32 v25, v18, v18
	v_add_f32_e32 v2, v13, v2
	v_add_f32_e32 v3, v24, v3
	v_add_f32_e32 v2, v15, v2
	v_add_f32_e32 v3, v25, v3
	v_add_f32_e32 v12, v2, v3
	v_mov_b32_e32 v13, v12
	s_nop 1
	v_permlane16_swap_b32_e32 v13, v12
	v_cvt_pk_bf16_f32 v2, v8, v9
	v_cvt_pk_bf16_f32 v3, v10, v11
	global_store_dwordx4 v[26:27], v[0:3], off
	s_waitcnt lgkmcnt(0)
	s_nop 0
	v_add_f32_e32 v0, v12, v13
	v_mov_b32_e32 v1, v0
	s_nop 1
	v_permlane32_swap_b32_e32 v1, v0
	v_cvt_pk_bf16_f32 v2, v4, v5
	v_cvt_pk_bf16_f32 v3, v6, v7
	v_cvt_pk_bf16_f32 v4, v20, v21
	v_cvt_pk_bf16_f32 v5, v18, v19
	global_store_dwordx4 v[26:27], v[2:5], off offset:256
	s_and_saveexec_b64 s[40:41], s[4:5]
	s_cbranch_execz .LBB0_1835
	s_waitcnt lgkmcnt(0)
	v_add_f32_e32 v0, v0, v1
	v_mul_f32_e32 v0, 0x4f800000, v0
	v_trunc_f32_e32 v0, v0
	v_mul_f32_e64 v1, |v0|, s56
	v_floor_f32_e32 v1, v1
	v_fma_f32 v2, v1, s57, |v0|
	v_cvt_u32_f32_e32 v0, v2
	v_cvt_u32_f32_e32 v1, v1
	v_lshl_add_u64 v[2:3], v[16:17], 3, s[0:1]
	global_atomic_add_x2 v[2:3], v[0:1], off

; __device__ __forceinline__ unsigned cvtpk(float lo, float hi) { f32x2v_ v = {lo, hi}; bf16x2v_ b = __builtin_convertvector(v, bf16x2v_); return __builtin_bit_cast(unsigned, b); }
; __device__ __forceinline__ void fx_add(float* p, size_t idx, float s) { atomicAdd((unsigned long long*)p + idx, (unsigned long long)(long long)(s * 4294967296.0f)); }
;     __device__ __forceinline__ void operator()(const f32x4 (&acc)[2][2][4][2], const Unit& u, int wr, int wc, int fr, int fq) const {
;         const int row0 = u.pm * BM + wr * 64 + fr, col0 = u.pn * BM + wc * 32 + 8 * fq;
; #pragma unroll
;         for (int ai = 0; ai < 2; ++ai)
; #pragma unroll
;             for (int m = 0; m < 4; ++m) { const int row = row0 + ai * HALF + m * 16; const size_t off = (size_t)row * 1024 + col0; float s = 0.f;
; #pragma unroll
;                 for (int bj = 0; bj < 2; ++bj) { f32x4 a0, a1;
;                     if (xin32) { const float* p = xin32 + off + bj * HALF; a0 = *(const f32x4*)p; a1 = *(const f32x4*)(p + 4); }
;                     else { const u32x4 w = *(const u32x4*)(xb + off + bj * HALF);
;                         a0 = (f32x4){__uint_as_float(w.x << 16), __uint_as_float(w.x & 0xffff0000u), __uint_as_float(w.y << 16), __uint_as_float(w.y & 0xffff0000u)};
;                         a1 = (f32x4){__uint_as_float(w.z << 16), __uint_as_float(w.z & 0xffff0000u), __uint_as_float(w.w << 16), __uint_as_float(w.w & 0xffff0000u)}; }
;                     const f32x4 v0 = a0 + acc[ai][bj][m][0] * alpha, v1 = a1 + acc[ai][bj][m][1] * alpha;
;                     u32x4 w; w.x = cvtpk(v0[0], v0[1]); w.y = cvtpk(v0[2], v0[3]); w.z = cvtpk(v1[0], v1[1]); w.w = cvtpk(v1[2], v1[3]);
;                     *(u32x4*)(xb + off + bj * HALF) = w;
;                     s += (v0[0] * v0[0] + v0[1] * v0[1]) + (v0[2] * v0[2] + v0[3] * v0[3]) + (v1[0] * v1[0] + v1[1] * v1[1]) + (v1[2] * v1[2] + v1[3] * v1[3]); }
;                 s += __shfl_xor(s, 16); s += __shfl_xor(s, 32);
;                 if (fq == 0) fx_add(ssout, row, s); }
.LBB0_1981:
	v_lshl_add_u32 v146, s52, 8, v148
	v_ashrrev_i32_e32 v147, 31, v146
	v_lshl_or_b32 v144, s51, 8, v150
	v_lshlrev_b64 v[156:157], 11, v[146:147]
	v_ashrrev_i32_e32 v145, 31, v144
	v_lshl_add_u64 v[156:157], s[22:23], 0, v[156:157]
	v_lshl_add_u64 v[166:167], v[144:145], 1, v[156:157]
	global_load_dwordx4 v[158:161], v[166:167], off
	global_load_dwordx4 v[162:165], v[166:167], off offset:256
	v_and_b32_e32 v156, 64, v154
	v_xor_b32_e32 v155, 16, v154
	v_add_u32_e32 v156, 64, v156
	v_xor_b32_e32 v157, 32, v154
	v_cmp_lt_i32_e32 vcc, v155, v156
	s_waitcnt vmcnt(0)
	v_lshlrev_b32_e32 v168, 16, v158
	v_cndmask_b32_e32 v155, v154, v155, vcc
	v_cmp_lt_i32_e32 vcc, v157, v156
	v_and_b32_e32 v169, 0xffff0000, v158
	v_lshlrev_b32_e32 v158, 16, v159
	v_and_b32_e32 v159, 0xffff0000, v159
	v_lshlrev_b32_e32 v172, 16, v162
	v_and_b32_e32 v173, 0xffff0000, v162
	v_lshlrev_b32_e32 v162, 16, v163
	v_and_b32_e32 v163, 0xffff0000, v163
	v_cndmask_b32_e32 v157, v154, v157, vcc
	v_lshlrev_b32_e32 v170, 16, v160
	v_and_b32_e32 v171, 0xffff0000, v160
	v_lshlrev_b32_e32 v160, 16, v161
	v_and_b32_e32 v161, 0xffff0000, v161
	v_lshlrev_b32_e32 v174, 16, v164
	v_and_b32_e32 v175, 0xffff0000, v164
	v_lshlrev_b32_e32 v164, 16, v165
	v_and_b32_e32 v165, 0xffff0000, v165
	v_pk_fma_f32 v[126:127], v[126:127], 0.5, v[158:159] op_sel_hi:[1,0,1]
	v_pk_fma_f32 v[124:125], v[124:125], 0.5, v[168:169] op_sel_hi:[1,0,1]
	v_pk_fma_f32 v[118:119], v[118:119], 0.5, v[162:163] op_sel_hi:[1,0,1]
	v_pk_fma_f32 v[116:117], v[116:117], 0.5, v[172:173] op_sel_hi:[1,0,1]
	v_lshlrev_b32_e32 v156, 2, v155
	v_lshlrev_b32_e32 v155, 2, v157
	v_pk_fma_f32 v[122:123], v[122:123], 0.5, v[160:161] op_sel_hi:[1,0,1]
	v_pk_fma_f32 v[120:121], v[120:121], 0.5, v[170:171] op_sel_hi:[1,0,1]
	v_pk_fma_f32 v[158:159], v[114:115], 0.5, v[164:165] op_sel_hi:[1,0,1]
	v_pk_fma_f32 v[160:161], v[112:113], 0.5, v[174:175] op_sel_hi:[1,0,1]
	v_mul_f32_e32 v114, v125, v125
	v_mul_f32_e32 v115, v127, v127
	v_mul_f32_e32 v157, v117, v117
	v_mul_f32_e32 v162, v119, v119
	v_cvt_pk_bf16_f32 v112, v124, v125
	v_mul_f32_e32 v125, v121, v121
	v_mul_f32_e32 v163, v161, v161
	v_fmac_f32_e32 v114, v124, v124
	v_fmac_f32_e32 v115, v126, v126
	v_fmac_f32_e32 v157, v116, v116
	v_fmac_f32_e32 v162, v118, v118
	v_cvt_pk_bf16_f32 v113, v126, v127
	v_mul_f32_e32 v127, v123, v123
	v_mul_f32_e32 v164, v159, v159
	v_fmac_f32_e32 v125, v120, v120
	v_fmac_f32_e32 v163, v160, v160
	v_add_f32_e32 v114, v114, v115
	v_add_f32_e32 v115, v157, v162
	v_fmac_f32_e32 v127, v122, v122
	v_fmac_f32_e32 v164, v158, v158
	v_add_f32_e32 v114, v125, v114
	v_add_f32_e32 v115, v163, v115
	v_add_f32_e32 v114, v127, v114
	v_add_f32_e32 v115, v164, v115
	v_add_f32_e32 v124, v114, v115
	v_mov_b32_e32 v125, v124
	s_nop 1
	v_permlane16_swap_b32_e32 v125, v124
	v_cvt_pk_bf16_f32 v114, v120, v121
	v_cvt_pk_bf16_f32 v115, v122, v123
	global_store_dwordx4 v[166:167], v[112:115], off
	s_waitcnt lgkmcnt(0)
	s_nop 0
	v_add_f32_e32 v112, v124, v125
	v_mov_b32_e32 v113, v112
	s_nop 1
	v_permlane32_swap_b32_e32 v113, v112
	v_cvt_pk_bf16_f32 v114, v116, v117
	v_cvt_pk_bf16_f32 v115, v118, v119
	v_cvt_pk_bf16_f32 v116, v160, v161
	v_cvt_pk_bf16_f32 v117, v158, v159
	global_store_dwordx4 v[166:167], v[114:117], off offset:256
	s_and_saveexec_b64 s[26:27], s[6:7]
	s_cbranch_execz .LBB0_1983
	s_waitcnt lgkmcnt(0)
	v_add_f32_e32 v112, v112, v113
	v_mul_f32_e32 v112, 0x4f800000, v112
	v_trunc_f32_e32 v112, v112
	v_mul_f32_e64 v113, |v112|, s47
	v_floor_f32_e32 v113, v113
	v_fma_f32 v114, v113, s48, |v112|
	v_cvt_u32_f32_e32 v112, v114
	v_cvt_u32_f32_e32 v113, v113
	v_lshl_add_u64 v[114:115], v[146:147], 3, s[10:11]
	global_atomic_add_x2 v[114:115], v[112:113], off
.LBB0_1983:
	s_or_b64 exec, exec, s[26:27]
	v_or_b32_e32 v112, 16, v146
	s_waitcnt lgkmcnt(0)
	v_ashrrev_i32_e32 v113, 31, v112
	v_lshlrev_b64 v[114:115], 11, v[112:113]
	v_lshl_add_u64 v[114:115], s[22:23], 0, v[114:115]
	v_lshl_add_u64 v[122:123], v[144:145], 1, v[114:115]
	global_load_dwordx4 v[114:117], v[122:123], off
	global_load_dwordx4 v[118:121], v[122:123], off offset:256
	s_waitcnt vmcnt(1)
	v_lshlrev_b32_e32 v124, 16, v114
	v_and_b32_e32 v125, 0xffff0000, v114
	v_lshlrev_b32_e32 v114, 16, v115
	v_and_b32_e32 v115, 0xffff0000, v115
	s_waitcnt vmcnt(0)
	v_lshlrev_b32_e32 v158, 16, v118
	v_and_b32_e32 v159, 0xffff0000, v118
	v_lshlrev_b32_e32 v118, 16, v119
	v_and_b32_e32 v119, 0xffff0000, v119
	v_lshlrev_b32_e32 v126, 16, v116
	v_and_b32_e32 v127, 0xffff0000, v116
	v_lshlrev_b32_e32 v116, 16, v117
	v_and_b32_e32 v117, 0xffff0000, v117
	v_lshlrev_b32_e32 v160, 16, v120
	v_and_b32_e32 v161, 0xffff0000, v120
	v_lshlrev_b32_e32 v120, 16, v121
	v_and_b32_e32 v121, 0xffff0000, v121
	v_pk_fma_f32 v[110:111], v[110:111], 0.5, v[114:115] op_sel_hi:[1,0,1]
	v_pk_fma_f32 v[108:109], v[108:109], 0.5, v[124:125] op_sel_hi:[1,0,1]
	v_pk_fma_f32 v[102:103], v[102:103], 0.5, v[118:119] op_sel_hi:[1,0,1]
	v_pk_fma_f32 v[100:101], v[100:101], 0.5, v[158:159] op_sel_hi:[1,0,1]
	v_pk_fma_f32 v[106:107], v[106:107], 0.5, v[116:117] op_sel_hi:[1,0,1]
	v_pk_fma_f32 v[104:105], v[104:105], 0.5, v[126:127] op_sel_hi:[1,0,1]
	v_pk_fma_f32 v[114:115], v[98:99], 0.5, v[120:121] op_sel_hi:[1,0,1]
	v_pk_fma_f32 v[116:117], v[96:97], 0.5, v[160:161] op_sel_hi:[1,0,1]
	v_mul_f32_e32 v98, v109, v109
	v_mul_f32_e32 v99, v111, v111
	v_mul_f32_e32 v118, v101, v101
	v_mul_f32_e32 v119, v103, v103
	v_cvt_pk_bf16_f32 v96, v108, v109
	v_mul_f32_e32 v109, v105, v105
	v_mul_f32_e32 v120, v117, v117
	v_fmac_f32_e32 v98, v108, v108
	v_fmac_f32_e32 v99, v110, v110
	v_fmac_f32_e32 v118, v100, v100
	v_fmac_f32_e32 v119, v102, v102
	v_cvt_pk_bf16_f32 v97, v110, v111
	v_mul_f32_e32 v111, v107, v107
	v_mul_f32_e32 v121, v115, v115
	v_fmac_f32_e32 v109, v104, v104
	v_fmac_f32_e32 v120, v116, v116
	v_add_f32_e32 v98, v98, v99
	v_add_f32_e32 v99, v118, v119
	v_fmac_f32_e32 v111, v106, v106
	v_fmac_f32_e32 v121, v114, v114
	v_add_f32_e32 v98, v109, v98
	v_add_f32_e32 v99, v120, v99
	v_add_f32_e32 v98, v111, v98
	v_add_f32_e32 v99, v121, v99
	v_add_f32_e32 v108, v98, v99
	v_mov_b32_e32 v109, v108
	s_nop 1
	v_permlane16_swap_b32_e32 v109, v108
	v_cvt_pk_bf16_f32 v98, v104, v105
	v_cvt_pk_bf16_f32 v99, v106, v107
	global_store_dwordx4 v[122:123], v[96:99], off
	s_waitcnt lgkmcnt(0)
	s_nop 0
	v_add_f32_e32 v96, v108, v109
	v_mov_b32_e32 v97, v96
	s_nop 1
	v_permlane32_swap_b32_e32 v97, v96
	v_cvt_pk_bf16_f32 v98, v100, v101
	v_cvt_pk_bf16_f32 v99, v102, v103
	v_cvt_pk_bf16_f32 v100, v116, v117
	v_cvt_pk_bf16_f32 v101, v114, v115
	global_store_dwordx4 v[122:123], v[98:101], off offset:256
	s_and_saveexec_b64 s[26:27], s[6:7]
	s_cbranch_execz .LBB0_1985
	s_waitcnt lgkmcnt(0)
	v_add_f32_e32 v96, v96, v97
	v_mul_f32_e32 v96, 0x4f800000, v96
	v_trunc_f32_e32 v96, v96
	v_mul_f32_e64 v97, |v96|, s47
	v_floor_f32_e32 v97, v97
	v_fma_f32 v98, v97, s48, |v96|
	v_cvt_u32_f32_e32 v96, v98
	v_cvt_u32_f32_e32 v97, v97
	v_lshl_add_u64 v[98:99], v[112:113], 3, s[10:11]
	global_atomic_add_x2 v[98:99], v[96:97], off
; __device__ __forceinline__ unsigned cvtpk(float lo, float hi) { f32x2v_ v = {lo, hi}; bf16x2v_ b = __builtin_convertvector(v, bf16x2v_); return __builtin_bit_cast(unsigned, b); }
; __device__ __forceinline__ void fx_add(float* p, size_t idx, float s) { atomicAdd((unsigned long long*)p + idx, (unsigned long long)(long long)(s * 4294967296.0f)); }
;     __device__ __forceinline__ void operator()(const f32x4 (&acc)[2][2][4][2], const Unit& u, int wr, int wc, int fr, int fq) const {
;     ...
;             for (int m = 0; m < 4; ++m) { const int row = row0 + ai * HALF + m * 16; const size_t off = (size_t)row * 1024 + col0; float s = 0.f;
; #pragma unroll
;                 for (int bj = 0; bj < 2; ++bj) { f32x4 a0, a1;
;                     if (xin32) { const float* p = xin32 + off + bj * HALF; a0 = *(const f32x4*)p; a1 = *(const f32x4*)(p + 4); }
;                     else { const u32x4 w = *(const u32x4*)(xb + off + bj * HALF);
;                         a0 = (f32x4){__uint_as_float(w.x << 16), __uint_as_float(w.x & 0xffff0000u), __uint_as_float(w.y << 16), __uint_as_float(w.y & 0xffff0000u)};
;                         a1 = (f32x4){__uint_as_float(w.z << 16), __uint_as_float(w.z & 0xffff0000u), __uint_as_float(w.w << 16), __uint_as_float(w.w & 0xffff0000u)}; }
;                     const f32x4 v0 = a0 + acc[ai][bj][m][0] * alpha, v1 = a1 + acc[ai][bj][m][1] * alpha;
;                     u32x4 w; w.x = cvtpk(v0[0], v0[1]); w.y = cvtpk(v0[2], v0[3]); w.z = cvtpk(v1[0], v1[1]); w.w = cvtpk(v1[2], v1[3]);
;                     *(u32x4*)(xb + off + bj * HALF) = w;
;                     s += (v0[0] * v0[0] + v0[1] * v0[1]) + (v0[2] * v0[2] + v0[3] * v0[3]) + (v1[0] * v1[0] + v1[1] * v1[1]) + (v1[2] * v1[2] + v1[3] * v1[3]); }
;                 s += __shfl_xor(s, 16); s += __shfl_xor(s, 32);
;                 if (fq == 0) fx_add(ssout, row, s); }
.LBB0_1985:
	s_or_b64 exec, exec, s[26:27]
	v_or_b32_e32 v96, 32, v146
	s_waitcnt lgkmcnt(0)
	v_ashrrev_i32_e32 v97, 31, v96
	v_lshlrev_b64 v[98:99], 11, v[96:97]
	v_lshl_add_u64 v[98:99], s[22:23], 0, v[98:99]
	v_lshl_add_u64 v[106:107], v[144:145], 1, v[98:99]
	global_load_dwordx4 v[98:101], v[106:107], off
	global_load_dwordx4 v[102:105], v[106:107], off offset:256
	s_waitcnt vmcnt(1)
	v_lshlrev_b32_e32 v108, 16, v98
	v_and_b32_e32 v109, 0xffff0000, v98
	v_lshlrev_b32_e32 v98, 16, v99
	v_and_b32_e32 v99, 0xffff0000, v99
	s_waitcnt vmcnt(0)
	v_lshlrev_b32_e32 v112, 16, v102
	v_and_b32_e32 v113, 0xffff0000, v102
	v_lshlrev_b32_e32 v102, 16, v103
	v_and_b32_e32 v103, 0xffff0000, v103
	v_lshlrev_b32_e32 v110, 16, v100
	v_and_b32_e32 v111, 0xffff0000, v100
	v_lshlrev_b32_e32 v100, 16, v101
	v_and_b32_e32 v101, 0xffff0000, v101
	v_lshlrev_b32_e32 v114, 16, v104
	v_and_b32_e32 v115, 0xffff0000, v104
	v_lshlrev_b32_e32 v104, 16, v105
	v_and_b32_e32 v105, 0xffff0000, v105
	v_pk_fma_f32 v[94:95], v[94:95], 0.5, v[98:99] op_sel_hi:[1,0,1]
	v_pk_fma_f32 v[92:93], v[92:93], 0.5, v[108:109] op_sel_hi:[1,0,1]
	v_pk_fma_f32 v[86:87], v[86:87], 0.5, v[102:103] op_sel_hi:[1,0,1]
	v_pk_fma_f32 v[84:85], v[84:85], 0.5, v[112:113] op_sel_hi:[1,0,1]
	v_pk_fma_f32 v[90:91], v[90:91], 0.5, v[100:101] op_sel_hi:[1,0,1]
	v_pk_fma_f32 v[88:89], v[88:89], 0.5, v[110:111] op_sel_hi:[1,0,1]
	v_pk_fma_f32 v[98:99], v[82:83], 0.5, v[104:105] op_sel_hi:[1,0,1]
	v_pk_fma_f32 v[100:101], v[80:81], 0.5, v[114:115] op_sel_hi:[1,0,1]
	v_mul_f32_e32 v82, v93, v93
	v_mul_f32_e32 v83, v95, v95
	v_mul_f32_e32 v102, v85, v85
	v_mul_f32_e32 v103, v87, v87
	v_cvt_pk_bf16_f32 v80, v92, v93
	v_mul_f32_e32 v93, v89, v89
	v_mul_f32_e32 v104, v101, v101
	v_fmac_f32_e32 v82, v92, v92
	v_fmac_f32_e32 v83, v94, v94
	v_fmac_f32_e32 v102, v84, v84
	v_fmac_f32_e32 v103, v86, v86
	v_cvt_pk_bf16_f32 v81, v94, v95
	v_mul_f32_e32 v95, v91, v91
	v_mul_f32_e32 v105, v99, v99
	v_fmac_f32_e32 v93, v88, v88
	v_fmac_f32_e32 v104, v100, v100
	v_add_f32_e32 v82, v82, v83
	v_add_f32_e32 v83, v102, v103
	v_fmac_f32_e32 v95, v90, v90
	v_fmac_f32_e32 v105, v98, v98
	v_add_f32_e32 v82, v93, v82
	v_add_f32_e32 v83, v104, v83
	v_add_f32_e32 v82, v95, v82
	v_add_f32_e32 v83, v105, v83
	v_add_f32_e32 v92, v82, v83
	v_mov_b32_e32 v93, v92
	s_nop 1
	v_permlane16_swap_b32_e32 v93, v92
	v_cvt_pk_bf16_f32 v82, v88, v89
	v_cvt_pk_bf16_f32 v83, v90, v91
	global_store_dwordx4 v[106:107], v[80:83], off
	s_waitcnt lgkmcnt(0)
	s_nop 0
	v_add_f32_e32 v80, v92, v93
	v_mov_b32_e32 v81, v80
	s_nop 1
	v_permlane32_swap_b32_e32 v81, v80
	v_cvt_pk_bf16_f32 v82, v84, v85
	v_cvt_pk_bf16_f32 v83, v86, v87
	v_cvt_pk_bf16_f32 v84, v100, v101
	v_cvt_pk_bf16_f32 v85, v98, v99
	global_store_dwordx4 v[106:107], v[82:85], off offset:256
	s_and_saveexec_b64 s[26:27], s[6:7]
	s_cbranch_execz .LBB0_1987
	s_waitcnt lgkmcnt(0)
	v_add_f32_e32 v80, v80, v81
	v_mul_f32_e32 v80, 0x4f800000, v80
	v_trunc_f32_e32 v80, v80
	v_mul_f32_e64 v81, |v80|, s47
	v_floor_f32_e32 v81, v81
	v_fma_f32 v82, v81, s48, |v80|
	v_cvt_u32_f32_e32 v80, v82
	v_cvt_u32_f32_e32 v81, v81
	v_lshl_add_u64 v[82:83], v[96:97], 3, s[10:11]
	global_atomic_add_x2 v[82:83], v[80:81], off
.LBB0_1987:
	s_or_b64 exec, exec, s[26:27]
	v_or_b32_e32 v80, 48, v146
	s_waitcnt lgkmcnt(0)
	v_ashrrev_i32_e32 v81, 31, v80
	v_lshlrev_b64 v[82:83], 11, v[80:81]
	v_lshl_add_u64 v[82:83], s[22:23], 0, v[82:83]
	v_lshl_add_u64 v[90:91], v[144:145], 1, v[82:83]
	global_load_dwordx4 v[82:85], v[90:91], off
	global_load_dwordx4 v[86:89], v[90:91], off offset:256
	s_waitcnt vmcnt(1)
	v_lshlrev_b32_e32 v92, 16, v82
	v_and_b32_e32 v93, 0xffff0000, v82
	v_lshlrev_b32_e32 v82, 16, v83
	v_and_b32_e32 v83, 0xffff0000, v83
	s_waitcnt vmcnt(0)
	v_lshlrev_b32_e32 v96, 16, v86
	v_and_b32_e32 v97, 0xffff0000, v86
	v_lshlrev_b32_e32 v86, 16, v87
	v_and_b32_e32 v87, 0xffff0000, v87
	v_lshlrev_b32_e32 v94, 16, v84
	v_and_b32_e32 v95, 0xffff0000, v84
	v_lshlrev_b32_e32 v84, 16, v85
	v_and_b32_e32 v85, 0xffff0000, v85
	v_lshlrev_b32_e32 v98, 16, v88
	v_and_b32_e32 v99, 0xffff0000, v88
	v_lshlrev_b32_e32 v88, 16, v89
	v_and_b32_e32 v89, 0xffff0000, v89
	v_pk_fma_f32 v[78:79], v[78:79], 0.5, v[82:83] op_sel_hi:[1,0,1]
	v_pk_fma_f32 v[76:77], v[76:77], 0.5, v[92:93] op_sel_hi:[1,0,1]
	v_pk_fma_f32 v[70:71], v[70:71], 0.5, v[86:87] op_sel_hi:[1,0,1]
	v_pk_fma_f32 v[68:69], v[68:69], 0.5, v[96:97] op_sel_hi:[1,0,1]
	v_pk_fma_f32 v[74:75], v[74:75], 0.5, v[84:85] op_sel_hi:[1,0,1]
	v_pk_fma_f32 v[72:73], v[72:73], 0.5, v[94:95] op_sel_hi:[1,0,1]
	v_pk_fma_f32 v[82:83], v[66:67], 0.5, v[88:89] op_sel_hi:[1,0,1]
	v_pk_fma_f32 v[84:85], v[64:65], 0.5, v[98:99] op_sel_hi:[1,0,1]
	v_mul_f32_e32 v66, v77, v77
	v_mul_f32_e32 v67, v79, v79
	v_mul_f32_e32 v86, v69, v69
	v_mul_f32_e32 v87, v71, v71
	v_cvt_pk_bf16_f32 v64, v76, v77
	v_mul_f32_e32 v77, v73, v73
	v_mul_f32_e32 v88, v85, v85
	v_fmac_f32_e32 v66, v76, v76
	v_fmac_f32_e32 v67, v78, v78
	v_fmac_f32_e32 v86, v68, v68
	v_fmac_f32_e32 v87, v70, v70
	v_cvt_pk_bf16_f32 v65, v78, v79
	v_mul_f32_e32 v79, v75, v75
	v_mul_f32_e32 v89, v83, v83
	v_fmac_f32_e32 v77, v72, v72
	v_fmac_f32_e32 v88, v84, v84
	v_add_f32_e32 v66, v66, v67
	v_add_f32_e32 v67, v86, v87
	v_fmac_f32_e32 v79, v74, v74
	v_fmac_f32_e32 v89, v82, v82
	v_add_f32_e32 v66, v77, v66
	v_add_f32_e32 v67, v88, v67
	v_add_f32_e32 v66, v79, v66
	v_add_f32_e32 v67, v89, v67
	v_add_f32_e32 v76, v66, v67
	v_mov_b32_e32 v77, v76
	s_nop 1
	v_permlane16_swap_b32_e32 v77, v76
	v_cvt_pk_bf16_f32 v66, v72, v73
	v_cvt_pk_bf16_f32 v67, v74, v75
	global_store_dwordx4 v[90:91], v[64:67], off
	s_waitcnt lgkmcnt(0)
	s_nop 0
	v_add_f32_e32 v64, v76, v77
	v_mov_b32_e32 v65, v64
	s_nop 1
	v_permlane32_swap_b32_e32 v65, v64
	v_cvt_pk_bf16_f32 v66, v68, v69
	v_cvt_pk_bf16_f32 v67, v70, v71
	v_cvt_pk_bf16_f32 v68, v84, v85
	v_cvt_pk_bf16_f32 v69, v82, v83
	global_store_dwordx4 v[90:91], v[66:69], off offset:256
	s_and_saveexec_b64 s[26:27], s[6:7]
	s_cbranch_execz .LBB0_1989
	s_waitcnt lgkmcnt(0)
	v_add_f32_e32 v64, v64, v65
	v_mul_f32_e32 v64, 0x4f800000, v64
	v_trunc_f32_e32 v64, v64
	v_mul_f32_e64 v65, |v64|, s47
	v_floor_f32_e32 v65, v65
	v_fma_f32 v66, v65, s48, |v64|
	v_cvt_u32_f32_e32 v64, v66
	v_cvt_u32_f32_e32 v65, v65
	v_lshl_add_u64 v[66:67], v[80:81], 3, s[10:11]
	global_atomic_add_x2 v[66:67], v[64:65], off
; __device__ __forceinline__ unsigned cvtpk(float lo, float hi) { f32x2v_ v = {lo, hi}; bf16x2v_ b = __builtin_convertvector(v, bf16x2v_); return __builtin_bit_cast(unsigned, b); }
; __device__ __forceinline__ void fx_add(float* p, size_t idx, float s) { atomicAdd((unsigned long long*)p + idx, (unsigned long long)(long long)(s * 4294967296.0f)); }
;     __device__ __forceinline__ void operator()(const f32x4 (&acc)[2][2][4][2], const Unit& u, int wr, int wc, int fr, int fq) const {
;     ...
;             for (int m = 0; m < 4; ++m) { const int row = row0 + ai * HALF + m * 16; const size_t off = (size_t)row * 1024 + col0; float s = 0.f;
; #pragma unroll
;                 for (int bj = 0; bj < 2; ++bj) { f32x4 a0, a1;
;                     if (xin32) { const float* p = xin32 + off + bj * HALF; a0 = *(const f32x4*)p; a1 = *(const f32x4*)(p + 4); }
;                     else { const u32x4 w = *(const u32x4*)(xb + off + bj * HALF);
;                         a0 = (f32x4){__uint_as_float(w.x << 16), __uint_as_float(w.x & 0xffff0000u), __uint_as_float(w.y << 16), __uint_as_float(w.y & 0xffff0000u)};
;                         a1 = (f32x4){__uint_as_float(w.z << 16), __uint_as_float(w.z & 0xffff0000u), __uint_as_float(w.w << 16), __uint_as_float(w.w & 0xffff0000u)}; }
;                     const f32x4 v0 = a0 + acc[ai][bj][m][0] * alpha, v1 = a1 + acc[ai][bj][m][1] * alpha;
;                     u32x4 w; w.x = cvtpk(v0[0], v0[1]); w.y = cvtpk(v0[2], v0[3]); w.z = cvtpk(v1[0], v1[1]); w.w = cvtpk(v1[2], v1[3]);
;                     *(u32x4*)(xb + off + bj * HALF) = w;
;                     s += (v0[0] * v0[0] + v0[1] * v0[1]) + (v0[2] * v0[2] + v0[3] * v0[3]) + (v1[0] * v1[0] + v1[1] * v1[1]) + (v1[2] * v1[2] + v1[3] * v1[3]); }
;                 s += __shfl_xor(s, 16); s += __shfl_xor(s, 32);
;                 if (fq == 0) fx_add(ssout, row, s); }
.LBB0_1989:
	s_or_b64 exec, exec, s[26:27]
	v_add_u32_e32 v64, 0x80, v146
	s_waitcnt lgkmcnt(0)
	v_ashrrev_i32_e32 v65, 31, v64
	v_lshlrev_b64 v[66:67], 11, v[64:65]
	v_lshl_add_u64 v[66:67], s[22:23], 0, v[66:67]
	v_lshl_add_u64 v[74:75], v[144:145], 1, v[66:67]
	global_load_dwordx4 v[66:69], v[74:75], off
	global_load_dwordx4 v[70:73], v[74:75], off offset:256
	s_waitcnt vmcnt(1)
	v_lshlrev_b32_e32 v76, 16, v66
	v_and_b32_e32 v77, 0xffff0000, v66
	v_lshlrev_b32_e32 v66, 16, v67
	v_and_b32_e32 v67, 0xffff0000, v67
	s_waitcnt vmcnt(0)
	v_lshlrev_b32_e32 v80, 16, v70
	v_and_b32_e32 v81, 0xffff0000, v70
	v_lshlrev_b32_e32 v70, 16, v71
	v_and_b32_e32 v71, 0xffff0000, v71
	v_lshlrev_b32_e32 v78, 16, v68
	v_and_b32_e32 v79, 0xffff0000, v68
	v_lshlrev_b32_e32 v68, 16, v69
	v_and_b32_e32 v69, 0xffff0000, v69
	v_lshlrev_b32_e32 v82, 16, v72
	v_and_b32_e32 v83, 0xffff0000, v72
	v_lshlrev_b32_e32 v72, 16, v73
	v_and_b32_e32 v73, 0xffff0000, v73
	v_pk_fma_f32 v[62:63], v[62:63], 0.5, v[66:67] op_sel_hi:[1,0,1]
	v_pk_fma_f32 v[60:61], v[60:61], 0.5, v[76:77] op_sel_hi:[1,0,1]
	v_pk_fma_f32 v[54:55], v[54:55], 0.5, v[70:71] op_sel_hi:[1,0,1]
	v_pk_fma_f32 v[52:53], v[52:53], 0.5, v[80:81] op_sel_hi:[1,0,1]
	v_pk_fma_f32 v[58:59], v[58:59], 0.5, v[68:69] op_sel_hi:[1,0,1]
	v_pk_fma_f32 v[56:57], v[56:57], 0.5, v[78:79] op_sel_hi:[1,0,1]
	v_pk_fma_f32 v[66:67], v[50:51], 0.5, v[72:73] op_sel_hi:[1,0,1]
	v_pk_fma_f32 v[68:69], v[48:49], 0.5, v[82:83] op_sel_hi:[1,0,1]
	v_mul_f32_e32 v50, v61, v61
	v_mul_f32_e32 v51, v63, v63
	v_mul_f32_e32 v70, v53, v53
	v_mul_f32_e32 v71, v55, v55
	v_cvt_pk_bf16_f32 v48, v60, v61
	v_mul_f32_e32 v61, v57, v57
	v_mul_f32_e32 v72, v69, v69
	v_fmac_f32_e32 v50, v60, v60
	v_fmac_f32_e32 v51, v62, v62
	v_fmac_f32_e32 v70, v52, v52
	v_fmac_f32_e32 v71, v54, v54
	v_cvt_pk_bf16_f32 v49, v62, v63
	v_mul_f32_e32 v63, v59, v59
	v_mul_f32_e32 v73, v67, v67
	v_fmac_f32_e32 v61, v56, v56
	v_fmac_f32_e32 v72, v68, v68
	v_add_f32_e32 v50, v50, v51
	v_add_f32_e32 v51, v70, v71
	v_fmac_f32_e32 v63, v58, v58
	v_fmac_f32_e32 v73, v66, v66
	v_add_f32_e32 v50, v61, v50
	v_add_f32_e32 v51, v72, v51
	v_add_f32_e32 v50, v63, v50
	v_add_f32_e32 v51, v73, v51
	v_add_f32_e32 v60, v50, v51
	v_mov_b32_e32 v61, v60
	s_nop 1
	v_permlane16_swap_b32_e32 v61, v60
	v_cvt_pk_bf16_f32 v50, v56, v57
	v_cvt_pk_bf16_f32 v51, v58, v59
	global_store_dwordx4 v[74:75], v[48:51], off
	s_waitcnt lgkmcnt(0)
	s_nop 0
	v_add_f32_e32 v48, v60, v61
	v_mov_b32_e32 v49, v48
	s_nop 1
	v_permlane32_swap_b32_e32 v49, v48
	v_cvt_pk_bf16_f32 v50, v52, v53
	v_cvt_pk_bf16_f32 v51, v54, v55
	v_cvt_pk_bf16_f32 v52, v68, v69
	v_cvt_pk_bf16_f32 v53, v66, v67
	global_store_dwordx4 v[74:75], v[50:53], off offset:256
	s_and_saveexec_b64 s[26:27], s[6:7]
	s_cbranch_execz .LBB0_1991
	s_waitcnt lgkmcnt(0)
	v_add_f32_e32 v48, v48, v49
	v_mul_f32_e32 v48, 0x4f800000, v48
	v_trunc_f32_e32 v48, v48
	v_mul_f32_e64 v49, |v48|, s47
	v_floor_f32_e32 v49, v49
	v_fma_f32 v50, v49, s48, |v48|
	v_cvt_u32_f32_e32 v48, v50
	v_cvt_u32_f32_e32 v49, v49
	v_lshl_add_u64 v[50:51], v[64:65], 3, s[10:11]
	global_atomic_add_x2 v[50:51], v[48:49], off
.LBB0_1991:
	s_or_b64 exec, exec, s[26:27]
	v_add_u32_e32 v48, 0x90, v146
	s_waitcnt lgkmcnt(0)
	v_ashrrev_i32_e32 v49, 31, v48
	v_lshlrev_b64 v[50:51], 11, v[48:49]
	v_lshl_add_u64 v[50:51], s[22:23], 0, v[50:51]
	v_lshl_add_u64 v[58:59], v[144:145], 1, v[50:51]
	global_load_dwordx4 v[50:53], v[58:59], off
	global_load_dwordx4 v[54:57], v[58:59], off offset:256
	s_waitcnt vmcnt(1)
	v_lshlrev_b32_e32 v60, 16, v50
	v_and_b32_e32 v61, 0xffff0000, v50
	v_lshlrev_b32_e32 v50, 16, v51
	v_and_b32_e32 v51, 0xffff0000, v51
	s_waitcnt vmcnt(0)
	v_lshlrev_b32_e32 v64, 16, v54
	v_and_b32_e32 v65, 0xffff0000, v54
	v_lshlrev_b32_e32 v54, 16, v55
	v_and_b32_e32 v55, 0xffff0000, v55
	v_lshlrev_b32_e32 v62, 16, v52
	v_and_b32_e32 v63, 0xffff0000, v52
	v_lshlrev_b32_e32 v52, 16, v53
	v_and_b32_e32 v53, 0xffff0000, v53
	v_lshlrev_b32_e32 v66, 16, v56
	v_and_b32_e32 v67, 0xffff0000, v56
	v_lshlrev_b32_e32 v56, 16, v57
	v_and_b32_e32 v57, 0xffff0000, v57
	v_pk_fma_f32 v[46:47], v[46:47], 0.5, v[50:51] op_sel_hi:[1,0,1]
	v_pk_fma_f32 v[44:45], v[44:45], 0.5, v[60:61] op_sel_hi:[1,0,1]
	v_pk_fma_f32 v[38:39], v[38:39], 0.5, v[54:55] op_sel_hi:[1,0,1]
	v_pk_fma_f32 v[36:37], v[36:37], 0.5, v[64:65] op_sel_hi:[1,0,1]
	v_pk_fma_f32 v[42:43], v[42:43], 0.5, v[52:53] op_sel_hi:[1,0,1]
	v_pk_fma_f32 v[40:41], v[40:41], 0.5, v[62:63] op_sel_hi:[1,0,1]
	v_pk_fma_f32 v[50:51], v[34:35], 0.5, v[56:57] op_sel_hi:[1,0,1]
	v_pk_fma_f32 v[52:53], v[32:33], 0.5, v[66:67] op_sel_hi:[1,0,1]
	v_mul_f32_e32 v34, v45, v45
	v_mul_f32_e32 v35, v47, v47
	v_mul_f32_e32 v54, v37, v37
	v_mul_f32_e32 v55, v39, v39
	v_cvt_pk_bf16_f32 v32, v44, v45
	v_mul_f32_e32 v45, v41, v41
	v_mul_f32_e32 v56, v53, v53
	v_fmac_f32_e32 v34, v44, v44
	v_fmac_f32_e32 v35, v46, v46
	v_fmac_f32_e32 v54, v36, v36
	v_fmac_f32_e32 v55, v38, v38
	v_cvt_pk_bf16_f32 v33, v46, v47
	v_mul_f32_e32 v47, v43, v43
	v_mul_f32_e32 v57, v51, v51
	v_fmac_f32_e32 v45, v40, v40
	v_fmac_f32_e32 v56, v52, v52
	v_add_f32_e32 v34, v34, v35
	v_add_f32_e32 v35, v54, v55
	v_fmac_f32_e32 v47, v42, v42
	v_fmac_f32_e32 v57, v50, v50
	v_add_f32_e32 v34, v45, v34
	v_add_f32_e32 v35, v56, v35
	v_add_f32_e32 v34, v47, v34
	v_add_f32_e32 v35, v57, v35
	v_add_f32_e32 v44, v34, v35
	v_mov_b32_e32 v45, v44
	s_nop 1
	v_permlane16_swap_b32_e32 v45, v44
	v_cvt_pk_bf16_f32 v34, v40, v41
	v_cvt_pk_bf16_f32 v35, v42, v43
	global_store_dwordx4 v[58:59], v[32:35], off
	s_waitcnt lgkmcnt(0)
	s_nop 0
	v_add_f32_e32 v32, v44, v45
	v_mov_b32_e32 v33, v32
	s_nop 1
	v_permlane32_swap_b32_e32 v33, v32
	v_cvt_pk_bf16_f32 v34, v36, v37
	v_cvt_pk_bf16_f32 v35, v38, v39
	v_cvt_pk_bf16_f32 v36, v52, v53
	v_cvt_pk_bf16_f32 v37, v50, v51
	global_store_dwordx4 v[58:59], v[34:37], off offset:256
	s_and_saveexec_b64 s[26:27], s[6:7]
	s_cbranch_execz .LBB0_1993
	s_waitcnt lgkmcnt(0)
	v_add_f32_e32 v32, v32, v33
	v_mul_f32_e32 v32, 0x4f800000, v32
	v_trunc_f32_e32 v32, v32
	v_mul_f32_e64 v33, |v32|, s47
	v_floor_f32_e32 v33, v33
	v_fma_f32 v34, v33, s48, |v32|
	v_cvt_u32_f32_e32 v32, v34
	v_cvt_u32_f32_e32 v33, v33
	v_lshl_add_u64 v[34:35], v[48:49], 3, s[10:11]
	global_atomic_add_x2 v[34:35], v[32:33], off
; __device__ __forceinline__ unsigned cvtpk(float lo, float hi) { f32x2v_ v = {lo, hi}; bf16x2v_ b = __builtin_convertvector(v, bf16x2v_); return __builtin_bit_cast(unsigned, b); }
; __device__ __forceinline__ void fx_add(float* p, size_t idx, float s) { atomicAdd((unsigned long long*)p + idx, (unsigned long long)(long long)(s * 4294967296.0f)); }
;     __device__ __forceinline__ void operator()(const f32x4 (&acc)[2][2][4][2], const Unit& u, int wr, int wc, int fr, int fq) const {
;     ...
;             for (int m = 0; m < 4; ++m) { const int row = row0 + ai * HALF + m * 16; const size_t off = (size_t)row * 1024 + col0; float s = 0.f;
; #pragma unroll
;                 for (int bj = 0; bj < 2; ++bj) { f32x4 a0, a1;
;                     if (xin32) { const float* p = xin32 + off + bj * HALF; a0 = *(const f32x4*)p; a1 = *(const f32x4*)(p + 4); }
;                     else { const u32x4 w = *(const u32x4*)(xb + off + bj * HALF);
;                         a0 = (f32x4){__uint_as_float(w.x << 16), __uint_as_float(w.x & 0xffff0000u), __uint_as_float(w.y << 16), __uint_as_float(w.y & 0xffff0000u)};
;                         a1 = (f32x4){__uint_as_float(w.z << 16), __uint_as_float(w.z & 0xffff0000u), __uint_as_float(w.w << 16), __uint_as_float(w.w & 0xffff0000u)}; }
;                     const f32x4 v0 = a0 + acc[ai][bj][m][0] * alpha, v1 = a1 + acc[ai][bj][m][1] * alpha;
;                     u32x4 w; w.x = cvtpk(v0[0], v0[1]); w.y = cvtpk(v0[2], v0[3]); w.z = cvtpk(v1[0], v1[1]); w.w = cvtpk(v1[2], v1[3]);
;                     *(u32x4*)(xb + off + bj * HALF) = w;
;                     s += (v0[0] * v0[0] + v0[1] * v0[1]) + (v0[2] * v0[2] + v0[3] * v0[3]) + (v1[0] * v1[0] + v1[1] * v1[1]) + (v1[2] * v1[2] + v1[3] * v1[3]); }
;                 s += __shfl_xor(s, 16); s += __shfl_xor(s, 32);
;                 if (fq == 0) fx_add(ssout, row, s); }
.LBB0_1993:
	s_or_b64 exec, exec, s[26:27]
	v_add_u32_e32 v32, 0xa0, v146
	s_waitcnt lgkmcnt(0)
	v_ashrrev_i32_e32 v33, 31, v32
	v_lshlrev_b64 v[34:35], 11, v[32:33]
	v_lshl_add_u64 v[34:35], s[22:23], 0, v[34:35]
	v_lshl_add_u64 v[42:43], v[144:145], 1, v[34:35]
	global_load_dwordx4 v[34:37], v[42:43], off
	global_load_dwordx4 v[38:41], v[42:43], off offset:256
	s_waitcnt vmcnt(1)
	v_lshlrev_b32_e32 v44, 16, v34
	v_and_b32_e32 v45, 0xffff0000, v34
	v_lshlrev_b32_e32 v34, 16, v35
	v_and_b32_e32 v35, 0xffff0000, v35
	s_waitcnt vmcnt(0)
	v_lshlrev_b32_e32 v48, 16, v38
	v_and_b32_e32 v49, 0xffff0000, v38
	v_lshlrev_b32_e32 v38, 16, v39
	v_and_b32_e32 v39, 0xffff0000, v39
	v_lshlrev_b32_e32 v46, 16, v36
	v_and_b32_e32 v47, 0xffff0000, v36
	v_lshlrev_b32_e32 v36, 16, v37
	v_and_b32_e32 v37, 0xffff0000, v37
	v_lshlrev_b32_e32 v50, 16, v40
	v_and_b32_e32 v51, 0xffff0000, v40
	v_lshlrev_b32_e32 v40, 16, v41
	v_and_b32_e32 v41, 0xffff0000, v41
	v_pk_fma_f32 v[30:31], v[30:31], 0.5, v[34:35] op_sel_hi:[1,0,1]
	v_pk_fma_f32 v[28:29], v[28:29], 0.5, v[44:45] op_sel_hi:[1,0,1]
	v_pk_fma_f32 v[22:23], v[22:23], 0.5, v[38:39] op_sel_hi:[1,0,1]
	v_pk_fma_f32 v[20:21], v[20:21], 0.5, v[48:49] op_sel_hi:[1,0,1]
	v_pk_fma_f32 v[26:27], v[26:27], 0.5, v[36:37] op_sel_hi:[1,0,1]
	v_pk_fma_f32 v[24:25], v[24:25], 0.5, v[46:47] op_sel_hi:[1,0,1]
	v_pk_fma_f32 v[34:35], v[18:19], 0.5, v[40:41] op_sel_hi:[1,0,1]
	v_pk_fma_f32 v[36:37], v[16:17], 0.5, v[50:51] op_sel_hi:[1,0,1]
	v_mul_f32_e32 v18, v29, v29
	v_mul_f32_e32 v19, v31, v31
	v_mul_f32_e32 v38, v21, v21
	v_mul_f32_e32 v39, v23, v23
	v_cvt_pk_bf16_f32 v16, v28, v29
	v_mul_f32_e32 v29, v25, v25
	v_mul_f32_e32 v40, v37, v37
	v_fmac_f32_e32 v18, v28, v28
	v_fmac_f32_e32 v19, v30, v30
	v_fmac_f32_e32 v38, v20, v20
	v_fmac_f32_e32 v39, v22, v22
	v_cvt_pk_bf16_f32 v17, v30, v31
	v_mul_f32_e32 v31, v27, v27
	v_mul_f32_e32 v41, v35, v35
	v_fmac_f32_e32 v29, v24, v24
	v_fmac_f32_e32 v40, v36, v36
	v_add_f32_e32 v18, v18, v19
	v_add_f32_e32 v19, v38, v39
	v_fmac_f32_e32 v31, v26, v26
	v_fmac_f32_e32 v41, v34, v34
	v_add_f32_e32 v18, v29, v18
	v_add_f32_e32 v19, v40, v19
	v_add_f32_e32 v18, v31, v18
	v_add_f32_e32 v19, v41, v19
	v_add_f32_e32 v28, v18, v19
	v_mov_b32_e32 v29, v28
	s_nop 1
	v_permlane16_swap_b32_e32 v29, v28
	v_cvt_pk_bf16_f32 v18, v24, v25
	v_cvt_pk_bf16_f32 v19, v26, v27
	global_store_dwordx4 v[42:43], v[16:19], off
	s_waitcnt lgkmcnt(0)
	s_nop 0
	v_add_f32_e32 v16, v28, v29
	v_mov_b32_e32 v17, v16
	s_nop 1
	v_permlane32_swap_b32_e32 v17, v16
	v_cvt_pk_bf16_f32 v18, v20, v21
	v_cvt_pk_bf16_f32 v19, v22, v23
	v_cvt_pk_bf16_f32 v20, v36, v37
	v_cvt_pk_bf16_f32 v21, v34, v35
	global_store_dwordx4 v[42:43], v[18:21], off offset:256
	s_and_saveexec_b64 s[26:27], s[6:7]
	s_cbranch_execz .LBB0_1995
	s_waitcnt lgkmcnt(0)
	v_add_f32_e32 v16, v16, v17
	v_mul_f32_e32 v16, 0x4f800000, v16
	v_trunc_f32_e32 v16, v16
	v_mul_f32_e64 v17, |v16|, s47
	v_floor_f32_e32 v17, v17
	v_fma_f32 v18, v17, s48, |v16|
	v_cvt_u32_f32_e32 v16, v18
	v_cvt_u32_f32_e32 v17, v17
	v_lshl_add_u64 v[18:19], v[32:33], 3, s[10:11]
	global_atomic_add_x2 v[18:19], v[16:17], off
.LBB0_1995:
	s_or_b64 exec, exec, s[26:27]
	v_add_u32_e32 v16, 0xb0, v146
	s_waitcnt lgkmcnt(0)
	v_ashrrev_i32_e32 v17, 31, v16
	v_lshlrev_b64 v[18:19], 11, v[16:17]
	v_lshl_add_u64 v[18:19], s[22:23], 0, v[18:19]
	v_lshl_add_u64 v[26:27], v[144:145], 1, v[18:19]
	global_load_dwordx4 v[18:21], v[26:27], off
	global_load_dwordx4 v[22:25], v[26:27], off offset:256
	s_waitcnt vmcnt(1)
	v_lshlrev_b32_e32 v28, 16, v18
	v_and_b32_e32 v29, 0xffff0000, v18
	v_lshlrev_b32_e32 v18, 16, v19
	v_and_b32_e32 v19, 0xffff0000, v19
	s_waitcnt vmcnt(0)
	v_lshlrev_b32_e32 v32, 16, v22
	v_and_b32_e32 v33, 0xffff0000, v22
	v_lshlrev_b32_e32 v22, 16, v23
	v_and_b32_e32 v23, 0xffff0000, v23
	v_lshlrev_b32_e32 v30, 16, v20
	v_and_b32_e32 v31, 0xffff0000, v20
	v_lshlrev_b32_e32 v20, 16, v21
	v_and_b32_e32 v21, 0xffff0000, v21
	v_lshlrev_b32_e32 v34, 16, v24
	v_and_b32_e32 v35, 0xffff0000, v24
	v_lshlrev_b32_e32 v24, 16, v25
	v_and_b32_e32 v25, 0xffff0000, v25
	v_pk_fma_f32 v[14:15], v[14:15], 0.5, v[18:19] op_sel_hi:[1,0,1]
	v_pk_fma_f32 v[12:13], v[12:13], 0.5, v[28:29] op_sel_hi:[1,0,1]
	v_pk_fma_f32 v[6:7], v[6:7], 0.5, v[22:23] op_sel_hi:[1,0,1]
	v_pk_fma_f32 v[4:5], v[4:5], 0.5, v[32:33] op_sel_hi:[1,0,1]
	v_pk_fma_f32 v[10:11], v[10:11], 0.5, v[20:21] op_sel_hi:[1,0,1]
	v_pk_fma_f32 v[8:9], v[8:9], 0.5, v[30:31] op_sel_hi:[1,0,1]
	v_pk_fma_f32 v[18:19], v[2:3], 0.5, v[24:25] op_sel_hi:[1,0,1]
	v_pk_fma_f32 v[20:21], v[0:1], 0.5, v[34:35] op_sel_hi:[1,0,1]
	v_mul_f32_e32 v2, v13, v13
	v_mul_f32_e32 v3, v15, v15
	v_mul_f32_e32 v22, v5, v5
	v_mul_f32_e32 v23, v7, v7
	v_cvt_pk_bf16_f32 v0, v12, v13
	v_mul_f32_e32 v13, v9, v9
	v_mul_f32_e32 v24, v21, v21
	v_fmac_f32_e32 v2, v12, v12
	v_fmac_f32_e32 v3, v14, v14
	v_fmac_f32_e32 v22, v4, v4
	v_fmac_f32_e32 v23, v6, v6
	v_cvt_pk_bf16_f32 v1, v14, v15
	v_mul_f32_e32 v15, v11, v11
	v_mul_f32_e32 v25, v19, v19
	v_fmac_f32_e32 v13, v8, v8
	v_fmac_f32_e32 v24, v20, v20
	v_add_f32_e32 v2, v2, v3
	v_add_f32_e32 v3, v22, v23
	v_fmac_f32_e32 v15, v10, v10
	v_fmac_f32_e32 v25, v18, v18
	v_add_f32_e32 v2, v13, v2
	v_add_f32_e32 v3, v24, v3
	v_add_f32_e32 v2, v15, v2
	v_add_f32_e32 v3, v25, v3
	v_add_f32_e32 v12, v2, v3
	v_mov_b32_e32 v13, v12
	s_nop 1
	v_permlane16_swap_b32_e32 v13, v12
	v_cvt_pk_bf16_f32 v2, v8, v9
	v_cvt_pk_bf16_f32 v3, v10, v11
	global_store_dwordx4 v[26:27], v[0:3], off
	s_waitcnt lgkmcnt(0)
	s_nop 0
	v_add_f32_e32 v0, v12, v13
	v_mov_b32_e32 v1, v0
	s_nop 1
	v_permlane32_swap_b32_e32 v1, v0
	v_cvt_pk_bf16_f32 v2, v4, v5
	v_cvt_pk_bf16_f32 v3, v6, v7
	v_cvt_pk_bf16_f32 v4, v20, v21
	v_cvt_pk_bf16_f32 v5, v18, v19
	global_store_dwordx4 v[26:27], v[2:5], off offset:256
	s_and_saveexec_b64 s[26:27], s[6:7]
	s_cbranch_execz .LBB0_1997
	s_waitcnt lgkmcnt(0)
	v_add_f32_e32 v0, v0, v1
	v_mul_f32_e32 v0, 0x4f800000, v0
	v_trunc_f32_e32 v0, v0
	v_mul_f32_e64 v1, |v0|, s47
	v_floor_f32_e32 v1, v1
	v_fma_f32 v2, v1, s48, |v0|
	v_cvt_u32_f32_e32 v0, v2
	v_cvt_u32_f32_e32 v1, v1
	v_lshl_add_u64 v[2:3], v[16:17], 3, s[10:11]
	global_atomic_add_x2 v[2:3], v[0:1], off
